# DeltaNet chunk forward-substitution rewritten by hand: M rows prefetched 2 steps ahead, DPP quad reduction, software-pipelined partial sums
# speedup vs baseline: 1.2018x; 1.0590x over previous
; template <int DIR>
; DI void dn_solve4(const float* M, const h16* Ki, const h16* Vi, const float* betal, const float* gcl, int half, int c, int pp, float (&x)[16]) {
;   const h16* src = half ? (Ki + c) : (Vi + c);
; #pragma unroll
;   for (int k = 0; k < 16; ++k) x[k] = 0.f;
; #pragma unroll
;   for (int il = 0; il < 64; ++il) {
;     const int ri = DIR ? 63 - il : il;
;     float part = 0.f;
; #pragma unroll
;     for (int k = 0; k < (il + 3) / 4; ++k) {
;       const int jl0 = 4 * k;
;       float mv = DIR ? M[ri * MLD + 63 - jl0 - pp] : M[ri * MLD + jl0 + pp];
;       if (jl0 + 3 >= il) mv = (jl0 + pp < il) ? mv : 0.f;
;       part += mv * x[k];
;     }
;     part += __shfl_xor(part, 1); part += __shfl_xor(part, 2);
;     const float e = half ? __expf(gcl[ri]) : 1.f;
;     const float xi = betal[ri] * (float)src[ri * LDH] * e - part;
;     if ((il & 3) == pp) x[il >> 2] = xi;
; DI void dn_c1_unit(const Params& p, int l, int head, int oc, h16* lds) {
;     ...
;     const int c = tid >> 2, pp = tid & 3;
; #pragma unroll 1
;     for (int dh2 = 0; dh2 < 4; ++dh2) {
;       const int dir = dh2 >> 1, half = dh2 & 1;
;       const int nloc = dir ? 255 - oc : oc;
;       const size_t unit = (size_t)(dir * 4 + head) * 256 + nloc;
;       float x[16];
;       if (dir == 0) dn_solve4<0>(M, Ki, Vi, betal, gcl, half, c, pp, x);
;       else dn_solve4<1>(M, Ki, Vi, betal + 64, gcl + 64, half, c, pp, x);
.LBB0_312:
	s_and_b32 s2, s9, 1
	s_cmp_lt_u32 s9, 2
	s_cselect_b64 s[76:77], -1, 0
	s_cmp_eq_u32 s2, 0
	s_cselect_b64 vcc, -1, 0
	s_cmp_eq_u32 s2, 1
	v_cndmask_b32_e32 v1, v183, v184, vcc
	s_cselect_b64 s[2:3], -1, 0
	v_lshl_add_u32 v114, v129, 1, v1
	v_cndmask_b32_e64 v1, 0, 1, s[2:3]
	s_cmp_gt_u32 s9, 1
	s_mov_b64 s[4:5], -1
	v_cmp_ne_u32_e64 s[78:79], 1, v1
	s_cbranch_scc0 .Lsolve_dir0
	v_and_b32_e32 v116, 3, v182
	v_cmp_eq_u32_e64 s[88:89], 0, v116
	v_cmp_eq_u32_e64 s[90:91], 1, v116
	v_cmp_eq_u32_e64 s[92:93], 2, v116
	v_cmp_eq_u32_e64 s[98:99], 3, v116
	v_cmp_gt_u32_e64 s[100:101], 1, v116
	v_cmp_gt_u32_e64 s[18:19], 2, v116
	v_cmp_gt_u32_e64 s[22:23], 3, v116
	v_lshlrev_b32_e32 v125, 2, v116
	v_sub_u32_e32 v117, v183, v125
	v_sub_u32_e32 v126, 3, v116
	v_mul_u32_u24_e32 v126, 0x90, v126
	v_add_u32_e32 v118, v114, v126
	v_mov_b32_e32 v2, 0
	v_mov_b32_e32 v3, 0
	v_mov_b32_e32 v4, 0
	v_mov_b32_e32 v5, 0
	v_mov_b32_e32 v6, 0
	v_mov_b32_e32 v7, 0
	v_mov_b32_e32 v8, 0
	v_mov_b32_e32 v9, 0
	v_mov_b32_e32 v10, 0
	v_mov_b32_e32 v11, 0
	v_mov_b32_e32 v12, 0
	v_mov_b32_e32 v13, 0
	v_mov_b32_e32 v14, 0
	v_mov_b32_e32 v15, 0
	v_mov_b32_e32 v16, 0
	v_mov_b32_e32 v17, 0
	ds_read_b32 v18, v117 offset:36348
	ds_read_u16 v35, v118 offset:8640
	ds_read_b32 v19, v117 offset:36332
	ds_read_u16 v36, v118 offset:8064
	ds_read_b32 v20, v117 offset:36316
	ds_read_u16 v37, v118 offset:7488
	ds_read_b32 v21, v117 offset:36300
	ds_read_u16 v38, v118 offset:6912
	s_waitcnt lgkmcnt(6)
	v_cvt_f32_f16_e32 v35, v35
	s_waitcnt lgkmcnt(4)
	v_cvt_f32_f16_e32 v36, v36
	s_waitcnt lgkmcnt(2)
	v_cvt_f32_f16_e32 v37, v37
	s_waitcnt lgkmcnt(0)
	v_cvt_f32_f16_e32 v38, v38
	v_mul_f32_e32 v18, v18, v35
	v_mul_f32_e32 v19, v19, v36
	v_mul_f32_e32 v20, v20, v37
	v_mul_f32_e32 v21, v21, v38
	ds_read_b32 v22, v117 offset:36284
	ds_read_u16 v39, v118 offset:6336
	ds_read_b32 v23, v117 offset:36268
	ds_read_u16 v40, v118 offset:5760
	ds_read_b32 v24, v117 offset:36252
	ds_read_u16 v41, v118 offset:5184
	ds_read_b32 v25, v117 offset:36236
	ds_read_u16 v42, v118 offset:4608
	s_waitcnt lgkmcnt(6)
	v_cvt_f32_f16_e32 v39, v39
	s_waitcnt lgkmcnt(4)
	v_cvt_f32_f16_e32 v40, v40
	s_waitcnt lgkmcnt(2)
	v_cvt_f32_f16_e32 v41, v41
	s_waitcnt lgkmcnt(0)
	v_cvt_f32_f16_e32 v42, v42
	v_mul_f32_e32 v22, v22, v39
	v_mul_f32_e32 v23, v23, v40
	v_mul_f32_e32 v24, v24, v41
	v_mul_f32_e32 v25, v25, v42
	ds_read_b32 v26, v117 offset:36220
	ds_read_u16 v43, v118 offset:4032
	ds_read_b32 v27, v117 offset:36204
	ds_read_u16 v44, v118 offset:3456
	ds_read_b32 v28, v117 offset:36188
	ds_read_u16 v45, v118 offset:2880
	ds_read_b32 v30, v117 offset:36172
	ds_read_u16 v46, v118 offset:2304
	s_waitcnt lgkmcnt(6)
	v_cvt_f32_f16_e32 v43, v43
	s_waitcnt lgkmcnt(4)
	v_cvt_f32_f16_e32 v44, v44
	s_waitcnt lgkmcnt(2)
	v_cvt_f32_f16_e32 v45, v45
	s_waitcnt lgkmcnt(0)
	v_cvt_f32_f16_e32 v46, v46
	v_mul_f32_e32 v26, v26, v43
	v_mul_f32_e32 v27, v27, v44
	v_mul_f32_e32 v28, v28, v45
	v_mul_f32_e32 v30, v30, v46
	ds_read_b32 v31, v117 offset:36156
	ds_read_u16 v47, v118 offset:1728
	ds_read_b32 v32, v117 offset:36140
	ds_read_u16 v48, v118 offset:1152
	ds_read_b32 v33, v117 offset:36124
	ds_read_u16 v49, v118 offset:576
	ds_read_b32 v34, v117 offset:36108
	ds_read_u16 v115, v118 offset:0
	s_waitcnt lgkmcnt(6)
	v_cvt_f32_f16_e32 v47, v47
	s_waitcnt lgkmcnt(4)
	v_cvt_f32_f16_e32 v48, v48
	s_waitcnt lgkmcnt(2)
	v_cvt_f32_f16_e32 v49, v49
	s_waitcnt lgkmcnt(0)
	v_cvt_f32_f16_e32 v115, v115
	v_mul_f32_e32 v31, v31, v47
	v_mul_f32_e32 v32, v32, v48
	v_mul_f32_e32 v33, v33, v49
	v_mul_f32_e32 v34, v34, v115
	s_and_b64 vcc, exec, s[78:79]
	s_cbranch_vccnz .Lsolved1_noexp
	ds_read_b32 v35, v117 offset:36860
	ds_read_b32 v36, v117 offset:36844
	ds_read_b32 v37, v117 offset:36828
	ds_read_b32 v38, v117 offset:36812
	ds_read_b32 v39, v117 offset:36796
	ds_read_b32 v40, v117 offset:36780
	ds_read_b32 v41, v117 offset:36764
	ds_read_b32 v42, v117 offset:36748
	s_waitcnt lgkmcnt(7)
	v_mul_f32_e32 v35, 0x3fb8aa3b, v35
	s_waitcnt lgkmcnt(6)
	v_mul_f32_e32 v36, 0x3fb8aa3b, v36
	s_waitcnt lgkmcnt(5)
	v_mul_f32_e32 v37, 0x3fb8aa3b, v37
	s_waitcnt lgkmcnt(4)
	v_mul_f32_e32 v38, 0x3fb8aa3b, v38
	s_waitcnt lgkmcnt(3)
	v_mul_f32_e32 v39, 0x3fb8aa3b, v39
	s_waitcnt lgkmcnt(2)
	v_mul_f32_e32 v40, 0x3fb8aa3b, v40
	s_waitcnt lgkmcnt(1)
	v_mul_f32_e32 v41, 0x3fb8aa3b, v41
	s_waitcnt lgkmcnt(0)
	v_mul_f32_e32 v42, 0x3fb8aa3b, v42
	v_exp_f32_e32 v35, v35
	v_exp_f32_e32 v36, v36
	v_exp_f32_e32 v37, v37
	v_exp_f32_e32 v38, v38
	v_exp_f32_e32 v39, v39
	v_exp_f32_e32 v40, v40
	v_exp_f32_e32 v41, v41
	v_exp_f32_e32 v42, v42
	ds_read_b32 v43, v117 offset:36732
	ds_read_b32 v44, v117 offset:36716
	ds_read_b32 v45, v117 offset:36700
	ds_read_b32 v46, v117 offset:36684
	ds_read_b32 v47, v117 offset:36668
	ds_read_b32 v48, v117 offset:36652
	ds_read_b32 v49, v117 offset:36636
	ds_read_b32 v115, v117 offset:36620
	s_waitcnt lgkmcnt(7)
	v_mul_f32_e32 v43, 0x3fb8aa3b, v43
	s_waitcnt lgkmcnt(6)
	v_mul_f32_e32 v44, 0x3fb8aa3b, v44
	s_waitcnt lgkmcnt(5)
	v_mul_f32_e32 v45, 0x3fb8aa3b, v45
	s_waitcnt lgkmcnt(4)
	v_mul_f32_e32 v46, 0x3fb8aa3b, v46
	s_waitcnt lgkmcnt(3)
	v_mul_f32_e32 v47, 0x3fb8aa3b, v47
	s_waitcnt lgkmcnt(2)
	v_mul_f32_e32 v48, 0x3fb8aa3b, v48
	s_waitcnt lgkmcnt(1)
	v_mul_f32_e32 v49, 0x3fb8aa3b, v49
	s_waitcnt lgkmcnt(0)
	v_mul_f32_e32 v115, 0x3fb8aa3b, v115
	v_exp_f32_e32 v43, v43
	v_exp_f32_e32 v44, v44
	v_exp_f32_e32 v45, v45
	v_exp_f32_e32 v46, v46
	v_exp_f32_e32 v47, v47
	v_exp_f32_e32 v48, v48
	v_exp_f32_e32 v49, v49
	v_exp_f32_e32 v115, v115
	s_branch .Lsolved1_go
; template <int DIR>
; DI void dn_solve4(const float* M, const h16* Ki, const h16* Vi, const float* betal, const float* gcl, int half, int c, int pp, float (&x)[16]) {
;   const h16* src = half ? (Ki + c) : (Vi + c);
; #pragma unroll
;   for (int k = 0; k < 16; ++k) x[k] = 0.f;
; #pragma unroll
;   for (int il = 0; il < 64; ++il) {
;     const int ri = DIR ? 63 - il : il;
;     float part = 0.f;
; #pragma unroll
;     for (int k = 0; k < (il + 3) / 4; ++k) {
;       const int jl0 = 4 * k;
;       float mv = DIR ? M[ri * MLD + 63 - jl0 - pp] : M[ri * MLD + jl0 + pp];
;       if (jl0 + 3 >= il) mv = (jl0 + pp < il) ? mv : 0.f;
;       part += mv * x[k];
;     }
;     part += __shfl_xor(part, 1); part += __shfl_xor(part, 2);
;     const float e = half ? __expf(gcl[ri]) : 1.f;
;     const float xi = betal[ri] * (float)src[ri * LDH] * e - part;
;     if ((il & 3) == pp) x[il >> 2] = xi;
;   }
.Lsolved1_noexp:
	v_mov_b32_e32 v35, 1.0
	v_mov_b32_e32 v36, 1.0
	v_mov_b32_e32 v37, 1.0
	v_mov_b32_e32 v38, 1.0
	v_mov_b32_e32 v39, 1.0
	v_mov_b32_e32 v40, 1.0
	v_mov_b32_e32 v41, 1.0
	v_mov_b32_e32 v42, 1.0
	v_mov_b32_e32 v43, 1.0
	v_mov_b32_e32 v44, 1.0
	v_mov_b32_e32 v45, 1.0
	v_mov_b32_e32 v46, 1.0
	v_mov_b32_e32 v47, 1.0
	v_mov_b32_e32 v48, 1.0
	v_mov_b32_e32 v49, 1.0
	v_mov_b32_e32 v115, 1.0
.Lsolved1_go:
	s_nop 0
	s_waitcnt lgkmcnt(0)
	v_add_u32_e32 v120, 0x8adc, v117
	ds_read_b32 v148, v120
	v_add_u32_e32 v121, 0x89cc, v117
	ds_read_b32 v216, v121
	v_mul_f32_e32 v125, v35, v18
	v_cndmask_b32_e64 v2, v2, v125, s[88:89]
	v_add_u32_e32 v119, 0x88bc, v117
	ds_read_b32 v132, v119
	s_waitcnt lgkmcnt(2)
	v_cndmask_b32_e64 v126, 0, v148, s[100:101]
	v_mul_f32_e32 v125, v126, v2
	s_nop 1
	v_add_f32_dpp v127, v125, v125 quad_perm:[1,0,3,2] row_mask:0xf bank_mask:0xf
	s_nop 1
	v_add_f32_dpp v125, v127, v127 quad_perm:[2,3,0,1] row_mask:0xf bank_mask:0xf
	v_fma_f32 v127, v35, v18, -v125
	v_cndmask_b32_e64 v2, v2, v127, s[90:91]
	v_add_u32_e32 v120, 0x87ac, v117
	ds_read_b32 v148, v120
	s_waitcnt lgkmcnt(2)
	v_cndmask_b32_e64 v126, 0, v216, s[18:19]
	v_mul_f32_e32 v125, v126, v2
	s_nop 1
	v_add_f32_dpp v127, v125, v125 quad_perm:[1,0,3,2] row_mask:0xf bank_mask:0xf
	s_nop 1
	v_add_f32_dpp v125, v127, v127 quad_perm:[2,3,0,1] row_mask:0xf bank_mask:0xf
	v_fma_f32 v127, v35, v18, -v125
	v_cndmask_b32_e64 v2, v2, v127, s[92:93]
	v_add_u32_e32 v121, 0x868c, v117
	ds_read2_b32 v[216:217], v121 offset0:4 offset1:0
	s_waitcnt lgkmcnt(2)
	v_cndmask_b32_e64 v126, 0, v132, s[22:23]
	v_mul_f32_e32 v125, v126, v2
	s_nop 1
	v_add_f32_dpp v127, v125, v125 quad_perm:[1,0,3,2] row_mask:0xf bank_mask:0xf
	s_nop 1
	v_add_f32_dpp v125, v127, v127 quad_perm:[2,3,0,1] row_mask:0xf bank_mask:0xf
	v_fma_f32 v127, v35, v18, -v125
	v_cndmask_b32_e64 v2, v2, v127, s[98:99]
	v_add_u32_e32 v119, 0x857c, v117
	ds_read2_b32 v[132:133], v119 offset0:4 offset1:0
	s_waitcnt lgkmcnt(2)
	v_mul_f32_e32 v125, v148, v2
	s_waitcnt lgkmcnt(1)
	v_mul_f32_e32 v124, v216, v2
	s_nop 0
	v_add_f32_dpp v127, v125, v125 quad_perm:[1,0,3,2] row_mask:0xf bank_mask:0xf
	s_nop 1
	v_add_f32_dpp v125, v127, v127 quad_perm:[2,3,0,1] row_mask:0xf bank_mask:0xf
	v_fma_f32 v127, v36, v19, -v125
	v_cndmask_b32_e64 v3, v3, v127, s[88:89]
	v_add_u32_e32 v120, 0x846c, v117
	ds_read2_b32 v[148:149], v120 offset0:4 offset1:0
	v_cndmask_b32_e64 v126, 0, v217, s[100:101]
	v_fma_f32 v125, v126, v3, v124
	s_waitcnt lgkmcnt(1)
	v_mul_f32_e32 v122, v132, v2
	s_nop 0
	v_add_f32_dpp v127, v125, v125 quad_perm:[1,0,3,2] row_mask:0xf bank_mask:0xf
	s_nop 1
	v_add_f32_dpp v125, v127, v127 quad_perm:[2,3,0,1] row_mask:0xf bank_mask:0xf
	v_fma_f32 v127, v36, v19, -v125
	v_cndmask_b32_e64 v3, v3, v127, s[90:91]
	v_add_u32_e32 v121, 0x835c, v117
	ds_read2_b32 v[216:217], v121 offset0:4 offset1:0
	v_cndmask_b32_e64 v126, 0, v133, s[18:19]
	v_fma_f32 v125, v126, v3, v122
	s_waitcnt lgkmcnt(1)
	v_mul_f32_e32 v123, v148, v2
	s_nop 0
	v_add_f32_dpp v127, v125, v125 quad_perm:[1,0,3,2] row_mask:0xf bank_mask:0xf
	s_nop 1
	v_add_f32_dpp v125, v127, v127 quad_perm:[2,3,0,1] row_mask:0xf bank_mask:0xf
	v_fma_f32 v127, v36, v19, -v125
	v_cndmask_b32_e64 v3, v3, v127, s[92:93]
	v_add_u32_e32 v119, 0x823c, v117
	ds_read2_b32 v[132:133], v119 offset0:8 offset1:4
	ds_read_b32 v134, v119
	v_cndmask_b32_e64 v126, 0, v149, s[22:23]
	v_fma_f32 v125, v126, v3, v123
	s_waitcnt lgkmcnt(2)
	v_mul_f32_e32 v124, v216, v2
	s_nop 0
	v_add_f32_dpp v127, v125, v125 quad_perm:[1,0,3,2] row_mask:0xf bank_mask:0xf
	s_nop 1
	v_add_f32_dpp v125, v127, v127 quad_perm:[2,3,0,1] row_mask:0xf bank_mask:0xf
	v_fma_f32 v127, v36, v19, -v125
	v_cndmask_b32_e64 v3, v3, v127, s[98:99]
	v_add_u32_e32 v120, 0x812c, v117
	ds_read2_b32 v[148:149], v120 offset0:8 offset1:4
	ds_read_b32 v150, v120
	v_fma_f32 v125, v217, v3, v124
	s_waitcnt lgkmcnt(3)
	v_mul_f32_e32 v122, v132, v2
	v_fmac_f32_e32 v122, v133, v3
	v_add_f32_dpp v127, v125, v125 quad_perm:[1,0,3,2] row_mask:0xf bank_mask:0xf
	s_nop 1
	v_add_f32_dpp v125, v127, v127 quad_perm:[2,3,0,1] row_mask:0xf bank_mask:0xf
	v_fma_f32 v127, v37, v20, -v125
	v_cndmask_b32_e64 v4, v4, v127, s[88:89]
	v_add_u32_e32 v121, 0x801c, v117
	ds_read2_b32 v[216:217], v121 offset0:8 offset1:4
	ds_read_b32 v218, v121
	s_waitcnt lgkmcnt(4)
	v_cndmask_b32_e64 v126, 0, v134, s[100:101]
	v_fma_f32 v125, v126, v4, v122
	s_waitcnt lgkmcnt(3)
	v_mul_f32_e32 v123, v148, v2
	v_fmac_f32_e32 v123, v149, v3
	v_add_f32_dpp v127, v125, v125 quad_perm:[1,0,3,2] row_mask:0xf bank_mask:0xf
	s_nop 1
	v_add_f32_dpp v125, v127, v127 quad_perm:[2,3,0,1] row_mask:0xf bank_mask:0xf
	v_fma_f32 v127, v37, v20, -v125
	v_cndmask_b32_e64 v4, v4, v127, s[90:91]
	v_add_u32_e32 v119, 0x7f0c, v117
	ds_read2_b32 v[132:133], v119 offset0:8 offset1:4
	ds_read_b32 v134, v119
	s_waitcnt lgkmcnt(4)
	v_cndmask_b32_e64 v126, 0, v150, s[18:19]
	v_fma_f32 v125, v126, v4, v123
	s_waitcnt lgkmcnt(3)
	v_mul_f32_e32 v124, v216, v2
	v_fmac_f32_e32 v124, v217, v3
	v_add_f32_dpp v127, v125, v125 quad_perm:[1,0,3,2] row_mask:0xf bank_mask:0xf
	s_nop 1
	v_add_f32_dpp v125, v127, v127 quad_perm:[2,3,0,1] row_mask:0xf bank_mask:0xf
	v_fma_f32 v127, v37, v20, -v125
	v_cndmask_b32_e64 v4, v4, v127, s[92:93]
	v_add_u32_e32 v120, 0x7dec, v117
	ds_read2_b32 v[148:149], v120 offset0:12 offset1:8
	ds_read2_b32 v[150:151], v120 offset0:4 offset1:0
	s_waitcnt lgkmcnt(4)
	v_cndmask_b32_e64 v126, 0, v218, s[22:23]
	v_fma_f32 v125, v126, v4, v124
	s_waitcnt lgkmcnt(3)
; template <int DIR>
; DI void dn_solve4(const float* M, const h16* Ki, const h16* Vi, const float* betal, const float* gcl, int half, int c, int pp, float (&x)[16]) {
;   const h16* src = half ? (Ki + c) : (Vi + c);
; #pragma unroll
;   for (int k = 0; k < 16; ++k) x[k] = 0.f;
; #pragma unroll
;   for (int il = 0; il < 64; ++il) {
;     const int ri = DIR ? 63 - il : il;
;     float part = 0.f;
; #pragma unroll
;     for (int k = 0; k < (il + 3) / 4; ++k) {
;       const int jl0 = 4 * k;
;       float mv = DIR ? M[ri * MLD + 63 - jl0 - pp] : M[ri * MLD + jl0 + pp];
;       if (jl0 + 3 >= il) mv = (jl0 + pp < il) ? mv : 0.f;
;       part += mv * x[k];
;     }
;     part += __shfl_xor(part, 1); part += __shfl_xor(part, 2);
;     const float e = half ? __expf(gcl[ri]) : 1.f;
;     const float xi = betal[ri] * (float)src[ri * LDH] * e - part;
;     if ((il & 3) == pp) x[il >> 2] = xi;
;   }
	v_mul_f32_e32 v122, v132, v2
	v_fmac_f32_e32 v122, v133, v3
	v_add_f32_dpp v127, v125, v125 quad_perm:[1,0,3,2] row_mask:0xf bank_mask:0xf
	s_nop 1
	v_add_f32_dpp v125, v127, v127 quad_perm:[2,3,0,1] row_mask:0xf bank_mask:0xf
	v_fma_f32 v127, v37, v20, -v125
	v_cndmask_b32_e64 v4, v4, v127, s[98:99]
	v_add_u32_e32 v121, 0x7cdc, v117
	ds_read2_b32 v[216:217], v121 offset0:12 offset1:8
	ds_read2_b32 v[218:219], v121 offset0:4 offset1:0
	s_waitcnt lgkmcnt(4)
	v_fma_f32 v125, v134, v4, v122
	s_waitcnt lgkmcnt(3)
	v_mul_f32_e32 v123, v148, v2
	v_fmac_f32_e32 v123, v149, v3
	v_add_f32_dpp v127, v125, v125 quad_perm:[1,0,3,2] row_mask:0xf bank_mask:0xf
	s_waitcnt lgkmcnt(2)
	v_fmac_f32_e32 v123, v150, v4
	s_nop 0
	v_add_f32_dpp v125, v127, v127 quad_perm:[2,3,0,1] row_mask:0xf bank_mask:0xf
	v_fma_f32 v127, v38, v21, -v125
	v_cndmask_b32_e64 v5, v5, v127, s[88:89]
	v_add_u32_e32 v119, 0x7bcc, v117
	ds_read2_b32 v[132:133], v119 offset0:12 offset1:8
	ds_read2_b32 v[134:135], v119 offset0:4 offset1:0
	v_cndmask_b32_e64 v126, 0, v151, s[100:101]
	v_fma_f32 v125, v126, v5, v123
	s_waitcnt lgkmcnt(3)
	v_mul_f32_e32 v124, v216, v2
	v_fmac_f32_e32 v124, v217, v3
	v_add_f32_dpp v127, v125, v125 quad_perm:[1,0,3,2] row_mask:0xf bank_mask:0xf
	s_waitcnt lgkmcnt(2)
	v_fmac_f32_e32 v124, v218, v4
	s_nop 0
	v_add_f32_dpp v125, v127, v127 quad_perm:[2,3,0,1] row_mask:0xf bank_mask:0xf
	v_fma_f32 v127, v38, v21, -v125
	v_cndmask_b32_e64 v5, v5, v127, s[90:91]
	v_add_u32_e32 v120, 0x7abc, v117
	ds_read2_b32 v[148:149], v120 offset0:12 offset1:8
	ds_read2_b32 v[150:151], v120 offset0:4 offset1:0
	v_cndmask_b32_e64 v126, 0, v219, s[18:19]
	v_fma_f32 v125, v126, v5, v124
	s_waitcnt lgkmcnt(3)
	v_mul_f32_e32 v122, v132, v2
	v_fmac_f32_e32 v122, v133, v3
	v_add_f32_dpp v127, v125, v125 quad_perm:[1,0,3,2] row_mask:0xf bank_mask:0xf
	s_waitcnt lgkmcnt(2)
	v_fmac_f32_e32 v122, v134, v4
	s_nop 0
	v_add_f32_dpp v125, v127, v127 quad_perm:[2,3,0,1] row_mask:0xf bank_mask:0xf
	v_fma_f32 v127, v38, v21, -v125
	v_cndmask_b32_e64 v5, v5, v127, s[92:93]
	v_add_u32_e32 v121, 0x799c, v117
	ds_read2_b32 v[216:217], v121 offset0:16 offset1:12
	ds_read2_b32 v[218:219], v121 offset0:8 offset1:4
	ds_read_b32 v220, v121
	v_cndmask_b32_e64 v126, 0, v135, s[22:23]
	v_fma_f32 v125, v126, v5, v122
	s_waitcnt lgkmcnt(4)
	v_mul_f32_e32 v123, v148, v2
	v_fmac_f32_e32 v123, v149, v3
	v_add_f32_dpp v127, v125, v125 quad_perm:[1,0,3,2] row_mask:0xf bank_mask:0xf
	s_waitcnt lgkmcnt(3)
	v_fmac_f32_e32 v123, v150, v4
	s_nop 0
	v_add_f32_dpp v125, v127, v127 quad_perm:[2,3,0,1] row_mask:0xf bank_mask:0xf
	v_fma_f32 v127, v38, v21, -v125
	v_cndmask_b32_e64 v5, v5, v127, s[98:99]
	v_add_u32_e32 v119, 0x788c, v117
	ds_read2_b32 v[132:133], v119 offset0:16 offset1:12
	ds_read2_b32 v[134:135], v119 offset0:8 offset1:4
	ds_read_b32 v136, v119
	v_fma_f32 v125, v151, v5, v123
	s_waitcnt lgkmcnt(5)
	v_mul_f32_e32 v124, v216, v2
	v_fmac_f32_e32 v124, v217, v3
	v_add_f32_dpp v127, v125, v125 quad_perm:[1,0,3,2] row_mask:0xf bank_mask:0xf
	s_waitcnt lgkmcnt(4)
	v_fmac_f32_e32 v124, v218, v4
	v_fmac_f32_e32 v124, v219, v5
	v_add_f32_dpp v125, v127, v127 quad_perm:[2,3,0,1] row_mask:0xf bank_mask:0xf
	v_fma_f32 v127, v39, v22, -v125
	v_cndmask_b32_e64 v6, v6, v127, s[88:89]
	v_add_u32_e32 v120, 0x777c, v117
	ds_read2_b32 v[148:149], v120 offset0:16 offset1:12
	ds_read2_b32 v[150:151], v120 offset0:8 offset1:4
	ds_read_b32 v152, v120
	s_waitcnt lgkmcnt(6)
	v_cndmask_b32_e64 v126, 0, v220, s[100:101]
	v_fma_f32 v125, v126, v6, v124
	s_waitcnt lgkmcnt(5)
	v_mul_f32_e32 v122, v132, v2
	v_fmac_f32_e32 v122, v133, v3
	v_add_f32_dpp v127, v125, v125 quad_perm:[1,0,3,2] row_mask:0xf bank_mask:0xf
	s_waitcnt lgkmcnt(4)
	v_fmac_f32_e32 v122, v134, v4
	v_fmac_f32_e32 v122, v135, v5
	v_add_f32_dpp v125, v127, v127 quad_perm:[2,3,0,1] row_mask:0xf bank_mask:0xf
	v_fma_f32 v127, v39, v22, -v125
	v_cndmask_b32_e64 v6, v6, v127, s[90:91]
	v_add_u32_e32 v121, 0x766c, v117
	ds_read2_b32 v[216:217], v121 offset0:16 offset1:12
	ds_read2_b32 v[218:219], v121 offset0:8 offset1:4
	ds_read_b32 v220, v121
	s_waitcnt lgkmcnt(6)
	v_cndmask_b32_e64 v126, 0, v136, s[18:19]
	v_fma_f32 v125, v126, v6, v122
	s_waitcnt lgkmcnt(5)
	v_mul_f32_e32 v123, v148, v2
	v_fmac_f32_e32 v123, v149, v3
	v_add_f32_dpp v127, v125, v125 quad_perm:[1,0,3,2] row_mask:0xf bank_mask:0xf
	s_waitcnt lgkmcnt(4)
	v_fmac_f32_e32 v123, v150, v4
	v_fmac_f32_e32 v123, v151, v5
	v_add_f32_dpp v125, v127, v127 quad_perm:[2,3,0,1] row_mask:0xf bank_mask:0xf
	v_fma_f32 v127, v39, v22, -v125
	v_cndmask_b32_e64 v6, v6, v127, s[92:93]
	v_add_u32_e32 v119, 0x754c, v117
	ds_read2_b32 v[132:133], v119 offset0:20 offset1:16
	ds_read2_b32 v[134:135], v119 offset0:12 offset1:8
	ds_read2_b32 v[136:137], v119 offset0:4 offset1:0
	s_waitcnt lgkmcnt(6)
	v_cndmask_b32_e64 v126, 0, v152, s[22:23]
	v_fma_f32 v125, v126, v6, v123
	s_waitcnt lgkmcnt(5)
	v_mul_f32_e32 v124, v216, v2
	v_fmac_f32_e32 v124, v217, v3
	v_add_f32_dpp v127, v125, v125 quad_perm:[1,0,3,2] row_mask:0xf bank_mask:0xf
	s_waitcnt lgkmcnt(4)
	v_fmac_f32_e32 v124, v218, v4
	v_fmac_f32_e32 v124, v219, v5
	v_add_f32_dpp v125, v127, v127 quad_perm:[2,3,0,1] row_mask:0xf bank_mask:0xf
	v_fma_f32 v127, v39, v22, -v125
	v_cndmask_b32_e64 v6, v6, v127, s[98:99]
	v_add_u32_e32 v120, 0x743c, v117
	ds_read2_b32 v[148:149], v120 offset0:20 offset1:16
	ds_read2_b32 v[150:151], v120 offset0:12 offset1:8
	ds_read2_b32 v[152:153], v120 offset0:4 offset1:0
	s_waitcnt lgkmcnt(6)
	v_fma_f32 v125, v220, v6, v124
	s_waitcnt lgkmcnt(5)
	v_mul_f32_e32 v122, v132, v2
	v_fmac_f32_e32 v122, v133, v3
	v_add_f32_dpp v127, v125, v125 quad_perm:[1,0,3,2] row_mask:0xf bank_mask:0xf
	s_waitcnt lgkmcnt(4)
; template <int DIR>
; DI void dn_solve4(const float* M, const h16* Ki, const h16* Vi, const float* betal, const float* gcl, int half, int c, int pp, float (&x)[16]) {
;   const h16* src = half ? (Ki + c) : (Vi + c);
; #pragma unroll
;   for (int k = 0; k < 16; ++k) x[k] = 0.f;
; #pragma unroll
;   for (int il = 0; il < 64; ++il) {
;     const int ri = DIR ? 63 - il : il;
;     float part = 0.f;
; #pragma unroll
;     for (int k = 0; k < (il + 3) / 4; ++k) {
;       const int jl0 = 4 * k;
;       float mv = DIR ? M[ri * MLD + 63 - jl0 - pp] : M[ri * MLD + jl0 + pp];
;       if (jl0 + 3 >= il) mv = (jl0 + pp < il) ? mv : 0.f;
;       part += mv * x[k];
;     }
;     part += __shfl_xor(part, 1); part += __shfl_xor(part, 2);
;     const float e = half ? __expf(gcl[ri]) : 1.f;
;     const float xi = betal[ri] * (float)src[ri * LDH] * e - part;
;     if ((il & 3) == pp) x[il >> 2] = xi;
;   }
	v_fmac_f32_e32 v122, v134, v4
	v_fmac_f32_e32 v122, v135, v5
	v_add_f32_dpp v125, v127, v127 quad_perm:[2,3,0,1] row_mask:0xf bank_mask:0xf
	v_fma_f32 v127, v40, v23, -v125
	v_cndmask_b32_e64 v7, v7, v127, s[88:89]
	s_waitcnt lgkmcnt(3)
	v_fmac_f32_e32 v122, v136, v6
	v_add_u32_e32 v121, 0x732c, v117
	ds_read2_b32 v[216:217], v121 offset0:20 offset1:16
	ds_read2_b32 v[218:219], v121 offset0:12 offset1:8
	ds_read2_b32 v[220:221], v121 offset0:4 offset1:0
	v_cndmask_b32_e64 v126, 0, v137, s[100:101]
	v_fma_f32 v125, v126, v7, v122
	s_waitcnt lgkmcnt(5)
	v_mul_f32_e32 v123, v148, v2
	v_fmac_f32_e32 v123, v149, v3
	v_add_f32_dpp v127, v125, v125 quad_perm:[1,0,3,2] row_mask:0xf bank_mask:0xf
	s_waitcnt lgkmcnt(4)
	v_fmac_f32_e32 v123, v150, v4
	v_fmac_f32_e32 v123, v151, v5
	v_add_f32_dpp v125, v127, v127 quad_perm:[2,3,0,1] row_mask:0xf bank_mask:0xf
	v_fma_f32 v127, v40, v23, -v125
	v_cndmask_b32_e64 v7, v7, v127, s[90:91]
	s_waitcnt lgkmcnt(3)
	v_fmac_f32_e32 v123, v152, v6
	v_add_u32_e32 v119, 0x721c, v117
	ds_read2_b32 v[132:133], v119 offset0:20 offset1:16
	ds_read2_b32 v[134:135], v119 offset0:12 offset1:8
	ds_read2_b32 v[136:137], v119 offset0:4 offset1:0
	v_cndmask_b32_e64 v126, 0, v153, s[18:19]
	v_fma_f32 v125, v126, v7, v123
	s_waitcnt lgkmcnt(5)
	v_mul_f32_e32 v124, v216, v2
	v_fmac_f32_e32 v124, v217, v3
	v_add_f32_dpp v127, v125, v125 quad_perm:[1,0,3,2] row_mask:0xf bank_mask:0xf
	s_waitcnt lgkmcnt(4)
	v_fmac_f32_e32 v124, v218, v4
	v_fmac_f32_e32 v124, v219, v5
	v_add_f32_dpp v125, v127, v127 quad_perm:[2,3,0,1] row_mask:0xf bank_mask:0xf
	v_fma_f32 v127, v40, v23, -v125
	v_cndmask_b32_e64 v7, v7, v127, s[92:93]
	s_waitcnt lgkmcnt(3)
	v_fmac_f32_e32 v124, v220, v6
	v_add_u32_e32 v120, 0x70fc, v117
	ds_read2_b32 v[148:149], v120 offset0:24 offset1:20
	ds_read2_b32 v[150:151], v120 offset0:16 offset1:12
	ds_read2_b32 v[152:153], v120 offset0:8 offset1:4
	ds_read_b32 v154, v120
	v_cndmask_b32_e64 v126, 0, v221, s[22:23]
	v_fma_f32 v125, v126, v7, v124
	s_waitcnt lgkmcnt(6)
	v_mul_f32_e32 v122, v132, v2
	v_fmac_f32_e32 v122, v133, v3
	v_add_f32_dpp v127, v125, v125 quad_perm:[1,0,3,2] row_mask:0xf bank_mask:0xf
	s_waitcnt lgkmcnt(5)
	v_fmac_f32_e32 v122, v134, v4
	v_fmac_f32_e32 v122, v135, v5
	v_add_f32_dpp v125, v127, v127 quad_perm:[2,3,0,1] row_mask:0xf bank_mask:0xf
	v_fma_f32 v127, v40, v23, -v125
	v_cndmask_b32_e64 v7, v7, v127, s[98:99]
	s_waitcnt lgkmcnt(4)
	v_fmac_f32_e32 v122, v136, v6
	v_add_u32_e32 v121, 0x6fec, v117
	ds_read2_b32 v[216:217], v121 offset0:24 offset1:20
	ds_read2_b32 v[218:219], v121 offset0:16 offset1:12
	ds_read2_b32 v[220:221], v121 offset0:8 offset1:4
	ds_read_b32 v222, v121
	v_fma_f32 v125, v137, v7, v122
	s_waitcnt lgkmcnt(7)
	v_mul_f32_e32 v123, v148, v2
	v_fmac_f32_e32 v123, v149, v3
	v_add_f32_dpp v127, v125, v125 quad_perm:[1,0,3,2] row_mask:0xf bank_mask:0xf
	s_waitcnt lgkmcnt(6)
	v_fmac_f32_e32 v123, v150, v4
	v_fmac_f32_e32 v123, v151, v5
	v_add_f32_dpp v125, v127, v127 quad_perm:[2,3,0,1] row_mask:0xf bank_mask:0xf
	v_fma_f32 v127, v41, v24, -v125
	v_cndmask_b32_e64 v8, v8, v127, s[88:89]
	s_waitcnt lgkmcnt(5)
	v_fmac_f32_e32 v123, v152, v6
	v_fmac_f32_e32 v123, v153, v7
	v_add_u32_e32 v119, 0x6edc, v117
	ds_read2_b32 v[132:133], v119 offset0:24 offset1:20
	ds_read2_b32 v[134:135], v119 offset0:16 offset1:12
	ds_read2_b32 v[136:137], v119 offset0:8 offset1:4
	ds_read_b32 v138, v119
	s_waitcnt lgkmcnt(8)
	v_cndmask_b32_e64 v126, 0, v154, s[100:101]
	v_fma_f32 v125, v126, v8, v123
	s_waitcnt lgkmcnt(7)
	v_mul_f32_e32 v124, v216, v2
	v_fmac_f32_e32 v124, v217, v3
	v_add_f32_dpp v127, v125, v125 quad_perm:[1,0,3,2] row_mask:0xf bank_mask:0xf
	s_waitcnt lgkmcnt(6)
	v_fmac_f32_e32 v124, v218, v4
	v_fmac_f32_e32 v124, v219, v5
	v_add_f32_dpp v125, v127, v127 quad_perm:[2,3,0,1] row_mask:0xf bank_mask:0xf
	v_fma_f32 v127, v41, v24, -v125
	v_cndmask_b32_e64 v8, v8, v127, s[90:91]
	s_waitcnt lgkmcnt(5)
	v_fmac_f32_e32 v124, v220, v6
	v_fmac_f32_e32 v124, v221, v7
	v_add_u32_e32 v120, 0x6dcc, v117
	ds_read2_b32 v[148:149], v120 offset0:24 offset1:20
	ds_read2_b32 v[150:151], v120 offset0:16 offset1:12
	ds_read2_b32 v[152:153], v120 offset0:8 offset1:4
	ds_read_b32 v154, v120
	s_waitcnt lgkmcnt(8)
	v_cndmask_b32_e64 v126, 0, v222, s[18:19]
	v_fma_f32 v125, v126, v8, v124
	s_waitcnt lgkmcnt(7)
	v_mul_f32_e32 v122, v132, v2
	v_fmac_f32_e32 v122, v133, v3
	v_add_f32_dpp v127, v125, v125 quad_perm:[1,0,3,2] row_mask:0xf bank_mask:0xf
	s_waitcnt lgkmcnt(6)
	v_fmac_f32_e32 v122, v134, v4
	v_fmac_f32_e32 v122, v135, v5
	v_add_f32_dpp v125, v127, v127 quad_perm:[2,3,0,1] row_mask:0xf bank_mask:0xf
	v_fma_f32 v127, v41, v24, -v125
	v_cndmask_b32_e64 v8, v8, v127, s[92:93]
	s_waitcnt lgkmcnt(5)
	v_fmac_f32_e32 v122, v136, v6
	v_fmac_f32_e32 v122, v137, v7
	v_add_u32_e32 v121, 0x6cac, v117
	ds_read2_b32 v[216:217], v121 offset0:28 offset1:24
	ds_read2_b32 v[218:219], v121 offset0:20 offset1:16
	ds_read2_b32 v[220:221], v121 offset0:12 offset1:8
	ds_read2_b32 v[222:223], v121 offset0:4 offset1:0
	s_waitcnt lgkmcnt(8)
	v_cndmask_b32_e64 v126, 0, v138, s[22:23]
	v_fma_f32 v125, v126, v8, v122
	s_waitcnt lgkmcnt(7)
	v_mul_f32_e32 v123, v148, v2
	v_fmac_f32_e32 v123, v149, v3
	v_add_f32_dpp v127, v125, v125 quad_perm:[1,0,3,2] row_mask:0xf bank_mask:0xf
	s_waitcnt lgkmcnt(6)
	v_fmac_f32_e32 v123, v150, v4
	v_fmac_f32_e32 v123, v151, v5
	v_add_f32_dpp v125, v127, v127 quad_perm:[2,3,0,1] row_mask:0xf bank_mask:0xf
	v_fma_f32 v127, v41, v24, -v125
	v_cndmask_b32_e64 v8, v8, v127, s[98:99]
	s_waitcnt lgkmcnt(5)
; template <int DIR>
; DI void dn_solve4(const float* M, const h16* Ki, const h16* Vi, const float* betal, const float* gcl, int half, int c, int pp, float (&x)[16]) {
;   const h16* src = half ? (Ki + c) : (Vi + c);
; #pragma unroll
;   for (int k = 0; k < 16; ++k) x[k] = 0.f;
; #pragma unroll
;   for (int il = 0; il < 64; ++il) {
;     const int ri = DIR ? 63 - il : il;
;     float part = 0.f;
; #pragma unroll
;     for (int k = 0; k < (il + 3) / 4; ++k) {
;       const int jl0 = 4 * k;
;       float mv = DIR ? M[ri * MLD + 63 - jl0 - pp] : M[ri * MLD + jl0 + pp];
;       if (jl0 + 3 >= il) mv = (jl0 + pp < il) ? mv : 0.f;
;       part += mv * x[k];
;     }
;     part += __shfl_xor(part, 1); part += __shfl_xor(part, 2);
;     const float e = half ? __expf(gcl[ri]) : 1.f;
;     const float xi = betal[ri] * (float)src[ri * LDH] * e - part;
;     if ((il & 3) == pp) x[il >> 2] = xi;
;   }
	v_fmac_f32_e32 v123, v152, v6
	v_fmac_f32_e32 v123, v153, v7
	v_add_u32_e32 v119, 0x6b9c, v117
	ds_read2_b32 v[132:133], v119 offset0:28 offset1:24
	ds_read2_b32 v[134:135], v119 offset0:20 offset1:16
	ds_read2_b32 v[136:137], v119 offset0:12 offset1:8
	ds_read2_b32 v[138:139], v119 offset0:4 offset1:0
	s_waitcnt lgkmcnt(8)
	v_fma_f32 v125, v154, v8, v123
	s_waitcnt lgkmcnt(7)
	v_mul_f32_e32 v124, v216, v2
	v_fmac_f32_e32 v124, v217, v3
	v_add_f32_dpp v127, v125, v125 quad_perm:[1,0,3,2] row_mask:0xf bank_mask:0xf
	s_waitcnt lgkmcnt(6)
	v_fmac_f32_e32 v124, v218, v4
	v_fmac_f32_e32 v124, v219, v5
	v_add_f32_dpp v125, v127, v127 quad_perm:[2,3,0,1] row_mask:0xf bank_mask:0xf
	v_fma_f32 v127, v42, v25, -v125
	v_cndmask_b32_e64 v9, v9, v127, s[88:89]
	s_waitcnt lgkmcnt(5)
	v_fmac_f32_e32 v124, v220, v6
	v_fmac_f32_e32 v124, v221, v7
	s_waitcnt lgkmcnt(4)
	v_fmac_f32_e32 v124, v222, v8
	v_add_u32_e32 v120, 0x6a8c, v117
	ds_read2_b32 v[148:149], v120 offset0:28 offset1:24
	ds_read2_b32 v[150:151], v120 offset0:20 offset1:16
	ds_read2_b32 v[152:153], v120 offset0:12 offset1:8
	ds_read2_b32 v[154:155], v120 offset0:4 offset1:0
	v_cndmask_b32_e64 v126, 0, v223, s[100:101]
	v_fma_f32 v125, v126, v9, v124
	s_waitcnt lgkmcnt(7)
	v_mul_f32_e32 v122, v132, v2
	v_fmac_f32_e32 v122, v133, v3
	v_add_f32_dpp v127, v125, v125 quad_perm:[1,0,3,2] row_mask:0xf bank_mask:0xf
	s_waitcnt lgkmcnt(6)
	v_fmac_f32_e32 v122, v134, v4
	v_fmac_f32_e32 v122, v135, v5
	v_add_f32_dpp v125, v127, v127 quad_perm:[2,3,0,1] row_mask:0xf bank_mask:0xf
	v_fma_f32 v127, v42, v25, -v125
	v_cndmask_b32_e64 v9, v9, v127, s[90:91]
	s_waitcnt lgkmcnt(5)
	v_fmac_f32_e32 v122, v136, v6
	v_fmac_f32_e32 v122, v137, v7
	s_waitcnt lgkmcnt(4)
	v_fmac_f32_e32 v122, v138, v8
	v_add_u32_e32 v121, 0x697c, v117
	ds_read2_b32 v[216:217], v121 offset0:28 offset1:24
	ds_read2_b32 v[218:219], v121 offset0:20 offset1:16
	ds_read2_b32 v[220:221], v121 offset0:12 offset1:8
	ds_read2_b32 v[222:223], v121 offset0:4 offset1:0
	v_cndmask_b32_e64 v126, 0, v139, s[18:19]
	v_fma_f32 v125, v126, v9, v122
	s_waitcnt lgkmcnt(7)
	v_mul_f32_e32 v123, v148, v2
	v_fmac_f32_e32 v123, v149, v3
	v_add_f32_dpp v127, v125, v125 quad_perm:[1,0,3,2] row_mask:0xf bank_mask:0xf
	s_waitcnt lgkmcnt(6)
	v_fmac_f32_e32 v123, v150, v4
	v_fmac_f32_e32 v123, v151, v5
	v_add_f32_dpp v125, v127, v127 quad_perm:[2,3,0,1] row_mask:0xf bank_mask:0xf
	v_fma_f32 v127, v42, v25, -v125
	v_cndmask_b32_e64 v9, v9, v127, s[92:93]
	s_waitcnt lgkmcnt(5)
	v_fmac_f32_e32 v123, v152, v6
	v_fmac_f32_e32 v123, v153, v7
	s_waitcnt lgkmcnt(4)
	v_fmac_f32_e32 v123, v154, v8
	v_add_u32_e32 v119, 0x685c, v117
	ds_read2_b32 v[132:133], v119 offset0:32 offset1:28
	ds_read2_b32 v[134:135], v119 offset0:24 offset1:20
	ds_read2_b32 v[136:137], v119 offset0:16 offset1:12
	ds_read2_b32 v[138:139], v119 offset0:8 offset1:4
	ds_read_b32 v140, v119
	v_cndmask_b32_e64 v126, 0, v155, s[22:23]
	v_fma_f32 v125, v126, v9, v123
	s_waitcnt lgkmcnt(8)
	v_mul_f32_e32 v124, v216, v2
	v_fmac_f32_e32 v124, v217, v3
	v_add_f32_dpp v127, v125, v125 quad_perm:[1,0,3,2] row_mask:0xf bank_mask:0xf
	s_waitcnt lgkmcnt(7)
	v_fmac_f32_e32 v124, v218, v4
	v_fmac_f32_e32 v124, v219, v5
	v_add_f32_dpp v125, v127, v127 quad_perm:[2,3,0,1] row_mask:0xf bank_mask:0xf
	v_fma_f32 v127, v42, v25, -v125
	v_cndmask_b32_e64 v9, v9, v127, s[98:99]
	s_waitcnt lgkmcnt(6)
	v_fmac_f32_e32 v124, v220, v6
	v_fmac_f32_e32 v124, v221, v7
	s_waitcnt lgkmcnt(5)
	v_fmac_f32_e32 v124, v222, v8
	v_add_u32_e32 v120, 0x674c, v117
	ds_read2_b32 v[148:149], v120 offset0:32 offset1:28
	ds_read2_b32 v[150:151], v120 offset0:24 offset1:20
	ds_read2_b32 v[152:153], v120 offset0:16 offset1:12
	ds_read2_b32 v[154:155], v120 offset0:8 offset1:4
	ds_read_b32 v156, v120
	v_fma_f32 v125, v223, v9, v124
	s_waitcnt lgkmcnt(9)
	v_mul_f32_e32 v122, v132, v2
	v_fmac_f32_e32 v122, v133, v3
	v_add_f32_dpp v127, v125, v125 quad_perm:[1,0,3,2] row_mask:0xf bank_mask:0xf
	s_waitcnt lgkmcnt(8)
	v_fmac_f32_e32 v122, v134, v4
	v_fmac_f32_e32 v122, v135, v5
	v_add_f32_dpp v125, v127, v127 quad_perm:[2,3,0,1] row_mask:0xf bank_mask:0xf
	v_fma_f32 v127, v43, v26, -v125
	v_cndmask_b32_e64 v10, v10, v127, s[88:89]
	s_waitcnt lgkmcnt(7)
	v_fmac_f32_e32 v122, v136, v6
	v_fmac_f32_e32 v122, v137, v7
	s_waitcnt lgkmcnt(6)
	v_fmac_f32_e32 v122, v138, v8
	v_fmac_f32_e32 v122, v139, v9
	v_add_u32_e32 v121, 0x663c, v117
	ds_read2_b32 v[216:217], v121 offset0:32 offset1:28
	ds_read2_b32 v[218:219], v121 offset0:24 offset1:20
	ds_read2_b32 v[220:221], v121 offset0:16 offset1:12
	ds_read2_b32 v[222:223], v121 offset0:8 offset1:4
	ds_read_b32 v224, v121
	s_waitcnt lgkmcnt(10)
	v_cndmask_b32_e64 v126, 0, v140, s[100:101]
	v_fma_f32 v125, v126, v10, v122
	s_waitcnt lgkmcnt(9)
	v_mul_f32_e32 v123, v148, v2
	v_fmac_f32_e32 v123, v149, v3
	v_add_f32_dpp v127, v125, v125 quad_perm:[1,0,3,2] row_mask:0xf bank_mask:0xf
	s_waitcnt lgkmcnt(8)
	v_fmac_f32_e32 v123, v150, v4
	v_fmac_f32_e32 v123, v151, v5
	v_add_f32_dpp v125, v127, v127 quad_perm:[2,3,0,1] row_mask:0xf bank_mask:0xf
	v_fma_f32 v127, v43, v26, -v125
	v_cndmask_b32_e64 v10, v10, v127, s[90:91]
	s_waitcnt lgkmcnt(7)
	v_fmac_f32_e32 v123, v152, v6
	v_fmac_f32_e32 v123, v153, v7
	s_waitcnt lgkmcnt(6)
	v_fmac_f32_e32 v123, v154, v8
	v_fmac_f32_e32 v123, v155, v9
	v_add_u32_e32 v119, 0x652c, v117
	ds_read2_b32 v[132:133], v119 offset0:32 offset1:28
	ds_read2_b32 v[134:135], v119 offset0:24 offset1:20
	ds_read2_b32 v[136:137], v119 offset0:16 offset1:12
	ds_read2_b32 v[138:139], v119 offset0:8 offset1:4
	ds_read_b32 v140, v119
	s_waitcnt lgkmcnt(10)
	v_cndmask_b32_e64 v126, 0, v156, s[18:19]
	v_fma_f32 v125, v126, v10, v123
	s_waitcnt lgkmcnt(9)
; template <int DIR>
; DI void dn_solve4(const float* M, const h16* Ki, const h16* Vi, const float* betal, const float* gcl, int half, int c, int pp, float (&x)[16]) {
;   const h16* src = half ? (Ki + c) : (Vi + c);
; #pragma unroll
;   for (int k = 0; k < 16; ++k) x[k] = 0.f;
; #pragma unroll
;   for (int il = 0; il < 64; ++il) {
;     const int ri = DIR ? 63 - il : il;
;     float part = 0.f;
; #pragma unroll
;     for (int k = 0; k < (il + 3) / 4; ++k) {
;       const int jl0 = 4 * k;
;       float mv = DIR ? M[ri * MLD + 63 - jl0 - pp] : M[ri * MLD + jl0 + pp];
;       if (jl0 + 3 >= il) mv = (jl0 + pp < il) ? mv : 0.f;
;       part += mv * x[k];
;     }
;     part += __shfl_xor(part, 1); part += __shfl_xor(part, 2);
;     const float e = half ? __expf(gcl[ri]) : 1.f;
;     const float xi = betal[ri] * (float)src[ri * LDH] * e - part;
;     if ((il & 3) == pp) x[il >> 2] = xi;
;   }
	v_mul_f32_e32 v124, v216, v2
	v_fmac_f32_e32 v124, v217, v3
	v_add_f32_dpp v127, v125, v125 quad_perm:[1,0,3,2] row_mask:0xf bank_mask:0xf
	s_waitcnt lgkmcnt(8)
	v_fmac_f32_e32 v124, v218, v4
	v_fmac_f32_e32 v124, v219, v5
	v_add_f32_dpp v125, v127, v127 quad_perm:[2,3,0,1] row_mask:0xf bank_mask:0xf
	v_fma_f32 v127, v43, v26, -v125
	v_cndmask_b32_e64 v10, v10, v127, s[92:93]
	s_waitcnt lgkmcnt(7)
	v_fmac_f32_e32 v124, v220, v6
	v_fmac_f32_e32 v124, v221, v7
	s_waitcnt lgkmcnt(6)
	v_fmac_f32_e32 v124, v222, v8
	v_fmac_f32_e32 v124, v223, v9
	v_add_u32_e32 v120, 0x640c, v117
	ds_read2_b32 v[148:149], v120 offset0:36 offset1:32
	ds_read2_b32 v[150:151], v120 offset0:28 offset1:24
	ds_read2_b32 v[152:153], v120 offset0:20 offset1:16
	ds_read2_b32 v[154:155], v120 offset0:12 offset1:8
	ds_read2_b32 v[156:157], v120 offset0:4 offset1:0
	s_waitcnt lgkmcnt(10)
	v_cndmask_b32_e64 v126, 0, v224, s[22:23]
	v_fma_f32 v125, v126, v10, v124
	s_waitcnt lgkmcnt(9)
	v_mul_f32_e32 v122, v132, v2
	v_fmac_f32_e32 v122, v133, v3
	v_add_f32_dpp v127, v125, v125 quad_perm:[1,0,3,2] row_mask:0xf bank_mask:0xf
	s_waitcnt lgkmcnt(8)
	v_fmac_f32_e32 v122, v134, v4
	v_fmac_f32_e32 v122, v135, v5
	v_add_f32_dpp v125, v127, v127 quad_perm:[2,3,0,1] row_mask:0xf bank_mask:0xf
	v_fma_f32 v127, v43, v26, -v125
	v_cndmask_b32_e64 v10, v10, v127, s[98:99]
	s_waitcnt lgkmcnt(7)
	v_fmac_f32_e32 v122, v136, v6
	v_fmac_f32_e32 v122, v137, v7
	s_waitcnt lgkmcnt(6)
	v_fmac_f32_e32 v122, v138, v8
	v_fmac_f32_e32 v122, v139, v9
	v_add_u32_e32 v121, 0x62fc, v117
	ds_read2_b32 v[216:217], v121 offset0:36 offset1:32
	ds_read2_b32 v[218:219], v121 offset0:28 offset1:24
	ds_read2_b32 v[220:221], v121 offset0:20 offset1:16
	ds_read2_b32 v[222:223], v121 offset0:12 offset1:8
	ds_read2_b32 v[224:225], v121 offset0:4 offset1:0
	s_waitcnt lgkmcnt(10)
	v_fma_f32 v125, v140, v10, v122
	s_waitcnt lgkmcnt(9)
	v_mul_f32_e32 v123, v148, v2
	v_fmac_f32_e32 v123, v149, v3
	v_add_f32_dpp v127, v125, v125 quad_perm:[1,0,3,2] row_mask:0xf bank_mask:0xf
	s_waitcnt lgkmcnt(8)
	v_fmac_f32_e32 v123, v150, v4
	v_fmac_f32_e32 v123, v151, v5
	v_add_f32_dpp v125, v127, v127 quad_perm:[2,3,0,1] row_mask:0xf bank_mask:0xf
	v_fma_f32 v127, v44, v27, -v125
	v_cndmask_b32_e64 v11, v11, v127, s[88:89]
	s_waitcnt lgkmcnt(7)
	v_fmac_f32_e32 v123, v152, v6
	v_fmac_f32_e32 v123, v153, v7
	s_waitcnt lgkmcnt(6)
	v_fmac_f32_e32 v123, v154, v8
	v_fmac_f32_e32 v123, v155, v9
	s_waitcnt lgkmcnt(5)
	v_fmac_f32_e32 v123, v156, v10
	v_add_u32_e32 v119, 0x61ec, v117
	ds_read2_b32 v[132:133], v119 offset0:36 offset1:32
	ds_read2_b32 v[134:135], v119 offset0:28 offset1:24
	ds_read2_b32 v[136:137], v119 offset0:20 offset1:16
	ds_read2_b32 v[138:139], v119 offset0:12 offset1:8
	ds_read2_b32 v[140:141], v119 offset0:4 offset1:0
	v_cndmask_b32_e64 v126, 0, v157, s[100:101]
	v_fma_f32 v125, v126, v11, v123
	s_waitcnt lgkmcnt(9)
	v_mul_f32_e32 v124, v216, v2
	v_fmac_f32_e32 v124, v217, v3
	v_add_f32_dpp v127, v125, v125 quad_perm:[1,0,3,2] row_mask:0xf bank_mask:0xf
	s_waitcnt lgkmcnt(8)
	v_fmac_f32_e32 v124, v218, v4
	v_fmac_f32_e32 v124, v219, v5
	v_add_f32_dpp v125, v127, v127 quad_perm:[2,3,0,1] row_mask:0xf bank_mask:0xf
	v_fma_f32 v127, v44, v27, -v125
	v_cndmask_b32_e64 v11, v11, v127, s[90:91]
	s_waitcnt lgkmcnt(7)
	v_fmac_f32_e32 v124, v220, v6
	v_fmac_f32_e32 v124, v221, v7
	s_waitcnt lgkmcnt(6)
	v_fmac_f32_e32 v124, v222, v8
	v_fmac_f32_e32 v124, v223, v9
	s_waitcnt lgkmcnt(5)
	v_fmac_f32_e32 v124, v224, v10
	v_add_u32_e32 v120, 0x60dc, v117
	ds_read2_b32 v[148:149], v120 offset0:36 offset1:32
	ds_read2_b32 v[150:151], v120 offset0:28 offset1:24
	ds_read2_b32 v[152:153], v120 offset0:20 offset1:16
	ds_read2_b32 v[154:155], v120 offset0:12 offset1:8
	ds_read2_b32 v[156:157], v120 offset0:4 offset1:0
	v_cndmask_b32_e64 v126, 0, v225, s[18:19]
	v_fma_f32 v125, v126, v11, v124
	s_waitcnt lgkmcnt(9)
	v_mul_f32_e32 v122, v132, v2
	v_fmac_f32_e32 v122, v133, v3
	v_add_f32_dpp v127, v125, v125 quad_perm:[1,0,3,2] row_mask:0xf bank_mask:0xf
	s_waitcnt lgkmcnt(8)
	v_fmac_f32_e32 v122, v134, v4
	v_fmac_f32_e32 v122, v135, v5
	v_add_f32_dpp v125, v127, v127 quad_perm:[2,3,0,1] row_mask:0xf bank_mask:0xf
	v_fma_f32 v127, v44, v27, -v125
	v_cndmask_b32_e64 v11, v11, v127, s[92:93]
	s_waitcnt lgkmcnt(7)
	v_fmac_f32_e32 v122, v136, v6
	v_fmac_f32_e32 v122, v137, v7
	s_waitcnt lgkmcnt(6)
	v_fmac_f32_e32 v122, v138, v8
	v_fmac_f32_e32 v122, v139, v9
	s_waitcnt lgkmcnt(5)
	v_fmac_f32_e32 v122, v140, v10
	v_add_u32_e32 v121, 0x5fbc, v117
	ds_read2_b32 v[216:217], v121 offset0:40 offset1:36
	ds_read2_b32 v[218:219], v121 offset0:32 offset1:28
	ds_read2_b32 v[220:221], v121 offset0:24 offset1:20
	ds_read2_b32 v[222:223], v121 offset0:16 offset1:12
	ds_read2_b32 v[224:225], v121 offset0:8 offset1:4
	ds_read_b32 v226, v121
	v_cndmask_b32_e64 v126, 0, v141, s[22:23]
	v_fma_f32 v125, v126, v11, v122
	s_waitcnt lgkmcnt(10)
	v_mul_f32_e32 v123, v148, v2
	v_fmac_f32_e32 v123, v149, v3
	v_add_f32_dpp v127, v125, v125 quad_perm:[1,0,3,2] row_mask:0xf bank_mask:0xf
	s_waitcnt lgkmcnt(9)
	v_fmac_f32_e32 v123, v150, v4
	v_fmac_f32_e32 v123, v151, v5
	v_add_f32_dpp v125, v127, v127 quad_perm:[2,3,0,1] row_mask:0xf bank_mask:0xf
	v_fma_f32 v127, v44, v27, -v125
	v_cndmask_b32_e64 v11, v11, v127, s[98:99]
	s_waitcnt lgkmcnt(8)
	v_fmac_f32_e32 v123, v152, v6
	v_fmac_f32_e32 v123, v153, v7
	s_waitcnt lgkmcnt(7)
	v_fmac_f32_e32 v123, v154, v8
	v_fmac_f32_e32 v123, v155, v9
	s_waitcnt lgkmcnt(6)
; template <int DIR>
; DI void dn_solve4(const float* M, const h16* Ki, const h16* Vi, const float* betal, const float* gcl, int half, int c, int pp, float (&x)[16]) {
;   const h16* src = half ? (Ki + c) : (Vi + c);
; #pragma unroll
;   for (int k = 0; k < 16; ++k) x[k] = 0.f;
; #pragma unroll
;   for (int il = 0; il < 64; ++il) {
;     const int ri = DIR ? 63 - il : il;
;     float part = 0.f;
; #pragma unroll
;     for (int k = 0; k < (il + 3) / 4; ++k) {
;       const int jl0 = 4 * k;
;       float mv = DIR ? M[ri * MLD + 63 - jl0 - pp] : M[ri * MLD + jl0 + pp];
;       if (jl0 + 3 >= il) mv = (jl0 + pp < il) ? mv : 0.f;
;       part += mv * x[k];
;     }
;     part += __shfl_xor(part, 1); part += __shfl_xor(part, 2);
;     const float e = half ? __expf(gcl[ri]) : 1.f;
;     const float xi = betal[ri] * (float)src[ri * LDH] * e - part;
;     if ((il & 3) == pp) x[il >> 2] = xi;
;   }
	v_fmac_f32_e32 v123, v156, v10
	v_add_u32_e32 v119, 0x5eac, v117
	ds_read2_b32 v[132:133], v119 offset0:40 offset1:36
	ds_read2_b32 v[134:135], v119 offset0:32 offset1:28
	ds_read2_b32 v[136:137], v119 offset0:24 offset1:20
	ds_read2_b32 v[138:139], v119 offset0:16 offset1:12
	ds_read2_b32 v[140:141], v119 offset0:8 offset1:4
	ds_read_b32 v142, v119
	v_fma_f32 v125, v157, v11, v123
	s_waitcnt lgkmcnt(11)
	v_mul_f32_e32 v124, v216, v2
	v_fmac_f32_e32 v124, v217, v3
	v_add_f32_dpp v127, v125, v125 quad_perm:[1,0,3,2] row_mask:0xf bank_mask:0xf
	s_waitcnt lgkmcnt(10)
	v_fmac_f32_e32 v124, v218, v4
	v_fmac_f32_e32 v124, v219, v5
	v_add_f32_dpp v125, v127, v127 quad_perm:[2,3,0,1] row_mask:0xf bank_mask:0xf
	v_fma_f32 v127, v45, v28, -v125
	v_cndmask_b32_e64 v12, v12, v127, s[88:89]
	s_waitcnt lgkmcnt(9)
	v_fmac_f32_e32 v124, v220, v6
	v_fmac_f32_e32 v124, v221, v7
	s_waitcnt lgkmcnt(8)
	v_fmac_f32_e32 v124, v222, v8
	v_fmac_f32_e32 v124, v223, v9
	s_waitcnt lgkmcnt(7)
	v_fmac_f32_e32 v124, v224, v10
	v_fmac_f32_e32 v124, v225, v11
	v_add_u32_e32 v120, 0x5d9c, v117
	ds_read2_b32 v[148:149], v120 offset0:40 offset1:36
	ds_read2_b32 v[150:151], v120 offset0:32 offset1:28
	ds_read2_b32 v[152:153], v120 offset0:24 offset1:20
	ds_read2_b32 v[154:155], v120 offset0:16 offset1:12
	ds_read2_b32 v[156:157], v120 offset0:8 offset1:4
	ds_read_b32 v158, v120
	s_waitcnt lgkmcnt(12)
	v_cndmask_b32_e64 v126, 0, v226, s[100:101]
	v_fma_f32 v125, v126, v12, v124
	s_waitcnt lgkmcnt(11)
	v_mul_f32_e32 v122, v132, v2
	v_fmac_f32_e32 v122, v133, v3
	v_add_f32_dpp v127, v125, v125 quad_perm:[1,0,3,2] row_mask:0xf bank_mask:0xf
	s_waitcnt lgkmcnt(10)
	v_fmac_f32_e32 v122, v134, v4
	v_fmac_f32_e32 v122, v135, v5
	v_add_f32_dpp v125, v127, v127 quad_perm:[2,3,0,1] row_mask:0xf bank_mask:0xf
	v_fma_f32 v127, v45, v28, -v125
	v_cndmask_b32_e64 v12, v12, v127, s[90:91]
	s_waitcnt lgkmcnt(9)
	v_fmac_f32_e32 v122, v136, v6
	v_fmac_f32_e32 v122, v137, v7
	s_waitcnt lgkmcnt(8)
	v_fmac_f32_e32 v122, v138, v8
	v_fmac_f32_e32 v122, v139, v9
	s_waitcnt lgkmcnt(7)
	v_fmac_f32_e32 v122, v140, v10
	v_fmac_f32_e32 v122, v141, v11
	v_add_u32_e32 v121, 0x5c8c, v117
	ds_read2_b32 v[216:217], v121 offset0:40 offset1:36
	ds_read2_b32 v[218:219], v121 offset0:32 offset1:28
	ds_read2_b32 v[220:221], v121 offset0:24 offset1:20
	ds_read2_b32 v[222:223], v121 offset0:16 offset1:12
	ds_read2_b32 v[224:225], v121 offset0:8 offset1:4
	ds_read_b32 v226, v121
	s_waitcnt lgkmcnt(12)
	v_cndmask_b32_e64 v126, 0, v142, s[18:19]
	v_fma_f32 v125, v126, v12, v122
	s_waitcnt lgkmcnt(11)
	v_mul_f32_e32 v123, v148, v2
	v_fmac_f32_e32 v123, v149, v3
	v_add_f32_dpp v127, v125, v125 quad_perm:[1,0,3,2] row_mask:0xf bank_mask:0xf
	s_waitcnt lgkmcnt(10)
	v_fmac_f32_e32 v123, v150, v4
	v_fmac_f32_e32 v123, v151, v5
	v_add_f32_dpp v125, v127, v127 quad_perm:[2,3,0,1] row_mask:0xf bank_mask:0xf
	v_fma_f32 v127, v45, v28, -v125
	v_cndmask_b32_e64 v12, v12, v127, s[92:93]
	s_waitcnt lgkmcnt(9)
	v_fmac_f32_e32 v123, v152, v6
	v_fmac_f32_e32 v123, v153, v7
	s_waitcnt lgkmcnt(8)
	v_fmac_f32_e32 v123, v154, v8
	v_fmac_f32_e32 v123, v155, v9
	s_waitcnt lgkmcnt(7)
	v_fmac_f32_e32 v123, v156, v10
	v_fmac_f32_e32 v123, v157, v11
	v_add_u32_e32 v119, 0x5b6c, v117
	ds_read2_b32 v[132:133], v119 offset0:44 offset1:40
	ds_read2_b32 v[134:135], v119 offset0:36 offset1:32
	ds_read2_b32 v[136:137], v119 offset0:28 offset1:24
	ds_read2_b32 v[138:139], v119 offset0:20 offset1:16
	ds_read2_b32 v[140:141], v119 offset0:12 offset1:8
	ds_read2_b32 v[142:143], v119 offset0:4 offset1:0
	s_waitcnt lgkmcnt(12)
	v_cndmask_b32_e64 v126, 0, v158, s[22:23]
	v_fma_f32 v125, v126, v12, v123
	s_waitcnt lgkmcnt(11)
	v_mul_f32_e32 v124, v216, v2
	v_fmac_f32_e32 v124, v217, v3
	v_add_f32_dpp v127, v125, v125 quad_perm:[1,0,3,2] row_mask:0xf bank_mask:0xf
	s_waitcnt lgkmcnt(10)
	v_fmac_f32_e32 v124, v218, v4
	v_fmac_f32_e32 v124, v219, v5
	v_add_f32_dpp v125, v127, v127 quad_perm:[2,3,0,1] row_mask:0xf bank_mask:0xf
	v_fma_f32 v127, v45, v28, -v125
	v_cndmask_b32_e64 v12, v12, v127, s[98:99]
	s_waitcnt lgkmcnt(9)
	v_fmac_f32_e32 v124, v220, v6
	v_fmac_f32_e32 v124, v221, v7
	s_waitcnt lgkmcnt(8)
	v_fmac_f32_e32 v124, v222, v8
	v_fmac_f32_e32 v124, v223, v9
	s_waitcnt lgkmcnt(7)
	v_fmac_f32_e32 v124, v224, v10
	v_fmac_f32_e32 v124, v225, v11
	v_add_u32_e32 v120, 0x5a5c, v117
	ds_read2_b32 v[148:149], v120 offset0:44 offset1:40
	ds_read2_b32 v[150:151], v120 offset0:36 offset1:32
	ds_read2_b32 v[152:153], v120 offset0:28 offset1:24
	ds_read2_b32 v[154:155], v120 offset0:20 offset1:16
	ds_read2_b32 v[156:157], v120 offset0:12 offset1:8
	ds_read2_b32 v[158:159], v120 offset0:4 offset1:0
	s_waitcnt lgkmcnt(12)
	v_fma_f32 v125, v226, v12, v124
	s_waitcnt lgkmcnt(11)
	v_mul_f32_e32 v122, v132, v2
	v_fmac_f32_e32 v122, v133, v3
	v_add_f32_dpp v127, v125, v125 quad_perm:[1,0,3,2] row_mask:0xf bank_mask:0xf
	s_waitcnt lgkmcnt(10)
	v_fmac_f32_e32 v122, v134, v4
	v_fmac_f32_e32 v122, v135, v5
	v_add_f32_dpp v125, v127, v127 quad_perm:[2,3,0,1] row_mask:0xf bank_mask:0xf
	v_fma_f32 v127, v46, v30, -v125
	v_cndmask_b32_e64 v13, v13, v127, s[88:89]
	s_waitcnt lgkmcnt(9)
	v_fmac_f32_e32 v122, v136, v6
	v_fmac_f32_e32 v122, v137, v7
	s_waitcnt lgkmcnt(8)
	v_fmac_f32_e32 v122, v138, v8
	v_fmac_f32_e32 v122, v139, v9
	s_waitcnt lgkmcnt(7)
	v_fmac_f32_e32 v122, v140, v10
	v_fmac_f32_e32 v122, v141, v11
	s_waitcnt lgkmcnt(6)
	v_fmac_f32_e32 v122, v142, v12
	v_add_u32_e32 v121, 0x594c, v117
	ds_read2_b32 v[216:217], v121 offset0:44 offset1:40
	ds_read2_b32 v[218:219], v121 offset0:36 offset1:32
	ds_read2_b32 v[220:221], v121 offset0:28 offset1:24
	ds_read2_b32 v[222:223], v121 offset0:20 offset1:16
	ds_read2_b32 v[224:225], v121 offset0:12 offset1:8
	ds_read2_b32 v[226:227], v121 offset0:4 offset1:0
	v_cndmask_b32_e64 v126, 0, v143, s[100:101]
	v_fma_f32 v125, v126, v13, v122
	s_waitcnt lgkmcnt(11)
; template <int DIR>
; DI void dn_solve4(const float* M, const h16* Ki, const h16* Vi, const float* betal, const float* gcl, int half, int c, int pp, float (&x)[16]) {
;   const h16* src = half ? (Ki + c) : (Vi + c);
; #pragma unroll
;   for (int k = 0; k < 16; ++k) x[k] = 0.f;
; #pragma unroll
;   for (int il = 0; il < 64; ++il) {
;     const int ri = DIR ? 63 - il : il;
;     float part = 0.f;
; #pragma unroll
;     for (int k = 0; k < (il + 3) / 4; ++k) {
;       const int jl0 = 4 * k;
;       float mv = DIR ? M[ri * MLD + 63 - jl0 - pp] : M[ri * MLD + jl0 + pp];
;       if (jl0 + 3 >= il) mv = (jl0 + pp < il) ? mv : 0.f;
;       part += mv * x[k];
;     }
;     part += __shfl_xor(part, 1); part += __shfl_xor(part, 2);
;     const float e = half ? __expf(gcl[ri]) : 1.f;
;     const float xi = betal[ri] * (float)src[ri * LDH] * e - part;
;     if ((il & 3) == pp) x[il >> 2] = xi;
;   }
	v_mul_f32_e32 v123, v148, v2
	v_fmac_f32_e32 v123, v149, v3
	v_add_f32_dpp v127, v125, v125 quad_perm:[1,0,3,2] row_mask:0xf bank_mask:0xf
	s_waitcnt lgkmcnt(10)
	v_fmac_f32_e32 v123, v150, v4
	v_fmac_f32_e32 v123, v151, v5
	v_add_f32_dpp v125, v127, v127 quad_perm:[2,3,0,1] row_mask:0xf bank_mask:0xf
	v_fma_f32 v127, v46, v30, -v125
	v_cndmask_b32_e64 v13, v13, v127, s[90:91]
	s_waitcnt lgkmcnt(9)
	v_fmac_f32_e32 v123, v152, v6
	v_fmac_f32_e32 v123, v153, v7
	s_waitcnt lgkmcnt(8)
	v_fmac_f32_e32 v123, v154, v8
	v_fmac_f32_e32 v123, v155, v9
	s_waitcnt lgkmcnt(7)
	v_fmac_f32_e32 v123, v156, v10
	v_fmac_f32_e32 v123, v157, v11
	s_waitcnt lgkmcnt(6)
	v_fmac_f32_e32 v123, v158, v12
	v_add_u32_e32 v119, 0x583c, v117
	ds_read2_b32 v[132:133], v119 offset0:44 offset1:40
	ds_read2_b32 v[134:135], v119 offset0:36 offset1:32
	ds_read2_b32 v[136:137], v119 offset0:28 offset1:24
	ds_read2_b32 v[138:139], v119 offset0:20 offset1:16
	ds_read2_b32 v[140:141], v119 offset0:12 offset1:8
	ds_read2_b32 v[142:143], v119 offset0:4 offset1:0
	v_cndmask_b32_e64 v126, 0, v159, s[18:19]
	v_fma_f32 v125, v126, v13, v123
	s_waitcnt lgkmcnt(11)
	v_mul_f32_e32 v124, v216, v2
	v_fmac_f32_e32 v124, v217, v3
	v_add_f32_dpp v127, v125, v125 quad_perm:[1,0,3,2] row_mask:0xf bank_mask:0xf
	s_waitcnt lgkmcnt(10)
	v_fmac_f32_e32 v124, v218, v4
	v_fmac_f32_e32 v124, v219, v5
	v_add_f32_dpp v125, v127, v127 quad_perm:[2,3,0,1] row_mask:0xf bank_mask:0xf
	v_fma_f32 v127, v46, v30, -v125
	v_cndmask_b32_e64 v13, v13, v127, s[92:93]
	s_waitcnt lgkmcnt(9)
	v_fmac_f32_e32 v124, v220, v6
	v_fmac_f32_e32 v124, v221, v7
	s_waitcnt lgkmcnt(8)
	v_fmac_f32_e32 v124, v222, v8
	v_fmac_f32_e32 v124, v223, v9
	s_waitcnt lgkmcnt(7)
	v_fmac_f32_e32 v124, v224, v10
	v_fmac_f32_e32 v124, v225, v11
	s_waitcnt lgkmcnt(6)
	v_fmac_f32_e32 v124, v226, v12
	v_add_u32_e32 v120, 0x571c, v117
	ds_read2_b32 v[148:149], v120 offset0:48 offset1:44
	ds_read2_b32 v[150:151], v120 offset0:40 offset1:36
	ds_read2_b32 v[152:153], v120 offset0:32 offset1:28
	ds_read2_b32 v[154:155], v120 offset0:24 offset1:20
	ds_read2_b32 v[156:157], v120 offset0:16 offset1:12
	ds_read2_b32 v[158:159], v120 offset0:8 offset1:4
	ds_read_b32 v160, v120
	v_cndmask_b32_e64 v126, 0, v227, s[22:23]
	v_fma_f32 v125, v126, v13, v124
	s_waitcnt lgkmcnt(12)
	v_mul_f32_e32 v122, v132, v2
	v_fmac_f32_e32 v122, v133, v3
	v_add_f32_dpp v127, v125, v125 quad_perm:[1,0,3,2] row_mask:0xf bank_mask:0xf
	s_waitcnt lgkmcnt(11)
	v_fmac_f32_e32 v122, v134, v4
	v_fmac_f32_e32 v122, v135, v5
	v_add_f32_dpp v125, v127, v127 quad_perm:[2,3,0,1] row_mask:0xf bank_mask:0xf
	v_fma_f32 v127, v46, v30, -v125
	v_cndmask_b32_e64 v13, v13, v127, s[98:99]
	s_waitcnt lgkmcnt(10)
	v_fmac_f32_e32 v122, v136, v6
	v_fmac_f32_e32 v122, v137, v7
	s_waitcnt lgkmcnt(9)
	v_fmac_f32_e32 v122, v138, v8
	v_fmac_f32_e32 v122, v139, v9
	s_waitcnt lgkmcnt(8)
	v_fmac_f32_e32 v122, v140, v10
	v_fmac_f32_e32 v122, v141, v11
	s_waitcnt lgkmcnt(7)
	v_fmac_f32_e32 v122, v142, v12
	v_add_u32_e32 v121, 0x560c, v117
	ds_read2_b32 v[216:217], v121 offset0:48 offset1:44
	ds_read2_b32 v[218:219], v121 offset0:40 offset1:36
	ds_read2_b32 v[220:221], v121 offset0:32 offset1:28
	ds_read2_b32 v[222:223], v121 offset0:24 offset1:20
	ds_read2_b32 v[224:225], v121 offset0:16 offset1:12
	ds_read2_b32 v[226:227], v121 offset0:8 offset1:4
	ds_read_b32 v228, v121
	v_fma_f32 v125, v143, v13, v122
	s_waitcnt lgkmcnt(13)
	v_mul_f32_e32 v123, v148, v2
	v_fmac_f32_e32 v123, v149, v3
	v_add_f32_dpp v127, v125, v125 quad_perm:[1,0,3,2] row_mask:0xf bank_mask:0xf
	s_waitcnt lgkmcnt(12)
	v_fmac_f32_e32 v123, v150, v4
	v_fmac_f32_e32 v123, v151, v5
	v_add_f32_dpp v125, v127, v127 quad_perm:[2,3,0,1] row_mask:0xf bank_mask:0xf
	v_fma_f32 v127, v47, v31, -v125
	v_cndmask_b32_e64 v14, v14, v127, s[88:89]
	s_waitcnt lgkmcnt(11)
	v_fmac_f32_e32 v123, v152, v6
	v_fmac_f32_e32 v123, v153, v7
	s_waitcnt lgkmcnt(10)
	v_fmac_f32_e32 v123, v154, v8
	v_fmac_f32_e32 v123, v155, v9
	s_waitcnt lgkmcnt(9)
	v_fmac_f32_e32 v123, v156, v10
	v_fmac_f32_e32 v123, v157, v11
	s_waitcnt lgkmcnt(8)
	v_fmac_f32_e32 v123, v158, v12
	v_fmac_f32_e32 v123, v159, v13
	v_add_u32_e32 v119, 0x54fc, v117
	ds_read2_b32 v[132:133], v119 offset0:48 offset1:44
	ds_read2_b32 v[134:135], v119 offset0:40 offset1:36
	ds_read2_b32 v[136:137], v119 offset0:32 offset1:28
	ds_read2_b32 v[138:139], v119 offset0:24 offset1:20
	ds_read2_b32 v[140:141], v119 offset0:16 offset1:12
	ds_read2_b32 v[142:143], v119 offset0:8 offset1:4
	ds_read_b32 v144, v119
	s_waitcnt lgkmcnt(14)
	v_cndmask_b32_e64 v126, 0, v160, s[100:101]
	v_fma_f32 v125, v126, v14, v123
	s_waitcnt lgkmcnt(13)
	v_mul_f32_e32 v124, v216, v2
	v_fmac_f32_e32 v124, v217, v3
	v_add_f32_dpp v127, v125, v125 quad_perm:[1,0,3,2] row_mask:0xf bank_mask:0xf
	s_waitcnt lgkmcnt(12)
	v_fmac_f32_e32 v124, v218, v4
	v_fmac_f32_e32 v124, v219, v5
	v_add_f32_dpp v125, v127, v127 quad_perm:[2,3,0,1] row_mask:0xf bank_mask:0xf
	v_fma_f32 v127, v47, v31, -v125
	v_cndmask_b32_e64 v14, v14, v127, s[90:91]
	s_waitcnt lgkmcnt(11)
	v_fmac_f32_e32 v124, v220, v6
	v_fmac_f32_e32 v124, v221, v7
	s_waitcnt lgkmcnt(10)
	v_fmac_f32_e32 v124, v222, v8
	v_fmac_f32_e32 v124, v223, v9
	s_waitcnt lgkmcnt(9)
	v_fmac_f32_e32 v124, v224, v10
	v_fmac_f32_e32 v124, v225, v11
	s_waitcnt lgkmcnt(8)
	v_fmac_f32_e32 v124, v226, v12
	v_fmac_f32_e32 v124, v227, v13
	v_add_u32_e32 v120, 0x53ec, v117
	ds_read2_b32 v[148:149], v120 offset0:48 offset1:44
	ds_read2_b32 v[150:151], v120 offset0:40 offset1:36
	ds_read2_b32 v[152:153], v120 offset0:32 offset1:28
	ds_read2_b32 v[154:155], v120 offset0:24 offset1:20
	ds_read2_b32 v[156:157], v120 offset0:16 offset1:12
	ds_read2_b32 v[158:159], v120 offset0:8 offset1:4
	ds_read_b32 v160, v120
	s_waitcnt lgkmcnt(14)
; template <int DIR>
; DI void dn_solve4(const float* M, const h16* Ki, const h16* Vi, const float* betal, const float* gcl, int half, int c, int pp, float (&x)[16]) {
;   const h16* src = half ? (Ki + c) : (Vi + c);
; #pragma unroll
;   for (int k = 0; k < 16; ++k) x[k] = 0.f;
; #pragma unroll
;   for (int il = 0; il < 64; ++il) {
;     const int ri = DIR ? 63 - il : il;
;     float part = 0.f;
; #pragma unroll
;     for (int k = 0; k < (il + 3) / 4; ++k) {
;       const int jl0 = 4 * k;
;       float mv = DIR ? M[ri * MLD + 63 - jl0 - pp] : M[ri * MLD + jl0 + pp];
;       if (jl0 + 3 >= il) mv = (jl0 + pp < il) ? mv : 0.f;
;       part += mv * x[k];
;     }
;     part += __shfl_xor(part, 1); part += __shfl_xor(part, 2);
;     const float e = half ? __expf(gcl[ri]) : 1.f;
;     const float xi = betal[ri] * (float)src[ri * LDH] * e - part;
;     if ((il & 3) == pp) x[il >> 2] = xi;
;   }
	v_cndmask_b32_e64 v126, 0, v228, s[18:19]
	v_fma_f32 v125, v126, v14, v124
	s_waitcnt lgkmcnt(13)
	v_mul_f32_e32 v122, v132, v2
	v_fmac_f32_e32 v122, v133, v3
	v_add_f32_dpp v127, v125, v125 quad_perm:[1,0,3,2] row_mask:0xf bank_mask:0xf
	s_waitcnt lgkmcnt(12)
	v_fmac_f32_e32 v122, v134, v4
	v_fmac_f32_e32 v122, v135, v5
	v_add_f32_dpp v125, v127, v127 quad_perm:[2,3,0,1] row_mask:0xf bank_mask:0xf
	v_fma_f32 v127, v47, v31, -v125
	v_cndmask_b32_e64 v14, v14, v127, s[92:93]
	s_waitcnt lgkmcnt(11)
	v_fmac_f32_e32 v122, v136, v6
	v_fmac_f32_e32 v122, v137, v7
	s_waitcnt lgkmcnt(10)
	v_fmac_f32_e32 v122, v138, v8
	v_fmac_f32_e32 v122, v139, v9
	s_waitcnt lgkmcnt(9)
	v_fmac_f32_e32 v122, v140, v10
	v_fmac_f32_e32 v122, v141, v11
	s_waitcnt lgkmcnt(8)
	v_fmac_f32_e32 v122, v142, v12
	v_fmac_f32_e32 v122, v143, v13
	v_add_u32_e32 v121, 0x52cc, v117
	ds_read2_b32 v[216:217], v121 offset0:52 offset1:48
	ds_read2_b32 v[218:219], v121 offset0:44 offset1:40
	ds_read2_b32 v[220:221], v121 offset0:36 offset1:32
	ds_read2_b32 v[222:223], v121 offset0:28 offset1:24
	ds_read2_b32 v[224:225], v121 offset0:20 offset1:16
	ds_read2_b32 v[226:227], v121 offset0:12 offset1:8
	ds_read2_b32 v[228:229], v121 offset0:4 offset1:0
	s_waitcnt lgkmcnt(14)
	v_cndmask_b32_e64 v126, 0, v144, s[22:23]
	v_fma_f32 v125, v126, v14, v122
	s_waitcnt lgkmcnt(13)
	v_mul_f32_e32 v123, v148, v2
	v_fmac_f32_e32 v123, v149, v3
	v_add_f32_dpp v127, v125, v125 quad_perm:[1,0,3,2] row_mask:0xf bank_mask:0xf
	s_waitcnt lgkmcnt(12)
	v_fmac_f32_e32 v123, v150, v4
	v_fmac_f32_e32 v123, v151, v5
	v_add_f32_dpp v125, v127, v127 quad_perm:[2,3,0,1] row_mask:0xf bank_mask:0xf
	v_fma_f32 v127, v47, v31, -v125
	v_cndmask_b32_e64 v14, v14, v127, s[98:99]
	s_waitcnt lgkmcnt(11)
	v_fmac_f32_e32 v123, v152, v6
	v_fmac_f32_e32 v123, v153, v7
	s_waitcnt lgkmcnt(10)
	v_fmac_f32_e32 v123, v154, v8
	v_fmac_f32_e32 v123, v155, v9
	s_waitcnt lgkmcnt(9)
	v_fmac_f32_e32 v123, v156, v10
	v_fmac_f32_e32 v123, v157, v11
	s_waitcnt lgkmcnt(8)
	v_fmac_f32_e32 v123, v158, v12
	v_fmac_f32_e32 v123, v159, v13
	v_add_u32_e32 v119, 0x51bc, v117
	ds_read2_b32 v[132:133], v119 offset0:52 offset1:48
	ds_read2_b32 v[134:135], v119 offset0:44 offset1:40
	ds_read2_b32 v[136:137], v119 offset0:36 offset1:32
	ds_read2_b32 v[138:139], v119 offset0:28 offset1:24
	ds_read2_b32 v[140:141], v119 offset0:20 offset1:16
	ds_read2_b32 v[142:143], v119 offset0:12 offset1:8
	ds_read2_b32 v[144:145], v119 offset0:4 offset1:0
	s_waitcnt lgkmcnt(14)
	v_fma_f32 v125, v160, v14, v123
	s_waitcnt lgkmcnt(13)
	v_mul_f32_e32 v124, v216, v2
	v_fmac_f32_e32 v124, v217, v3
	v_add_f32_dpp v127, v125, v125 quad_perm:[1,0,3,2] row_mask:0xf bank_mask:0xf
	s_waitcnt lgkmcnt(12)
	v_fmac_f32_e32 v124, v218, v4
	v_fmac_f32_e32 v124, v219, v5
	v_add_f32_dpp v125, v127, v127 quad_perm:[2,3,0,1] row_mask:0xf bank_mask:0xf
	v_fma_f32 v127, v48, v32, -v125
	v_cndmask_b32_e64 v15, v15, v127, s[88:89]
	s_waitcnt lgkmcnt(11)
	v_fmac_f32_e32 v124, v220, v6
	v_fmac_f32_e32 v124, v221, v7
	s_waitcnt lgkmcnt(10)
	v_fmac_f32_e32 v124, v222, v8
	v_fmac_f32_e32 v124, v223, v9
	s_waitcnt lgkmcnt(9)
	v_fmac_f32_e32 v124, v224, v10
	v_fmac_f32_e32 v124, v225, v11
	s_waitcnt lgkmcnt(8)
	v_fmac_f32_e32 v124, v226, v12
	v_fmac_f32_e32 v124, v227, v13
	s_waitcnt lgkmcnt(7)
	v_fmac_f32_e32 v124, v228, v14
	v_add_u32_e32 v120, 0x50ac, v117
	ds_read2_b32 v[148:149], v120 offset0:52 offset1:48
	ds_read2_b32 v[150:151], v120 offset0:44 offset1:40
	ds_read2_b32 v[152:153], v120 offset0:36 offset1:32
	ds_read2_b32 v[154:155], v120 offset0:28 offset1:24
	ds_read2_b32 v[156:157], v120 offset0:20 offset1:16
	ds_read2_b32 v[158:159], v120 offset0:12 offset1:8
	ds_read2_b32 v[160:161], v120 offset0:4 offset1:0
	v_cndmask_b32_e64 v126, 0, v229, s[100:101]
	v_fma_f32 v125, v126, v15, v124
	s_waitcnt lgkmcnt(13)
	v_mul_f32_e32 v122, v132, v2
	v_fmac_f32_e32 v122, v133, v3
	v_add_f32_dpp v127, v125, v125 quad_perm:[1,0,3,2] row_mask:0xf bank_mask:0xf
	s_waitcnt lgkmcnt(12)
	v_fmac_f32_e32 v122, v134, v4
	v_fmac_f32_e32 v122, v135, v5
	v_add_f32_dpp v125, v127, v127 quad_perm:[2,3,0,1] row_mask:0xf bank_mask:0xf
	v_fma_f32 v127, v48, v32, -v125
	v_cndmask_b32_e64 v15, v15, v127, s[90:91]
	s_waitcnt lgkmcnt(11)
	v_fmac_f32_e32 v122, v136, v6
	v_fmac_f32_e32 v122, v137, v7
	s_waitcnt lgkmcnt(10)
	v_fmac_f32_e32 v122, v138, v8
	v_fmac_f32_e32 v122, v139, v9
	s_waitcnt lgkmcnt(9)
	v_fmac_f32_e32 v122, v140, v10
	v_fmac_f32_e32 v122, v141, v11
	s_waitcnt lgkmcnt(8)
	v_fmac_f32_e32 v122, v142, v12
	v_fmac_f32_e32 v122, v143, v13
	s_waitcnt lgkmcnt(7)
	v_fmac_f32_e32 v122, v144, v14
	v_add_u32_e32 v121, 0x4f9c, v117
	ds_read2_b32 v[216:217], v121 offset0:52 offset1:48
	ds_read2_b32 v[218:219], v121 offset0:44 offset1:40
	ds_read2_b32 v[220:221], v121 offset0:36 offset1:32
	ds_read2_b32 v[222:223], v121 offset0:28 offset1:24
	ds_read2_b32 v[224:225], v121 offset0:20 offset1:16
	ds_read2_b32 v[226:227], v121 offset0:12 offset1:8
	ds_read2_b32 v[228:229], v121 offset0:4 offset1:0
	v_cndmask_b32_e64 v126, 0, v145, s[18:19]
	v_fma_f32 v125, v126, v15, v122
	s_waitcnt lgkmcnt(13)
	v_mul_f32_e32 v123, v148, v2
	v_fmac_f32_e32 v123, v149, v3
	v_add_f32_dpp v127, v125, v125 quad_perm:[1,0,3,2] row_mask:0xf bank_mask:0xf
	s_waitcnt lgkmcnt(12)
	v_fmac_f32_e32 v123, v150, v4
	v_fmac_f32_e32 v123, v151, v5
	v_add_f32_dpp v125, v127, v127 quad_perm:[2,3,0,1] row_mask:0xf bank_mask:0xf
	v_fma_f32 v127, v48, v32, -v125
	v_cndmask_b32_e64 v15, v15, v127, s[92:93]
	s_waitcnt lgkmcnt(11)
	v_fmac_f32_e32 v123, v152, v6
	v_fmac_f32_e32 v123, v153, v7
	s_waitcnt lgkmcnt(10)
	v_fmac_f32_e32 v123, v154, v8
	v_fmac_f32_e32 v123, v155, v9
	s_waitcnt lgkmcnt(9)
; template <int DIR>
; DI void dn_solve4(const float* M, const h16* Ki, const h16* Vi, const float* betal, const float* gcl, int half, int c, int pp, float (&x)[16]) {
;   const h16* src = half ? (Ki + c) : (Vi + c);
; #pragma unroll
;   for (int k = 0; k < 16; ++k) x[k] = 0.f;
; #pragma unroll
;   for (int il = 0; il < 64; ++il) {
;     const int ri = DIR ? 63 - il : il;
;     float part = 0.f;
; #pragma unroll
;     for (int k = 0; k < (il + 3) / 4; ++k) {
;       const int jl0 = 4 * k;
;       float mv = DIR ? M[ri * MLD + 63 - jl0 - pp] : M[ri * MLD + jl0 + pp];
;       if (jl0 + 3 >= il) mv = (jl0 + pp < il) ? mv : 0.f;
;       part += mv * x[k];
;     }
;     part += __shfl_xor(part, 1); part += __shfl_xor(part, 2);
;     const float e = half ? __expf(gcl[ri]) : 1.f;
;     const float xi = betal[ri] * (float)src[ri * LDH] * e - part;
;     if ((il & 3) == pp) x[il >> 2] = xi;
;   }
	v_fmac_f32_e32 v123, v156, v10
	v_fmac_f32_e32 v123, v157, v11
	s_waitcnt lgkmcnt(8)
	v_fmac_f32_e32 v123, v158, v12
	v_fmac_f32_e32 v123, v159, v13
	s_waitcnt lgkmcnt(7)
	v_fmac_f32_e32 v123, v160, v14
	v_add_u32_e32 v119, 0x4e7c, v117
	ds_read2_b32 v[132:133], v119 offset0:56 offset1:52
	ds_read2_b32 v[134:135], v119 offset0:48 offset1:44
	ds_read2_b32 v[136:137], v119 offset0:40 offset1:36
	ds_read2_b32 v[138:139], v119 offset0:32 offset1:28
	ds_read2_b32 v[140:141], v119 offset0:24 offset1:20
	ds_read2_b32 v[142:143], v119 offset0:16 offset1:12
	ds_read2_b32 v[144:145], v119 offset0:8 offset1:4
	ds_read_b32 v146, v119
	v_cndmask_b32_e64 v126, 0, v161, s[22:23]
	v_fma_f32 v125, v126, v15, v123
	s_waitcnt lgkmcnt(14)
	v_mul_f32_e32 v124, v216, v2
	v_fmac_f32_e32 v124, v217, v3
	v_add_f32_dpp v127, v125, v125 quad_perm:[1,0,3,2] row_mask:0xf bank_mask:0xf
	s_waitcnt lgkmcnt(13)
	v_fmac_f32_e32 v124, v218, v4
	v_fmac_f32_e32 v124, v219, v5
	v_add_f32_dpp v125, v127, v127 quad_perm:[2,3,0,1] row_mask:0xf bank_mask:0xf
	v_fma_f32 v127, v48, v32, -v125
	v_cndmask_b32_e64 v15, v15, v127, s[98:99]
	s_waitcnt lgkmcnt(12)
	v_fmac_f32_e32 v124, v220, v6
	v_fmac_f32_e32 v124, v221, v7
	s_waitcnt lgkmcnt(11)
	v_fmac_f32_e32 v124, v222, v8
	v_fmac_f32_e32 v124, v223, v9
	s_waitcnt lgkmcnt(10)
	v_fmac_f32_e32 v124, v224, v10
	v_fmac_f32_e32 v124, v225, v11
	s_waitcnt lgkmcnt(9)
	v_fmac_f32_e32 v124, v226, v12
	v_fmac_f32_e32 v124, v227, v13
	s_waitcnt lgkmcnt(8)
	v_fmac_f32_e32 v124, v228, v14
	v_add_u32_e32 v120, 0x4d6c, v117
	ds_read2_b32 v[148:149], v120 offset0:56 offset1:52
	ds_read2_b32 v[150:151], v120 offset0:48 offset1:44
	ds_read2_b32 v[152:153], v120 offset0:40 offset1:36
	ds_read2_b32 v[154:155], v120 offset0:32 offset1:28
	ds_read2_b32 v[156:157], v120 offset0:24 offset1:20
	ds_read2_b32 v[158:159], v120 offset0:16 offset1:12
	ds_read2_b32 v[160:161], v120 offset0:8 offset1:4
	ds_read_b32 v162, v120
	v_fma_f32 v125, v229, v15, v124
	s_waitcnt lgkmcnt(15)
	v_mul_f32_e32 v122, v132, v2
	v_fmac_f32_e32 v122, v133, v3
	v_add_f32_dpp v127, v125, v125 quad_perm:[1,0,3,2] row_mask:0xf bank_mask:0xf
	s_waitcnt lgkmcnt(14)
	v_fmac_f32_e32 v122, v134, v4
	v_fmac_f32_e32 v122, v135, v5
	v_add_f32_dpp v125, v127, v127 quad_perm:[2,3,0,1] row_mask:0xf bank_mask:0xf
	v_fma_f32 v127, v49, v33, -v125
	v_cndmask_b32_e64 v16, v16, v127, s[88:89]
	s_waitcnt lgkmcnt(13)
	v_fmac_f32_e32 v122, v136, v6
	v_fmac_f32_e32 v122, v137, v7
	s_waitcnt lgkmcnt(12)
	v_fmac_f32_e32 v122, v138, v8
	v_fmac_f32_e32 v122, v139, v9
	s_waitcnt lgkmcnt(11)
	v_fmac_f32_e32 v122, v140, v10
	v_fmac_f32_e32 v122, v141, v11
	s_waitcnt lgkmcnt(10)
	v_fmac_f32_e32 v122, v142, v12
	v_fmac_f32_e32 v122, v143, v13
	s_waitcnt lgkmcnt(9)
	v_fmac_f32_e32 v122, v144, v14
	v_fmac_f32_e32 v122, v145, v15
	v_add_u32_e32 v121, 0x4c5c, v117
	ds_read2_b32 v[216:217], v121 offset0:56 offset1:52
	ds_read2_b32 v[218:219], v121 offset0:48 offset1:44
	ds_read2_b32 v[220:221], v121 offset0:40 offset1:36
	ds_read2_b32 v[222:223], v121 offset0:32 offset1:28
	ds_read2_b32 v[224:225], v121 offset0:24 offset1:20
	ds_read2_b32 v[226:227], v121 offset0:16 offset1:12
	ds_read2_b32 v[228:229], v121 offset0:8 offset1:4
	ds_read_b32 v230, v121
	s_waitcnt lgkmcnt(15)
	v_cndmask_b32_e64 v126, 0, v146, s[100:101]
	v_fma_f32 v125, v126, v16, v122
	s_waitcnt lgkmcnt(15)
	v_mul_f32_e32 v123, v148, v2
	v_fmac_f32_e32 v123, v149, v3
	v_add_f32_dpp v127, v125, v125 quad_perm:[1,0,3,2] row_mask:0xf bank_mask:0xf
	s_waitcnt lgkmcnt(14)
	v_fmac_f32_e32 v123, v150, v4
	v_fmac_f32_e32 v123, v151, v5
	v_add_f32_dpp v125, v127, v127 quad_perm:[2,3,0,1] row_mask:0xf bank_mask:0xf
	v_fma_f32 v127, v49, v33, -v125
	v_cndmask_b32_e64 v16, v16, v127, s[90:91]
	s_waitcnt lgkmcnt(13)
	v_fmac_f32_e32 v123, v152, v6
	v_fmac_f32_e32 v123, v153, v7
	s_waitcnt lgkmcnt(12)
	v_fmac_f32_e32 v123, v154, v8
	v_fmac_f32_e32 v123, v155, v9
	s_waitcnt lgkmcnt(11)
	v_fmac_f32_e32 v123, v156, v10
	v_fmac_f32_e32 v123, v157, v11
	s_waitcnt lgkmcnt(10)
	v_fmac_f32_e32 v123, v158, v12
	v_fmac_f32_e32 v123, v159, v13
	s_waitcnt lgkmcnt(9)
	v_fmac_f32_e32 v123, v160, v14
	v_fmac_f32_e32 v123, v161, v15
	v_add_u32_e32 v119, 0x4b4c, v117
	ds_read2_b32 v[132:133], v119 offset0:56 offset1:52
	ds_read2_b32 v[134:135], v119 offset0:48 offset1:44
	ds_read2_b32 v[136:137], v119 offset0:40 offset1:36
	ds_read2_b32 v[138:139], v119 offset0:32 offset1:28
	ds_read2_b32 v[140:141], v119 offset0:24 offset1:20
	ds_read2_b32 v[142:143], v119 offset0:16 offset1:12
	ds_read2_b32 v[144:145], v119 offset0:8 offset1:4
	ds_read_b32 v146, v119
	s_waitcnt lgkmcnt(15)
	v_cndmask_b32_e64 v126, 0, v162, s[18:19]
	v_fma_f32 v125, v126, v16, v123
	s_waitcnt lgkmcnt(15)
	v_mul_f32_e32 v124, v216, v2
	v_fmac_f32_e32 v124, v217, v3
	v_add_f32_dpp v127, v125, v125 quad_perm:[1,0,3,2] row_mask:0xf bank_mask:0xf
	s_waitcnt lgkmcnt(14)
	v_fmac_f32_e32 v124, v218, v4
	v_fmac_f32_e32 v124, v219, v5
	v_add_f32_dpp v125, v127, v127 quad_perm:[2,3,0,1] row_mask:0xf bank_mask:0xf
	v_fma_f32 v127, v49, v33, -v125
	v_cndmask_b32_e64 v16, v16, v127, s[92:93]
	s_waitcnt lgkmcnt(13)
	v_fmac_f32_e32 v124, v220, v6
	v_fmac_f32_e32 v124, v221, v7
	s_waitcnt lgkmcnt(12)
	v_fmac_f32_e32 v124, v222, v8
	v_fmac_f32_e32 v124, v223, v9
	s_waitcnt lgkmcnt(11)
	v_fmac_f32_e32 v124, v224, v10
	v_fmac_f32_e32 v124, v225, v11
	s_waitcnt lgkmcnt(10)
	v_fmac_f32_e32 v124, v226, v12
	v_fmac_f32_e32 v124, v227, v13
	s_waitcnt lgkmcnt(9)
; template <int DIR>
; DI void dn_solve4(const float* M, const h16* Ki, const h16* Vi, const float* betal, const float* gcl, int half, int c, int pp, float (&x)[16]) {
;   const h16* src = half ? (Ki + c) : (Vi + c);
; #pragma unroll
;   for (int k = 0; k < 16; ++k) x[k] = 0.f;
; #pragma unroll
;   for (int il = 0; il < 64; ++il) {
;     const int ri = DIR ? 63 - il : il;
;     float part = 0.f;
; #pragma unroll
;     for (int k = 0; k < (il + 3) / 4; ++k) {
;       const int jl0 = 4 * k;
;       float mv = DIR ? M[ri * MLD + 63 - jl0 - pp] : M[ri * MLD + jl0 + pp];
;       if (jl0 + 3 >= il) mv = (jl0 + pp < il) ? mv : 0.f;
;       part += mv * x[k];
;     }
;     part += __shfl_xor(part, 1); part += __shfl_xor(part, 2);
;     const float e = half ? __expf(gcl[ri]) : 1.f;
;     const float xi = betal[ri] * (float)src[ri * LDH] * e - part;
;     if ((il & 3) == pp) x[il >> 2] = xi;
;   }
	v_fmac_f32_e32 v124, v228, v14
	v_fmac_f32_e32 v124, v229, v15
	v_add_u32_e32 v120, 0x4a2c, v117
	ds_read2_b32 v[148:149], v120 offset0:60 offset1:56
	ds_read2_b32 v[150:151], v120 offset0:52 offset1:48
	ds_read2_b32 v[152:153], v120 offset0:44 offset1:40
	ds_read2_b32 v[154:155], v120 offset0:36 offset1:32
	ds_read2_b32 v[156:157], v120 offset0:28 offset1:24
	ds_read2_b32 v[158:159], v120 offset0:20 offset1:16
	ds_read2_b32 v[160:161], v120 offset0:12 offset1:8
	ds_read2_b32 v[162:163], v120 offset0:4 offset1:0
	s_waitcnt lgkmcnt(15)
	v_cndmask_b32_e64 v126, 0, v230, s[22:23]
	v_fma_f32 v125, v126, v16, v124
	s_waitcnt lgkmcnt(15)
	v_mul_f32_e32 v122, v132, v2
	v_fmac_f32_e32 v122, v133, v3
	v_add_f32_dpp v127, v125, v125 quad_perm:[1,0,3,2] row_mask:0xf bank_mask:0xf
	s_waitcnt lgkmcnt(14)
	v_fmac_f32_e32 v122, v134, v4
	v_fmac_f32_e32 v122, v135, v5
	v_add_f32_dpp v125, v127, v127 quad_perm:[2,3,0,1] row_mask:0xf bank_mask:0xf
	v_fma_f32 v127, v49, v33, -v125
	v_cndmask_b32_e64 v16, v16, v127, s[98:99]
	s_waitcnt lgkmcnt(13)
	v_fmac_f32_e32 v122, v136, v6
	v_fmac_f32_e32 v122, v137, v7
	s_waitcnt lgkmcnt(12)
	v_fmac_f32_e32 v122, v138, v8
	v_fmac_f32_e32 v122, v139, v9
	s_waitcnt lgkmcnt(11)
	v_fmac_f32_e32 v122, v140, v10
	v_fmac_f32_e32 v122, v141, v11
	s_waitcnt lgkmcnt(10)
	v_fmac_f32_e32 v122, v142, v12
	v_fmac_f32_e32 v122, v143, v13
	s_waitcnt lgkmcnt(9)
	v_fmac_f32_e32 v122, v144, v14
	v_fmac_f32_e32 v122, v145, v15
	v_add_u32_e32 v121, 0x491c, v117
	ds_read2_b32 v[216:217], v121 offset0:60 offset1:56
	ds_read2_b32 v[218:219], v121 offset0:52 offset1:48
	ds_read2_b32 v[220:221], v121 offset0:44 offset1:40
	ds_read2_b32 v[222:223], v121 offset0:36 offset1:32
	ds_read2_b32 v[224:225], v121 offset0:28 offset1:24
	ds_read2_b32 v[226:227], v121 offset0:20 offset1:16
	ds_read2_b32 v[228:229], v121 offset0:12 offset1:8
	ds_read2_b32 v[230:231], v121 offset0:4 offset1:0
	s_waitcnt lgkmcnt(15)
	v_fma_f32 v125, v146, v16, v122
	s_waitcnt lgkmcnt(15)
	v_mul_f32_e32 v123, v148, v2
	v_fmac_f32_e32 v123, v149, v3
	v_add_f32_dpp v127, v125, v125 quad_perm:[1,0,3,2] row_mask:0xf bank_mask:0xf
	s_waitcnt lgkmcnt(14)
	v_fmac_f32_e32 v123, v150, v4
	v_fmac_f32_e32 v123, v151, v5
	v_add_f32_dpp v125, v127, v127 quad_perm:[2,3,0,1] row_mask:0xf bank_mask:0xf
	v_fma_f32 v127, v115, v34, -v125
	v_cndmask_b32_e64 v17, v17, v127, s[88:89]
	s_waitcnt lgkmcnt(13)
	v_fmac_f32_e32 v123, v152, v6
	v_fmac_f32_e32 v123, v153, v7
	s_waitcnt lgkmcnt(12)
	v_fmac_f32_e32 v123, v154, v8
	v_fmac_f32_e32 v123, v155, v9
	s_waitcnt lgkmcnt(11)
	v_fmac_f32_e32 v123, v156, v10
	v_fmac_f32_e32 v123, v157, v11
	s_waitcnt lgkmcnt(10)
	v_fmac_f32_e32 v123, v158, v12
	v_fmac_f32_e32 v123, v159, v13
	s_waitcnt lgkmcnt(9)
	v_fmac_f32_e32 v123, v160, v14
	v_fmac_f32_e32 v123, v161, v15
	s_waitcnt lgkmcnt(8)
	v_fmac_f32_e32 v123, v162, v16
	v_add_u32_e32 v119, 0x480c, v117
	ds_read2_b32 v[132:133], v119 offset0:60 offset1:56
	ds_read2_b32 v[134:135], v119 offset0:52 offset1:48
	ds_read2_b32 v[136:137], v119 offset0:44 offset1:40
	ds_read2_b32 v[138:139], v119 offset0:36 offset1:32
	ds_read2_b32 v[140:141], v119 offset0:28 offset1:24
	ds_read2_b32 v[142:143], v119 offset0:20 offset1:16
	ds_read2_b32 v[144:145], v119 offset0:12 offset1:8
	ds_read2_b32 v[146:147], v119 offset0:4 offset1:0
	v_cndmask_b32_e64 v126, 0, v163, s[100:101]
	v_fma_f32 v125, v126, v17, v123
	s_waitcnt lgkmcnt(15)
	v_mul_f32_e32 v124, v216, v2
	v_fmac_f32_e32 v124, v217, v3
	v_add_f32_dpp v127, v125, v125 quad_perm:[1,0,3,2] row_mask:0xf bank_mask:0xf
	s_waitcnt lgkmcnt(14)
	v_fmac_f32_e32 v124, v218, v4
	v_fmac_f32_e32 v124, v219, v5
	v_add_f32_dpp v125, v127, v127 quad_perm:[2,3,0,1] row_mask:0xf bank_mask:0xf
	v_fma_f32 v127, v115, v34, -v125
	v_cndmask_b32_e64 v17, v17, v127, s[90:91]
	s_waitcnt lgkmcnt(13)
	v_fmac_f32_e32 v124, v220, v6
	v_fmac_f32_e32 v124, v221, v7
	s_waitcnt lgkmcnt(12)
	v_fmac_f32_e32 v124, v222, v8
	v_fmac_f32_e32 v124, v223, v9
	s_waitcnt lgkmcnt(11)
	v_fmac_f32_e32 v124, v224, v10
	v_fmac_f32_e32 v124, v225, v11
	s_waitcnt lgkmcnt(10)
	v_fmac_f32_e32 v124, v226, v12
	v_fmac_f32_e32 v124, v227, v13
	s_waitcnt lgkmcnt(9)
	v_fmac_f32_e32 v124, v228, v14
	v_fmac_f32_e32 v124, v229, v15
	s_waitcnt lgkmcnt(8)
	v_fmac_f32_e32 v124, v230, v16
	v_cndmask_b32_e64 v126, 0, v231, s[18:19]
	v_fma_f32 v125, v126, v17, v124
	s_waitcnt lgkmcnt(7)
	v_mul_f32_e32 v122, v132, v2
	v_fmac_f32_e32 v122, v133, v3
	v_add_f32_dpp v127, v125, v125 quad_perm:[1,0,3,2] row_mask:0xf bank_mask:0xf
	s_waitcnt lgkmcnt(6)
	v_fmac_f32_e32 v122, v134, v4
	v_fmac_f32_e32 v122, v135, v5
	v_add_f32_dpp v125, v127, v127 quad_perm:[2,3,0,1] row_mask:0xf bank_mask:0xf
	v_fma_f32 v127, v115, v34, -v125
	v_cndmask_b32_e64 v17, v17, v127, s[92:93]
	s_waitcnt lgkmcnt(5)
	v_fmac_f32_e32 v122, v136, v6
	v_fmac_f32_e32 v122, v137, v7
	s_waitcnt lgkmcnt(4)
	v_fmac_f32_e32 v122, v138, v8
	v_fmac_f32_e32 v122, v139, v9
	s_waitcnt lgkmcnt(3)
	v_fmac_f32_e32 v122, v140, v10
	v_fmac_f32_e32 v122, v141, v11
	s_waitcnt lgkmcnt(2)
	v_fmac_f32_e32 v122, v142, v12
	v_fmac_f32_e32 v122, v143, v13
	s_waitcnt lgkmcnt(1)
	v_fmac_f32_e32 v122, v144, v14
	v_fmac_f32_e32 v122, v145, v15
	s_waitcnt lgkmcnt(0)
	v_fmac_f32_e32 v122, v146, v16
	v_cndmask_b32_e64 v126, 0, v147, s[22:23]
	v_fma_f32 v125, v126, v17, v122
	s_nop 1
	v_add_f32_dpp v127, v125, v125 quad_perm:[1,0,3,2] row_mask:0xf bank_mask:0xf
	s_nop 1
	v_add_f32_dpp v125, v127, v127 quad_perm:[2,3,0,1] row_mask:0xf bank_mask:0xf
	v_fma_f32 v127, v115, v34, -v125
	v_cndmask_b32_e64 v17, v17, v127, s[98:99]
	v_mov_b32_e32 v29, v93
	s_branch .LBB0_828
; template <int DIR>
; DI void dn_solve4(const float* M, const h16* Ki, const h16* Vi, const float* betal, const float* gcl, int half, int c, int pp, float (&x)[16]) {
;   const h16* src = half ? (Ki + c) : (Vi + c);
; #pragma unroll
;   for (int k = 0; k < 16; ++k) x[k] = 0.f;
; #pragma unroll
;   for (int il = 0; il < 64; ++il) {
;     const int ri = DIR ? 63 - il : il;
;     float part = 0.f;
; #pragma unroll
;     for (int k = 0; k < (il + 3) / 4; ++k) {
;       const int jl0 = 4 * k;
;       float mv = DIR ? M[ri * MLD + 63 - jl0 - pp] : M[ri * MLD + jl0 + pp];
;       if (jl0 + 3 >= il) mv = (jl0 + pp < il) ? mv : 0.f;
;       part += mv * x[k];
;     }
;     part += __shfl_xor(part, 1); part += __shfl_xor(part, 2);
;     const float e = half ? __expf(gcl[ri]) : 1.f;
;     const float xi = betal[ri] * (float)src[ri * LDH] * e - part;
.Lsolve_dir0:
	v_and_b32_e32 v116, 3, v182
	v_cmp_eq_u32_e64 s[88:89], 0, v116
	v_cmp_eq_u32_e64 s[90:91], 1, v116
	v_cmp_eq_u32_e64 s[92:93], 2, v116
	v_cmp_eq_u32_e64 s[98:99], 3, v116
	v_cmp_gt_u32_e64 s[100:101], 1, v116
	v_cmp_gt_u32_e64 s[18:19], 2, v116
	v_cmp_gt_u32_e64 s[22:23], 3, v116
	v_lshlrev_b32_e32 v125, 2, v116
	v_add_u32_e32 v117, v183, v125
	v_mul_u32_u24_e32 v126, 0x90, v116
	v_add_u32_e32 v118, v114, v126
	v_mov_b32_e32 v2, 0
	v_mov_b32_e32 v3, 0
	v_mov_b32_e32 v4, 0
	v_mov_b32_e32 v5, 0
	v_mov_b32_e32 v6, 0
	v_mov_b32_e32 v7, 0
	v_mov_b32_e32 v8, 0
	v_mov_b32_e32 v9, 0
	v_mov_b32_e32 v10, 0
	v_mov_b32_e32 v11, 0
	v_mov_b32_e32 v12, 0
	v_mov_b32_e32 v13, 0
	v_mov_b32_e32 v14, 0
	v_mov_b32_e32 v15, 0
	v_mov_b32_e32 v16, 0
	v_mov_b32_e32 v17, 0
	ds_read_b32 v18, v117 offset:35840
	ds_read_u16 v35, v118 offset:0
	ds_read_b32 v19, v117 offset:35856
	ds_read_u16 v36, v118 offset:576
	ds_read_b32 v20, v117 offset:35872
	ds_read_u16 v37, v118 offset:1152
	ds_read_b32 v21, v117 offset:35888
	ds_read_u16 v38, v118 offset:1728
	s_waitcnt lgkmcnt(6)
	v_cvt_f32_f16_e32 v35, v35
	s_waitcnt lgkmcnt(4)
	v_cvt_f32_f16_e32 v36, v36
	s_waitcnt lgkmcnt(2)
	v_cvt_f32_f16_e32 v37, v37
	s_waitcnt lgkmcnt(0)
	v_cvt_f32_f16_e32 v38, v38
	v_mul_f32_e32 v18, v18, v35
	v_mul_f32_e32 v19, v19, v36
	v_mul_f32_e32 v20, v20, v37
	v_mul_f32_e32 v21, v21, v38
	ds_read_b32 v22, v117 offset:35904
	ds_read_u16 v39, v118 offset:2304
	ds_read_b32 v23, v117 offset:35920
	ds_read_u16 v40, v118 offset:2880
	ds_read_b32 v24, v117 offset:35936
	ds_read_u16 v41, v118 offset:3456
	ds_read_b32 v25, v117 offset:35952
	ds_read_u16 v42, v118 offset:4032
	s_waitcnt lgkmcnt(6)
	v_cvt_f32_f16_e32 v39, v39
	s_waitcnt lgkmcnt(4)
	v_cvt_f32_f16_e32 v40, v40
	s_waitcnt lgkmcnt(2)
	v_cvt_f32_f16_e32 v41, v41
	s_waitcnt lgkmcnt(0)
	v_cvt_f32_f16_e32 v42, v42
	v_mul_f32_e32 v22, v22, v39
	v_mul_f32_e32 v23, v23, v40
	v_mul_f32_e32 v24, v24, v41
	v_mul_f32_e32 v25, v25, v42
	ds_read_b32 v26, v117 offset:35968
	ds_read_u16 v43, v118 offset:4608
	ds_read_b32 v27, v117 offset:35984
	ds_read_u16 v44, v118 offset:5184
	ds_read_b32 v28, v117 offset:36000
	ds_read_u16 v45, v118 offset:5760
	ds_read_b32 v30, v117 offset:36016
	ds_read_u16 v46, v118 offset:6336
	s_waitcnt lgkmcnt(6)
	v_cvt_f32_f16_e32 v43, v43
	s_waitcnt lgkmcnt(4)
	v_cvt_f32_f16_e32 v44, v44
	s_waitcnt lgkmcnt(2)
	v_cvt_f32_f16_e32 v45, v45
	s_waitcnt lgkmcnt(0)
	v_cvt_f32_f16_e32 v46, v46
	v_mul_f32_e32 v26, v26, v43
	v_mul_f32_e32 v27, v27, v44
	v_mul_f32_e32 v28, v28, v45
	v_mul_f32_e32 v30, v30, v46
	ds_read_b32 v31, v117 offset:36032
	ds_read_u16 v47, v118 offset:6912
	ds_read_b32 v32, v117 offset:36048
	ds_read_u16 v48, v118 offset:7488
	ds_read_b32 v33, v117 offset:36064
	ds_read_u16 v49, v118 offset:8064
	ds_read_b32 v34, v117 offset:36080
	ds_read_u16 v115, v118 offset:8640
	s_waitcnt lgkmcnt(6)
	v_cvt_f32_f16_e32 v47, v47
	s_waitcnt lgkmcnt(4)
	v_cvt_f32_f16_e32 v48, v48
	s_waitcnt lgkmcnt(2)
	v_cvt_f32_f16_e32 v49, v49
	s_waitcnt lgkmcnt(0)
	v_cvt_f32_f16_e32 v115, v115
	v_mul_f32_e32 v31, v31, v47
	v_mul_f32_e32 v32, v32, v48
	v_mul_f32_e32 v33, v33, v49
	v_mul_f32_e32 v34, v34, v115
	s_and_b64 vcc, exec, s[78:79]
	s_cbranch_vccnz .Lsolved0_noexp
	ds_read_b32 v35, v117 offset:36352
	ds_read_b32 v36, v117 offset:36368
	ds_read_b32 v37, v117 offset:36384
	ds_read_b32 v38, v117 offset:36400
	ds_read_b32 v39, v117 offset:36416
	ds_read_b32 v40, v117 offset:36432
	ds_read_b32 v41, v117 offset:36448
	ds_read_b32 v42, v117 offset:36464
	s_waitcnt lgkmcnt(7)
	v_mul_f32_e32 v35, 0x3fb8aa3b, v35
	s_waitcnt lgkmcnt(6)
	v_mul_f32_e32 v36, 0x3fb8aa3b, v36
	s_waitcnt lgkmcnt(5)
	v_mul_f32_e32 v37, 0x3fb8aa3b, v37
	s_waitcnt lgkmcnt(4)
	v_mul_f32_e32 v38, 0x3fb8aa3b, v38
	s_waitcnt lgkmcnt(3)
	v_mul_f32_e32 v39, 0x3fb8aa3b, v39
	s_waitcnt lgkmcnt(2)
	v_mul_f32_e32 v40, 0x3fb8aa3b, v40
	s_waitcnt lgkmcnt(1)
	v_mul_f32_e32 v41, 0x3fb8aa3b, v41
	s_waitcnt lgkmcnt(0)
	v_mul_f32_e32 v42, 0x3fb8aa3b, v42
	v_exp_f32_e32 v35, v35
	v_exp_f32_e32 v36, v36
	v_exp_f32_e32 v37, v37
	v_exp_f32_e32 v38, v38
	v_exp_f32_e32 v39, v39
	v_exp_f32_e32 v40, v40
	v_exp_f32_e32 v41, v41
	v_exp_f32_e32 v42, v42
	ds_read_b32 v43, v117 offset:36480
	ds_read_b32 v44, v117 offset:36496
	ds_read_b32 v45, v117 offset:36512
	ds_read_b32 v46, v117 offset:36528
	ds_read_b32 v47, v117 offset:36544
	ds_read_b32 v48, v117 offset:36560
	ds_read_b32 v49, v117 offset:36576
	ds_read_b32 v115, v117 offset:36592
	s_waitcnt lgkmcnt(7)
	v_mul_f32_e32 v43, 0x3fb8aa3b, v43
	s_waitcnt lgkmcnt(6)
	v_mul_f32_e32 v44, 0x3fb8aa3b, v44
	s_waitcnt lgkmcnt(5)
	v_mul_f32_e32 v45, 0x3fb8aa3b, v45
	s_waitcnt lgkmcnt(4)
	v_mul_f32_e32 v46, 0x3fb8aa3b, v46
	s_waitcnt lgkmcnt(3)
	v_mul_f32_e32 v47, 0x3fb8aa3b, v47
	s_waitcnt lgkmcnt(2)
	v_mul_f32_e32 v48, 0x3fb8aa3b, v48
	s_waitcnt lgkmcnt(1)
	v_mul_f32_e32 v49, 0x3fb8aa3b, v49
	s_waitcnt lgkmcnt(0)
	v_mul_f32_e32 v115, 0x3fb8aa3b, v115
	v_exp_f32_e32 v43, v43
	v_exp_f32_e32 v44, v44
	v_exp_f32_e32 v45, v45
	v_exp_f32_e32 v46, v46
	v_exp_f32_e32 v47, v47
	v_exp_f32_e32 v48, v48
	v_exp_f32_e32 v49, v49
	v_exp_f32_e32 v115, v115
	s_branch .Lsolved0_go

; template <int DIR>
; DI void dn_solve4(const float* M, const h16* Ki, const h16* Vi, const float* betal, const float* gcl, int half, int c, int pp, float (&x)[16]) {
;   const h16* src = half ? (Ki + c) : (Vi + c);
; #pragma unroll
;   for (int k = 0; k < 16; ++k) x[k] = 0.f;
; #pragma unroll
;   for (int il = 0; il < 64; ++il) {
;     const int ri = DIR ? 63 - il : il;
;     float part = 0.f;
; #pragma unroll
;     for (int k = 0; k < (il + 3) / 4; ++k) {
;       const int jl0 = 4 * k;
;       float mv = DIR ? M[ri * MLD + 63 - jl0 - pp] : M[ri * MLD + jl0 + pp];
;       if (jl0 + 3 >= il) mv = (jl0 + pp < il) ? mv : 0.f;
;       part += mv * x[k];
;     }
;     part += __shfl_xor(part, 1); part += __shfl_xor(part, 2);
;     const float e = half ? __expf(gcl[ri]) : 1.f;
;     const float xi = betal[ri] * (float)src[ri * LDH] * e - part;
;     if ((il & 3) == pp) x[il >> 2] = xi;
;   }
.Lsolved0_go:
	s_nop 0
	s_waitcnt lgkmcnt(0)
	v_add_u32_e32 v120, 0x4910, v117
	ds_read_b32 v148, v120
	v_add_u32_e32 v121, 0x4a20, v117
	ds_read_b32 v216, v121
	v_mul_f32_e32 v125, v35, v18
	v_cndmask_b32_e64 v2, v2, v125, s[88:89]
	v_add_u32_e32 v119, 0x4b30, v117
	ds_read_b32 v132, v119
	s_waitcnt lgkmcnt(2)
	v_cndmask_b32_e64 v126, 0, v148, s[100:101]
	v_mul_f32_e32 v125, v126, v2
	s_nop 1
	v_add_f32_dpp v127, v125, v125 quad_perm:[1,0,3,2] row_mask:0xf bank_mask:0xf
	s_nop 1
	v_add_f32_dpp v125, v127, v127 quad_perm:[2,3,0,1] row_mask:0xf bank_mask:0xf
	v_fma_f32 v127, v35, v18, -v125
	v_cndmask_b32_e64 v2, v2, v127, s[90:91]
	v_add_u32_e32 v120, 0x4c40, v117
	ds_read_b32 v148, v120
	s_waitcnt lgkmcnt(2)
	v_cndmask_b32_e64 v126, 0, v216, s[18:19]
	v_mul_f32_e32 v125, v126, v2
	s_nop 1
	v_add_f32_dpp v127, v125, v125 quad_perm:[1,0,3,2] row_mask:0xf bank_mask:0xf
	s_nop 1
	v_add_f32_dpp v125, v127, v127 quad_perm:[2,3,0,1] row_mask:0xf bank_mask:0xf
	v_fma_f32 v127, v35, v18, -v125
	v_cndmask_b32_e64 v2, v2, v127, s[92:93]
	v_add_u32_e32 v121, 0x4d50, v117
	ds_read2_b32 v[216:217], v121 offset0:0 offset1:4
	s_waitcnt lgkmcnt(2)
	v_cndmask_b32_e64 v126, 0, v132, s[22:23]
	v_mul_f32_e32 v125, v126, v2
	s_nop 1
	v_add_f32_dpp v127, v125, v125 quad_perm:[1,0,3,2] row_mask:0xf bank_mask:0xf
	s_nop 1
	v_add_f32_dpp v125, v127, v127 quad_perm:[2,3,0,1] row_mask:0xf bank_mask:0xf
	v_fma_f32 v127, v35, v18, -v125
	v_cndmask_b32_e64 v2, v2, v127, s[98:99]
	v_add_u32_e32 v119, 0x4e60, v117
	ds_read2_b32 v[132:133], v119 offset0:0 offset1:4
	s_waitcnt lgkmcnt(2)
	v_mul_f32_e32 v125, v148, v2
	s_waitcnt lgkmcnt(1)
	v_mul_f32_e32 v124, v216, v2
	s_nop 0
	v_add_f32_dpp v127, v125, v125 quad_perm:[1,0,3,2] row_mask:0xf bank_mask:0xf
	s_nop 1
	v_add_f32_dpp v125, v127, v127 quad_perm:[2,3,0,1] row_mask:0xf bank_mask:0xf
	v_fma_f32 v127, v36, v19, -v125
	v_cndmask_b32_e64 v3, v3, v127, s[88:89]
	v_add_u32_e32 v120, 0x4f70, v117
	ds_read2_b32 v[148:149], v120 offset0:0 offset1:4
	v_cndmask_b32_e64 v126, 0, v217, s[100:101]
	v_fma_f32 v125, v126, v3, v124
	s_waitcnt lgkmcnt(1)
	v_mul_f32_e32 v122, v132, v2
	s_nop 0
	v_add_f32_dpp v127, v125, v125 quad_perm:[1,0,3,2] row_mask:0xf bank_mask:0xf
	s_nop 1
	v_add_f32_dpp v125, v127, v127 quad_perm:[2,3,0,1] row_mask:0xf bank_mask:0xf
	v_fma_f32 v127, v36, v19, -v125
	v_cndmask_b32_e64 v3, v3, v127, s[90:91]
	v_add_u32_e32 v121, 0x5080, v117
	ds_read2_b32 v[216:217], v121 offset0:0 offset1:4
	v_cndmask_b32_e64 v126, 0, v133, s[18:19]
	v_fma_f32 v125, v126, v3, v122
	s_waitcnt lgkmcnt(1)
	v_mul_f32_e32 v123, v148, v2
	s_nop 0
	v_add_f32_dpp v127, v125, v125 quad_perm:[1,0,3,2] row_mask:0xf bank_mask:0xf
	s_nop 1
	v_add_f32_dpp v125, v127, v127 quad_perm:[2,3,0,1] row_mask:0xf bank_mask:0xf
	v_fma_f32 v127, v36, v19, -v125
	v_cndmask_b32_e64 v3, v3, v127, s[92:93]
	v_add_u32_e32 v119, 0x5190, v117
	ds_read2_b32 v[132:133], v119 offset0:0 offset1:4
	ds_read_b32 v134, v119 offset:32
	v_cndmask_b32_e64 v126, 0, v149, s[22:23]
	v_fma_f32 v125, v126, v3, v123
	s_waitcnt lgkmcnt(2)
	v_mul_f32_e32 v124, v216, v2
	s_nop 0
	v_add_f32_dpp v127, v125, v125 quad_perm:[1,0,3,2] row_mask:0xf bank_mask:0xf
	s_nop 1
	v_add_f32_dpp v125, v127, v127 quad_perm:[2,3,0,1] row_mask:0xf bank_mask:0xf
	v_fma_f32 v127, v36, v19, -v125
	v_cndmask_b32_e64 v3, v3, v127, s[98:99]
	v_add_u32_e32 v120, 0x52a0, v117
	ds_read2_b32 v[148:149], v120 offset0:0 offset1:4
	ds_read_b32 v150, v120 offset:32
	v_fma_f32 v125, v217, v3, v124
	s_waitcnt lgkmcnt(3)
	v_mul_f32_e32 v122, v132, v2
	v_fmac_f32_e32 v122, v133, v3
	v_add_f32_dpp v127, v125, v125 quad_perm:[1,0,3,2] row_mask:0xf bank_mask:0xf
	s_nop 1
	v_add_f32_dpp v125, v127, v127 quad_perm:[2,3,0,1] row_mask:0xf bank_mask:0xf
	v_fma_f32 v127, v37, v20, -v125
	v_cndmask_b32_e64 v4, v4, v127, s[88:89]
	v_add_u32_e32 v121, 0x53b0, v117
	ds_read2_b32 v[216:217], v121 offset0:0 offset1:4
	ds_read_b32 v218, v121 offset:32
	s_waitcnt lgkmcnt(4)
	v_cndmask_b32_e64 v126, 0, v134, s[100:101]
	v_fma_f32 v125, v126, v4, v122
	s_waitcnt lgkmcnt(3)
	v_mul_f32_e32 v123, v148, v2
	v_fmac_f32_e32 v123, v149, v3
	v_add_f32_dpp v127, v125, v125 quad_perm:[1,0,3,2] row_mask:0xf bank_mask:0xf
	s_nop 1
	v_add_f32_dpp v125, v127, v127 quad_perm:[2,3,0,1] row_mask:0xf bank_mask:0xf
	v_fma_f32 v127, v37, v20, -v125
	v_cndmask_b32_e64 v4, v4, v127, s[90:91]
	v_add_u32_e32 v119, 0x54c0, v117
	ds_read2_b32 v[132:133], v119 offset0:0 offset1:4
	ds_read_b32 v134, v119 offset:32
	s_waitcnt lgkmcnt(4)
	v_cndmask_b32_e64 v126, 0, v150, s[18:19]
	v_fma_f32 v125, v126, v4, v123
	s_waitcnt lgkmcnt(3)
	v_mul_f32_e32 v124, v216, v2
	v_fmac_f32_e32 v124, v217, v3
	v_add_f32_dpp v127, v125, v125 quad_perm:[1,0,3,2] row_mask:0xf bank_mask:0xf
	s_nop 1
	v_add_f32_dpp v125, v127, v127 quad_perm:[2,3,0,1] row_mask:0xf bank_mask:0xf
	v_fma_f32 v127, v37, v20, -v125
	v_cndmask_b32_e64 v4, v4, v127, s[92:93]
	v_add_u32_e32 v120, 0x55d0, v117
	ds_read2_b32 v[148:149], v120 offset0:0 offset1:4
	ds_read2_b32 v[150:151], v120 offset0:8 offset1:12
	s_waitcnt lgkmcnt(4)
	v_cndmask_b32_e64 v126, 0, v218, s[22:23]
	v_fma_f32 v125, v126, v4, v124
	s_waitcnt lgkmcnt(3)
	v_mul_f32_e32 v122, v132, v2
	v_fmac_f32_e32 v122, v133, v3
	v_add_f32_dpp v127, v125, v125 quad_perm:[1,0,3,2] row_mask:0xf bank_mask:0xf
	s_nop 1
	v_add_f32_dpp v125, v127, v127 quad_perm:[2,3,0,1] row_mask:0xf bank_mask:0xf
	v_fma_f32 v127, v37, v20, -v125
	v_cndmask_b32_e64 v4, v4, v127, s[98:99]
	v_add_u32_e32 v121, 0x56e0, v117
	ds_read2_b32 v[216:217], v121 offset0:0 offset1:4
	ds_read2_b32 v[218:219], v121 offset0:8 offset1:12
	s_waitcnt lgkmcnt(4)
; template <int DIR>
; DI void dn_solve4(const float* M, const h16* Ki, const h16* Vi, const float* betal, const float* gcl, int half, int c, int pp, float (&x)[16]) {
;   const h16* src = half ? (Ki + c) : (Vi + c);
; #pragma unroll
;   for (int k = 0; k < 16; ++k) x[k] = 0.f;
; #pragma unroll
;   for (int il = 0; il < 64; ++il) {
;     const int ri = DIR ? 63 - il : il;
;     float part = 0.f;
; #pragma unroll
;     for (int k = 0; k < (il + 3) / 4; ++k) {
;       const int jl0 = 4 * k;
;       float mv = DIR ? M[ri * MLD + 63 - jl0 - pp] : M[ri * MLD + jl0 + pp];
;       if (jl0 + 3 >= il) mv = (jl0 + pp < il) ? mv : 0.f;
;       part += mv * x[k];
;     }
;     part += __shfl_xor(part, 1); part += __shfl_xor(part, 2);
;     const float e = half ? __expf(gcl[ri]) : 1.f;
;     const float xi = betal[ri] * (float)src[ri * LDH] * e - part;
;     if ((il & 3) == pp) x[il >> 2] = xi;
;   }
	v_fma_f32 v125, v134, v4, v122
	s_waitcnt lgkmcnt(3)
	v_mul_f32_e32 v123, v148, v2
	v_fmac_f32_e32 v123, v149, v3
	v_add_f32_dpp v127, v125, v125 quad_perm:[1,0,3,2] row_mask:0xf bank_mask:0xf
	s_waitcnt lgkmcnt(2)
	v_fmac_f32_e32 v123, v150, v4
	s_nop 0
	v_add_f32_dpp v125, v127, v127 quad_perm:[2,3,0,1] row_mask:0xf bank_mask:0xf
	v_fma_f32 v127, v38, v21, -v125
	v_cndmask_b32_e64 v5, v5, v127, s[88:89]
	v_add_u32_e32 v119, 0x57f0, v117
	ds_read2_b32 v[132:133], v119 offset0:0 offset1:4
	ds_read2_b32 v[134:135], v119 offset0:8 offset1:12
	v_cndmask_b32_e64 v126, 0, v151, s[100:101]
	v_fma_f32 v125, v126, v5, v123
	s_waitcnt lgkmcnt(3)
	v_mul_f32_e32 v124, v216, v2
	v_fmac_f32_e32 v124, v217, v3
	v_add_f32_dpp v127, v125, v125 quad_perm:[1,0,3,2] row_mask:0xf bank_mask:0xf
	s_waitcnt lgkmcnt(2)
	v_fmac_f32_e32 v124, v218, v4
	s_nop 0
	v_add_f32_dpp v125, v127, v127 quad_perm:[2,3,0,1] row_mask:0xf bank_mask:0xf
	v_fma_f32 v127, v38, v21, -v125
	v_cndmask_b32_e64 v5, v5, v127, s[90:91]
	v_add_u32_e32 v120, 0x5900, v117
	ds_read2_b32 v[148:149], v120 offset0:0 offset1:4
	ds_read2_b32 v[150:151], v120 offset0:8 offset1:12
	v_cndmask_b32_e64 v126, 0, v219, s[18:19]
	v_fma_f32 v125, v126, v5, v124
	s_waitcnt lgkmcnt(3)
	v_mul_f32_e32 v122, v132, v2
	v_fmac_f32_e32 v122, v133, v3
	v_add_f32_dpp v127, v125, v125 quad_perm:[1,0,3,2] row_mask:0xf bank_mask:0xf
	s_waitcnt lgkmcnt(2)
	v_fmac_f32_e32 v122, v134, v4
	s_nop 0
	v_add_f32_dpp v125, v127, v127 quad_perm:[2,3,0,1] row_mask:0xf bank_mask:0xf
	v_fma_f32 v127, v38, v21, -v125
	v_cndmask_b32_e64 v5, v5, v127, s[92:93]
	v_add_u32_e32 v121, 0x5a10, v117
	ds_read2_b32 v[216:217], v121 offset0:0 offset1:4
	ds_read2_b32 v[218:219], v121 offset0:8 offset1:12
	ds_read_b32 v220, v121 offset:64
	v_cndmask_b32_e64 v126, 0, v135, s[22:23]
	v_fma_f32 v125, v126, v5, v122
	s_waitcnt lgkmcnt(4)
	v_mul_f32_e32 v123, v148, v2
	v_fmac_f32_e32 v123, v149, v3
	v_add_f32_dpp v127, v125, v125 quad_perm:[1,0,3,2] row_mask:0xf bank_mask:0xf
	s_waitcnt lgkmcnt(3)
	v_fmac_f32_e32 v123, v150, v4
	s_nop 0
	v_add_f32_dpp v125, v127, v127 quad_perm:[2,3,0,1] row_mask:0xf bank_mask:0xf
	v_fma_f32 v127, v38, v21, -v125
	v_cndmask_b32_e64 v5, v5, v127, s[98:99]
	v_add_u32_e32 v119, 0x5b20, v117
	ds_read2_b32 v[132:133], v119 offset0:0 offset1:4
	ds_read2_b32 v[134:135], v119 offset0:8 offset1:12
	ds_read_b32 v136, v119 offset:64
	v_fma_f32 v125, v151, v5, v123
	s_waitcnt lgkmcnt(5)
	v_mul_f32_e32 v124, v216, v2
	v_fmac_f32_e32 v124, v217, v3
	v_add_f32_dpp v127, v125, v125 quad_perm:[1,0,3,2] row_mask:0xf bank_mask:0xf
	s_waitcnt lgkmcnt(4)
	v_fmac_f32_e32 v124, v218, v4
	v_fmac_f32_e32 v124, v219, v5
	v_add_f32_dpp v125, v127, v127 quad_perm:[2,3,0,1] row_mask:0xf bank_mask:0xf
	v_fma_f32 v127, v39, v22, -v125
	v_cndmask_b32_e64 v6, v6, v127, s[88:89]
	v_add_u32_e32 v120, 0x5c30, v117
	ds_read2_b32 v[148:149], v120 offset0:0 offset1:4
	ds_read2_b32 v[150:151], v120 offset0:8 offset1:12
	ds_read_b32 v152, v120 offset:64
	s_waitcnt lgkmcnt(6)
	v_cndmask_b32_e64 v126, 0, v220, s[100:101]
	v_fma_f32 v125, v126, v6, v124
	s_waitcnt lgkmcnt(5)
	v_mul_f32_e32 v122, v132, v2
	v_fmac_f32_e32 v122, v133, v3
	v_add_f32_dpp v127, v125, v125 quad_perm:[1,0,3,2] row_mask:0xf bank_mask:0xf
	s_waitcnt lgkmcnt(4)
	v_fmac_f32_e32 v122, v134, v4
	v_fmac_f32_e32 v122, v135, v5
	v_add_f32_dpp v125, v127, v127 quad_perm:[2,3,0,1] row_mask:0xf bank_mask:0xf
	v_fma_f32 v127, v39, v22, -v125
	v_cndmask_b32_e64 v6, v6, v127, s[90:91]
	v_add_u32_e32 v121, 0x5d40, v117
	ds_read2_b32 v[216:217], v121 offset0:0 offset1:4
	ds_read2_b32 v[218:219], v121 offset0:8 offset1:12
	ds_read_b32 v220, v121 offset:64
	s_waitcnt lgkmcnt(6)
	v_cndmask_b32_e64 v126, 0, v136, s[18:19]
	v_fma_f32 v125, v126, v6, v122
	s_waitcnt lgkmcnt(5)
	v_mul_f32_e32 v123, v148, v2
	v_fmac_f32_e32 v123, v149, v3
	v_add_f32_dpp v127, v125, v125 quad_perm:[1,0,3,2] row_mask:0xf bank_mask:0xf
	s_waitcnt lgkmcnt(4)
	v_fmac_f32_e32 v123, v150, v4
	v_fmac_f32_e32 v123, v151, v5
	v_add_f32_dpp v125, v127, v127 quad_perm:[2,3,0,1] row_mask:0xf bank_mask:0xf
	v_fma_f32 v127, v39, v22, -v125
	v_cndmask_b32_e64 v6, v6, v127, s[92:93]
	v_add_u32_e32 v119, 0x5e50, v117
	ds_read2_b32 v[132:133], v119 offset0:0 offset1:4
	ds_read2_b32 v[134:135], v119 offset0:8 offset1:12
	ds_read2_b32 v[136:137], v119 offset0:16 offset1:20
	s_waitcnt lgkmcnt(6)
	v_cndmask_b32_e64 v126, 0, v152, s[22:23]
	v_fma_f32 v125, v126, v6, v123
	s_waitcnt lgkmcnt(5)
	v_mul_f32_e32 v124, v216, v2
	v_fmac_f32_e32 v124, v217, v3
	v_add_f32_dpp v127, v125, v125 quad_perm:[1,0,3,2] row_mask:0xf bank_mask:0xf
	s_waitcnt lgkmcnt(4)
	v_fmac_f32_e32 v124, v218, v4
	v_fmac_f32_e32 v124, v219, v5
	v_add_f32_dpp v125, v127, v127 quad_perm:[2,3,0,1] row_mask:0xf bank_mask:0xf
	v_fma_f32 v127, v39, v22, -v125
	v_cndmask_b32_e64 v6, v6, v127, s[98:99]
	v_add_u32_e32 v120, 0x5f60, v117
	ds_read2_b32 v[148:149], v120 offset0:0 offset1:4
	ds_read2_b32 v[150:151], v120 offset0:8 offset1:12
	ds_read2_b32 v[152:153], v120 offset0:16 offset1:20
	s_waitcnt lgkmcnt(6)
	v_fma_f32 v125, v220, v6, v124
	s_waitcnt lgkmcnt(5)
	v_mul_f32_e32 v122, v132, v2
	v_fmac_f32_e32 v122, v133, v3
	v_add_f32_dpp v127, v125, v125 quad_perm:[1,0,3,2] row_mask:0xf bank_mask:0xf
	s_waitcnt lgkmcnt(4)
	v_fmac_f32_e32 v122, v134, v4
	v_fmac_f32_e32 v122, v135, v5
	v_add_f32_dpp v125, v127, v127 quad_perm:[2,3,0,1] row_mask:0xf bank_mask:0xf
	v_fma_f32 v127, v40, v23, -v125
	v_cndmask_b32_e64 v7, v7, v127, s[88:89]
	s_waitcnt lgkmcnt(3)
; template <int DIR>
; DI void dn_solve4(const float* M, const h16* Ki, const h16* Vi, const float* betal, const float* gcl, int half, int c, int pp, float (&x)[16]) {
;   const h16* src = half ? (Ki + c) : (Vi + c);
; #pragma unroll
;   for (int k = 0; k < 16; ++k) x[k] = 0.f;
; #pragma unroll
;   for (int il = 0; il < 64; ++il) {
;     const int ri = DIR ? 63 - il : il;
;     float part = 0.f;
; #pragma unroll
;     for (int k = 0; k < (il + 3) / 4; ++k) {
;       const int jl0 = 4 * k;
;       float mv = DIR ? M[ri * MLD + 63 - jl0 - pp] : M[ri * MLD + jl0 + pp];
;       if (jl0 + 3 >= il) mv = (jl0 + pp < il) ? mv : 0.f;
;       part += mv * x[k];
;     }
;     part += __shfl_xor(part, 1); part += __shfl_xor(part, 2);
;     const float e = half ? __expf(gcl[ri]) : 1.f;
;     const float xi = betal[ri] * (float)src[ri * LDH] * e - part;
;     if ((il & 3) == pp) x[il >> 2] = xi;
;   }
	v_fmac_f32_e32 v122, v136, v6
	v_add_u32_e32 v121, 0x6070, v117
	ds_read2_b32 v[216:217], v121 offset0:0 offset1:4
	ds_read2_b32 v[218:219], v121 offset0:8 offset1:12
	ds_read2_b32 v[220:221], v121 offset0:16 offset1:20
	v_cndmask_b32_e64 v126, 0, v137, s[100:101]
	v_fma_f32 v125, v126, v7, v122
	s_waitcnt lgkmcnt(5)
	v_mul_f32_e32 v123, v148, v2
	v_fmac_f32_e32 v123, v149, v3
	v_add_f32_dpp v127, v125, v125 quad_perm:[1,0,3,2] row_mask:0xf bank_mask:0xf
	s_waitcnt lgkmcnt(4)
	v_fmac_f32_e32 v123, v150, v4
	v_fmac_f32_e32 v123, v151, v5
	v_add_f32_dpp v125, v127, v127 quad_perm:[2,3,0,1] row_mask:0xf bank_mask:0xf
	v_fma_f32 v127, v40, v23, -v125
	v_cndmask_b32_e64 v7, v7, v127, s[90:91]
	s_waitcnt lgkmcnt(3)
	v_fmac_f32_e32 v123, v152, v6
	v_add_u32_e32 v119, 0x6180, v117
	ds_read2_b32 v[132:133], v119 offset0:0 offset1:4
	ds_read2_b32 v[134:135], v119 offset0:8 offset1:12
	ds_read2_b32 v[136:137], v119 offset0:16 offset1:20
	v_cndmask_b32_e64 v126, 0, v153, s[18:19]
	v_fma_f32 v125, v126, v7, v123
	s_waitcnt lgkmcnt(5)
	v_mul_f32_e32 v124, v216, v2
	v_fmac_f32_e32 v124, v217, v3
	v_add_f32_dpp v127, v125, v125 quad_perm:[1,0,3,2] row_mask:0xf bank_mask:0xf
	s_waitcnt lgkmcnt(4)
	v_fmac_f32_e32 v124, v218, v4
	v_fmac_f32_e32 v124, v219, v5
	v_add_f32_dpp v125, v127, v127 quad_perm:[2,3,0,1] row_mask:0xf bank_mask:0xf
	v_fma_f32 v127, v40, v23, -v125
	v_cndmask_b32_e64 v7, v7, v127, s[92:93]
	s_waitcnt lgkmcnt(3)
	v_fmac_f32_e32 v124, v220, v6
	v_add_u32_e32 v120, 0x6290, v117
	ds_read2_b32 v[148:149], v120 offset0:0 offset1:4
	ds_read2_b32 v[150:151], v120 offset0:8 offset1:12
	ds_read2_b32 v[152:153], v120 offset0:16 offset1:20
	ds_read_b32 v154, v120 offset:96
	v_cndmask_b32_e64 v126, 0, v221, s[22:23]
	v_fma_f32 v125, v126, v7, v124
	s_waitcnt lgkmcnt(6)
	v_mul_f32_e32 v122, v132, v2
	v_fmac_f32_e32 v122, v133, v3
	v_add_f32_dpp v127, v125, v125 quad_perm:[1,0,3,2] row_mask:0xf bank_mask:0xf
	s_waitcnt lgkmcnt(5)
	v_fmac_f32_e32 v122, v134, v4
	v_fmac_f32_e32 v122, v135, v5
	v_add_f32_dpp v125, v127, v127 quad_perm:[2,3,0,1] row_mask:0xf bank_mask:0xf
	v_fma_f32 v127, v40, v23, -v125
	v_cndmask_b32_e64 v7, v7, v127, s[98:99]
	s_waitcnt lgkmcnt(4)
	v_fmac_f32_e32 v122, v136, v6
	v_add_u32_e32 v121, 0x63a0, v117
	ds_read2_b32 v[216:217], v121 offset0:0 offset1:4
	ds_read2_b32 v[218:219], v121 offset0:8 offset1:12
	ds_read2_b32 v[220:221], v121 offset0:16 offset1:20
	ds_read_b32 v222, v121 offset:96
	v_fma_f32 v125, v137, v7, v122
	s_waitcnt lgkmcnt(7)
	v_mul_f32_e32 v123, v148, v2
	v_fmac_f32_e32 v123, v149, v3
	v_add_f32_dpp v127, v125, v125 quad_perm:[1,0,3,2] row_mask:0xf bank_mask:0xf
	s_waitcnt lgkmcnt(6)
	v_fmac_f32_e32 v123, v150, v4
	v_fmac_f32_e32 v123, v151, v5
	v_add_f32_dpp v125, v127, v127 quad_perm:[2,3,0,1] row_mask:0xf bank_mask:0xf
	v_fma_f32 v127, v41, v24, -v125
	v_cndmask_b32_e64 v8, v8, v127, s[88:89]
	s_waitcnt lgkmcnt(5)
	v_fmac_f32_e32 v123, v152, v6
	v_fmac_f32_e32 v123, v153, v7
	v_add_u32_e32 v119, 0x64b0, v117
	ds_read2_b32 v[132:133], v119 offset0:0 offset1:4
	ds_read2_b32 v[134:135], v119 offset0:8 offset1:12
	ds_read2_b32 v[136:137], v119 offset0:16 offset1:20
	ds_read_b32 v138, v119 offset:96
	s_waitcnt lgkmcnt(8)
	v_cndmask_b32_e64 v126, 0, v154, s[100:101]
	v_fma_f32 v125, v126, v8, v123
	s_waitcnt lgkmcnt(7)
	v_mul_f32_e32 v124, v216, v2
	v_fmac_f32_e32 v124, v217, v3
	v_add_f32_dpp v127, v125, v125 quad_perm:[1,0,3,2] row_mask:0xf bank_mask:0xf
	s_waitcnt lgkmcnt(6)
	v_fmac_f32_e32 v124, v218, v4
	v_fmac_f32_e32 v124, v219, v5
	v_add_f32_dpp v125, v127, v127 quad_perm:[2,3,0,1] row_mask:0xf bank_mask:0xf
	v_fma_f32 v127, v41, v24, -v125
	v_cndmask_b32_e64 v8, v8, v127, s[90:91]
	s_waitcnt lgkmcnt(5)
	v_fmac_f32_e32 v124, v220, v6
	v_fmac_f32_e32 v124, v221, v7
	v_add_u32_e32 v120, 0x65c0, v117
	ds_read2_b32 v[148:149], v120 offset0:0 offset1:4
	ds_read2_b32 v[150:151], v120 offset0:8 offset1:12
	ds_read2_b32 v[152:153], v120 offset0:16 offset1:20
	ds_read_b32 v154, v120 offset:96
	s_waitcnt lgkmcnt(8)
	v_cndmask_b32_e64 v126, 0, v222, s[18:19]
	v_fma_f32 v125, v126, v8, v124
	s_waitcnt lgkmcnt(7)
	v_mul_f32_e32 v122, v132, v2
	v_fmac_f32_e32 v122, v133, v3
	v_add_f32_dpp v127, v125, v125 quad_perm:[1,0,3,2] row_mask:0xf bank_mask:0xf
	s_waitcnt lgkmcnt(6)
	v_fmac_f32_e32 v122, v134, v4
	v_fmac_f32_e32 v122, v135, v5
	v_add_f32_dpp v125, v127, v127 quad_perm:[2,3,0,1] row_mask:0xf bank_mask:0xf
	v_fma_f32 v127, v41, v24, -v125
	v_cndmask_b32_e64 v8, v8, v127, s[92:93]
	s_waitcnt lgkmcnt(5)
	v_fmac_f32_e32 v122, v136, v6
	v_fmac_f32_e32 v122, v137, v7
	v_add_u32_e32 v121, 0x66d0, v117
	ds_read2_b32 v[216:217], v121 offset0:0 offset1:4
	ds_read2_b32 v[218:219], v121 offset0:8 offset1:12
	ds_read2_b32 v[220:221], v121 offset0:16 offset1:20
	ds_read2_b32 v[222:223], v121 offset0:24 offset1:28
	s_waitcnt lgkmcnt(8)
	v_cndmask_b32_e64 v126, 0, v138, s[22:23]
	v_fma_f32 v125, v126, v8, v122
	s_waitcnt lgkmcnt(7)
	v_mul_f32_e32 v123, v148, v2
	v_fmac_f32_e32 v123, v149, v3
	v_add_f32_dpp v127, v125, v125 quad_perm:[1,0,3,2] row_mask:0xf bank_mask:0xf
	s_waitcnt lgkmcnt(6)
	v_fmac_f32_e32 v123, v150, v4
	v_fmac_f32_e32 v123, v151, v5
	v_add_f32_dpp v125, v127, v127 quad_perm:[2,3,0,1] row_mask:0xf bank_mask:0xf
	v_fma_f32 v127, v41, v24, -v125
	v_cndmask_b32_e64 v8, v8, v127, s[98:99]
	s_waitcnt lgkmcnt(5)
	v_fmac_f32_e32 v123, v152, v6
	v_fmac_f32_e32 v123, v153, v7
	v_add_u32_e32 v119, 0x67e0, v117
	ds_read2_b32 v[132:133], v119 offset0:0 offset1:4
	ds_read2_b32 v[134:135], v119 offset0:8 offset1:12
	ds_read2_b32 v[136:137], v119 offset0:16 offset1:20
	ds_read2_b32 v[138:139], v119 offset0:24 offset1:28
	s_waitcnt lgkmcnt(8)
; template <int DIR>
; DI void dn_solve4(const float* M, const h16* Ki, const h16* Vi, const float* betal, const float* gcl, int half, int c, int pp, float (&x)[16]) {
;   const h16* src = half ? (Ki + c) : (Vi + c);
; #pragma unroll
;   for (int k = 0; k < 16; ++k) x[k] = 0.f;
; #pragma unroll
;   for (int il = 0; il < 64; ++il) {
;     const int ri = DIR ? 63 - il : il;
;     float part = 0.f;
; #pragma unroll
;     for (int k = 0; k < (il + 3) / 4; ++k) {
;       const int jl0 = 4 * k;
;       float mv = DIR ? M[ri * MLD + 63 - jl0 - pp] : M[ri * MLD + jl0 + pp];
;       if (jl0 + 3 >= il) mv = (jl0 + pp < il) ? mv : 0.f;
;       part += mv * x[k];
;     }
;     part += __shfl_xor(part, 1); part += __shfl_xor(part, 2);
;     const float e = half ? __expf(gcl[ri]) : 1.f;
;     const float xi = betal[ri] * (float)src[ri * LDH] * e - part;
;     if ((il & 3) == pp) x[il >> 2] = xi;
;   }
	v_fma_f32 v125, v154, v8, v123
	s_waitcnt lgkmcnt(7)
	v_mul_f32_e32 v124, v216, v2
	v_fmac_f32_e32 v124, v217, v3
	v_add_f32_dpp v127, v125, v125 quad_perm:[1,0,3,2] row_mask:0xf bank_mask:0xf
	s_waitcnt lgkmcnt(6)
	v_fmac_f32_e32 v124, v218, v4
	v_fmac_f32_e32 v124, v219, v5
	v_add_f32_dpp v125, v127, v127 quad_perm:[2,3,0,1] row_mask:0xf bank_mask:0xf
	v_fma_f32 v127, v42, v25, -v125
	v_cndmask_b32_e64 v9, v9, v127, s[88:89]
	s_waitcnt lgkmcnt(5)
	v_fmac_f32_e32 v124, v220, v6
	v_fmac_f32_e32 v124, v221, v7
	s_waitcnt lgkmcnt(4)
	v_fmac_f32_e32 v124, v222, v8
	v_add_u32_e32 v120, 0x68f0, v117
	ds_read2_b32 v[148:149], v120 offset0:0 offset1:4
	ds_read2_b32 v[150:151], v120 offset0:8 offset1:12
	ds_read2_b32 v[152:153], v120 offset0:16 offset1:20
	ds_read2_b32 v[154:155], v120 offset0:24 offset1:28
	v_cndmask_b32_e64 v126, 0, v223, s[100:101]
	v_fma_f32 v125, v126, v9, v124
	s_waitcnt lgkmcnt(7)
	v_mul_f32_e32 v122, v132, v2
	v_fmac_f32_e32 v122, v133, v3
	v_add_f32_dpp v127, v125, v125 quad_perm:[1,0,3,2] row_mask:0xf bank_mask:0xf
	s_waitcnt lgkmcnt(6)
	v_fmac_f32_e32 v122, v134, v4
	v_fmac_f32_e32 v122, v135, v5
	v_add_f32_dpp v125, v127, v127 quad_perm:[2,3,0,1] row_mask:0xf bank_mask:0xf
	v_fma_f32 v127, v42, v25, -v125
	v_cndmask_b32_e64 v9, v9, v127, s[90:91]
	s_waitcnt lgkmcnt(5)
	v_fmac_f32_e32 v122, v136, v6
	v_fmac_f32_e32 v122, v137, v7
	s_waitcnt lgkmcnt(4)
	v_fmac_f32_e32 v122, v138, v8
	v_add_u32_e32 v121, 0x6a00, v117
	ds_read2_b32 v[216:217], v121 offset0:0 offset1:4
	ds_read2_b32 v[218:219], v121 offset0:8 offset1:12
	ds_read2_b32 v[220:221], v121 offset0:16 offset1:20
	ds_read2_b32 v[222:223], v121 offset0:24 offset1:28
	v_cndmask_b32_e64 v126, 0, v139, s[18:19]
	v_fma_f32 v125, v126, v9, v122
	s_waitcnt lgkmcnt(7)
	v_mul_f32_e32 v123, v148, v2
	v_fmac_f32_e32 v123, v149, v3
	v_add_f32_dpp v127, v125, v125 quad_perm:[1,0,3,2] row_mask:0xf bank_mask:0xf
	s_waitcnt lgkmcnt(6)
	v_fmac_f32_e32 v123, v150, v4
	v_fmac_f32_e32 v123, v151, v5
	v_add_f32_dpp v125, v127, v127 quad_perm:[2,3,0,1] row_mask:0xf bank_mask:0xf
	v_fma_f32 v127, v42, v25, -v125
	v_cndmask_b32_e64 v9, v9, v127, s[92:93]
	s_waitcnt lgkmcnt(5)
	v_fmac_f32_e32 v123, v152, v6
	v_fmac_f32_e32 v123, v153, v7
	s_waitcnt lgkmcnt(4)
	v_fmac_f32_e32 v123, v154, v8
	v_add_u32_e32 v119, 0x6b10, v117
	ds_read2_b32 v[132:133], v119 offset0:0 offset1:4
	ds_read2_b32 v[134:135], v119 offset0:8 offset1:12
	ds_read2_b32 v[136:137], v119 offset0:16 offset1:20
	ds_read2_b32 v[138:139], v119 offset0:24 offset1:28
	ds_read_b32 v140, v119 offset:128
	v_cndmask_b32_e64 v126, 0, v155, s[22:23]
	v_fma_f32 v125, v126, v9, v123
	s_waitcnt lgkmcnt(8)
	v_mul_f32_e32 v124, v216, v2
	v_fmac_f32_e32 v124, v217, v3
	v_add_f32_dpp v127, v125, v125 quad_perm:[1,0,3,2] row_mask:0xf bank_mask:0xf
	s_waitcnt lgkmcnt(7)
	v_fmac_f32_e32 v124, v218, v4
	v_fmac_f32_e32 v124, v219, v5
	v_add_f32_dpp v125, v127, v127 quad_perm:[2,3,0,1] row_mask:0xf bank_mask:0xf
	v_fma_f32 v127, v42, v25, -v125
	v_cndmask_b32_e64 v9, v9, v127, s[98:99]
	s_waitcnt lgkmcnt(6)
	v_fmac_f32_e32 v124, v220, v6
	v_fmac_f32_e32 v124, v221, v7
	s_waitcnt lgkmcnt(5)
	v_fmac_f32_e32 v124, v222, v8
	v_add_u32_e32 v120, 0x6c20, v117
	ds_read2_b32 v[148:149], v120 offset0:0 offset1:4
	ds_read2_b32 v[150:151], v120 offset0:8 offset1:12
	ds_read2_b32 v[152:153], v120 offset0:16 offset1:20
	ds_read2_b32 v[154:155], v120 offset0:24 offset1:28
	ds_read_b32 v156, v120 offset:128
	v_fma_f32 v125, v223, v9, v124
	s_waitcnt lgkmcnt(9)
	v_mul_f32_e32 v122, v132, v2
	v_fmac_f32_e32 v122, v133, v3
	v_add_f32_dpp v127, v125, v125 quad_perm:[1,0,3,2] row_mask:0xf bank_mask:0xf
	s_waitcnt lgkmcnt(8)
	v_fmac_f32_e32 v122, v134, v4
	v_fmac_f32_e32 v122, v135, v5
	v_add_f32_dpp v125, v127, v127 quad_perm:[2,3,0,1] row_mask:0xf bank_mask:0xf
	v_fma_f32 v127, v43, v26, -v125
	v_cndmask_b32_e64 v10, v10, v127, s[88:89]
	s_waitcnt lgkmcnt(7)
	v_fmac_f32_e32 v122, v136, v6
	v_fmac_f32_e32 v122, v137, v7
	s_waitcnt lgkmcnt(6)
	v_fmac_f32_e32 v122, v138, v8
	v_fmac_f32_e32 v122, v139, v9
	v_add_u32_e32 v121, 0x6d30, v117
	ds_read2_b32 v[216:217], v121 offset0:0 offset1:4
	ds_read2_b32 v[218:219], v121 offset0:8 offset1:12
	ds_read2_b32 v[220:221], v121 offset0:16 offset1:20
	ds_read2_b32 v[222:223], v121 offset0:24 offset1:28
	ds_read_b32 v224, v121 offset:128
	s_waitcnt lgkmcnt(10)
	v_cndmask_b32_e64 v126, 0, v140, s[100:101]
	v_fma_f32 v125, v126, v10, v122
	s_waitcnt lgkmcnt(9)
	v_mul_f32_e32 v123, v148, v2
	v_fmac_f32_e32 v123, v149, v3
	v_add_f32_dpp v127, v125, v125 quad_perm:[1,0,3,2] row_mask:0xf bank_mask:0xf
	s_waitcnt lgkmcnt(8)
	v_fmac_f32_e32 v123, v150, v4
	v_fmac_f32_e32 v123, v151, v5
	v_add_f32_dpp v125, v127, v127 quad_perm:[2,3,0,1] row_mask:0xf bank_mask:0xf
	v_fma_f32 v127, v43, v26, -v125
	v_cndmask_b32_e64 v10, v10, v127, s[90:91]
	s_waitcnt lgkmcnt(7)
	v_fmac_f32_e32 v123, v152, v6
	v_fmac_f32_e32 v123, v153, v7
	s_waitcnt lgkmcnt(6)
	v_fmac_f32_e32 v123, v154, v8
	v_fmac_f32_e32 v123, v155, v9
	v_add_u32_e32 v119, 0x6e40, v117
	ds_read2_b32 v[132:133], v119 offset0:0 offset1:4
	ds_read2_b32 v[134:135], v119 offset0:8 offset1:12
	ds_read2_b32 v[136:137], v119 offset0:16 offset1:20
	ds_read2_b32 v[138:139], v119 offset0:24 offset1:28
	ds_read_b32 v140, v119 offset:128
	s_waitcnt lgkmcnt(10)
	v_cndmask_b32_e64 v126, 0, v156, s[18:19]
	v_fma_f32 v125, v126, v10, v123
	s_waitcnt lgkmcnt(9)
	v_mul_f32_e32 v124, v216, v2
	v_fmac_f32_e32 v124, v217, v3
	v_add_f32_dpp v127, v125, v125 quad_perm:[1,0,3,2] row_mask:0xf bank_mask:0xf
	s_waitcnt lgkmcnt(8)
; template <int DIR>
; DI void dn_solve4(const float* M, const h16* Ki, const h16* Vi, const float* betal, const float* gcl, int half, int c, int pp, float (&x)[16]) {
;   const h16* src = half ? (Ki + c) : (Vi + c);
; #pragma unroll
;   for (int k = 0; k < 16; ++k) x[k] = 0.f;
; #pragma unroll
;   for (int il = 0; il < 64; ++il) {
;     const int ri = DIR ? 63 - il : il;
;     float part = 0.f;
; #pragma unroll
;     for (int k = 0; k < (il + 3) / 4; ++k) {
;       const int jl0 = 4 * k;
;       float mv = DIR ? M[ri * MLD + 63 - jl0 - pp] : M[ri * MLD + jl0 + pp];
;       if (jl0 + 3 >= il) mv = (jl0 + pp < il) ? mv : 0.f;
;       part += mv * x[k];
;     }
;     part += __shfl_xor(part, 1); part += __shfl_xor(part, 2);
;     const float e = half ? __expf(gcl[ri]) : 1.f;
;     const float xi = betal[ri] * (float)src[ri * LDH] * e - part;
;     if ((il & 3) == pp) x[il >> 2] = xi;
;   }
	v_fmac_f32_e32 v124, v218, v4
	v_fmac_f32_e32 v124, v219, v5
	v_add_f32_dpp v125, v127, v127 quad_perm:[2,3,0,1] row_mask:0xf bank_mask:0xf
	v_fma_f32 v127, v43, v26, -v125
	v_cndmask_b32_e64 v10, v10, v127, s[92:93]
	s_waitcnt lgkmcnt(7)
	v_fmac_f32_e32 v124, v220, v6
	v_fmac_f32_e32 v124, v221, v7
	s_waitcnt lgkmcnt(6)
	v_fmac_f32_e32 v124, v222, v8
	v_fmac_f32_e32 v124, v223, v9
	v_add_u32_e32 v120, 0x6f50, v117
	ds_read2_b32 v[148:149], v120 offset0:0 offset1:4
	ds_read2_b32 v[150:151], v120 offset0:8 offset1:12
	ds_read2_b32 v[152:153], v120 offset0:16 offset1:20
	ds_read2_b32 v[154:155], v120 offset0:24 offset1:28
	ds_read2_b32 v[156:157], v120 offset0:32 offset1:36
	s_waitcnt lgkmcnt(10)
	v_cndmask_b32_e64 v126, 0, v224, s[22:23]
	v_fma_f32 v125, v126, v10, v124
	s_waitcnt lgkmcnt(9)
	v_mul_f32_e32 v122, v132, v2
	v_fmac_f32_e32 v122, v133, v3
	v_add_f32_dpp v127, v125, v125 quad_perm:[1,0,3,2] row_mask:0xf bank_mask:0xf
	s_waitcnt lgkmcnt(8)
	v_fmac_f32_e32 v122, v134, v4
	v_fmac_f32_e32 v122, v135, v5
	v_add_f32_dpp v125, v127, v127 quad_perm:[2,3,0,1] row_mask:0xf bank_mask:0xf
	v_fma_f32 v127, v43, v26, -v125
	v_cndmask_b32_e64 v10, v10, v127, s[98:99]
	s_waitcnt lgkmcnt(7)
	v_fmac_f32_e32 v122, v136, v6
	v_fmac_f32_e32 v122, v137, v7
	s_waitcnt lgkmcnt(6)
	v_fmac_f32_e32 v122, v138, v8
	v_fmac_f32_e32 v122, v139, v9
	v_add_u32_e32 v121, 0x7060, v117
	ds_read2_b32 v[216:217], v121 offset0:0 offset1:4
	ds_read2_b32 v[218:219], v121 offset0:8 offset1:12
	ds_read2_b32 v[220:221], v121 offset0:16 offset1:20
	ds_read2_b32 v[222:223], v121 offset0:24 offset1:28
	ds_read2_b32 v[224:225], v121 offset0:32 offset1:36
	s_waitcnt lgkmcnt(10)
	v_fma_f32 v125, v140, v10, v122
	s_waitcnt lgkmcnt(9)
	v_mul_f32_e32 v123, v148, v2
	v_fmac_f32_e32 v123, v149, v3
	v_add_f32_dpp v127, v125, v125 quad_perm:[1,0,3,2] row_mask:0xf bank_mask:0xf
	s_waitcnt lgkmcnt(8)
	v_fmac_f32_e32 v123, v150, v4
	v_fmac_f32_e32 v123, v151, v5
	v_add_f32_dpp v125, v127, v127 quad_perm:[2,3,0,1] row_mask:0xf bank_mask:0xf
	v_fma_f32 v127, v44, v27, -v125
	v_cndmask_b32_e64 v11, v11, v127, s[88:89]
	s_waitcnt lgkmcnt(7)
	v_fmac_f32_e32 v123, v152, v6
	v_fmac_f32_e32 v123, v153, v7
	s_waitcnt lgkmcnt(6)
	v_fmac_f32_e32 v123, v154, v8
	v_fmac_f32_e32 v123, v155, v9
	s_waitcnt lgkmcnt(5)
	v_fmac_f32_e32 v123, v156, v10
	v_add_u32_e32 v119, 0x7170, v117
	ds_read2_b32 v[132:133], v119 offset0:0 offset1:4
	ds_read2_b32 v[134:135], v119 offset0:8 offset1:12
	ds_read2_b32 v[136:137], v119 offset0:16 offset1:20
	ds_read2_b32 v[138:139], v119 offset0:24 offset1:28
	ds_read2_b32 v[140:141], v119 offset0:32 offset1:36
	v_cndmask_b32_e64 v126, 0, v157, s[100:101]
	v_fma_f32 v125, v126, v11, v123
	s_waitcnt lgkmcnt(9)
	v_mul_f32_e32 v124, v216, v2
	v_fmac_f32_e32 v124, v217, v3
	v_add_f32_dpp v127, v125, v125 quad_perm:[1,0,3,2] row_mask:0xf bank_mask:0xf
	s_waitcnt lgkmcnt(8)
	v_fmac_f32_e32 v124, v218, v4
	v_fmac_f32_e32 v124, v219, v5
	v_add_f32_dpp v125, v127, v127 quad_perm:[2,3,0,1] row_mask:0xf bank_mask:0xf
	v_fma_f32 v127, v44, v27, -v125
	v_cndmask_b32_e64 v11, v11, v127, s[90:91]
	s_waitcnt lgkmcnt(7)
	v_fmac_f32_e32 v124, v220, v6
	v_fmac_f32_e32 v124, v221, v7
	s_waitcnt lgkmcnt(6)
	v_fmac_f32_e32 v124, v222, v8
	v_fmac_f32_e32 v124, v223, v9
	s_waitcnt lgkmcnt(5)
	v_fmac_f32_e32 v124, v224, v10
	v_add_u32_e32 v120, 0x7280, v117
	ds_read2_b32 v[148:149], v120 offset0:0 offset1:4
	ds_read2_b32 v[150:151], v120 offset0:8 offset1:12
	ds_read2_b32 v[152:153], v120 offset0:16 offset1:20
	ds_read2_b32 v[154:155], v120 offset0:24 offset1:28
	ds_read2_b32 v[156:157], v120 offset0:32 offset1:36
	v_cndmask_b32_e64 v126, 0, v225, s[18:19]
	v_fma_f32 v125, v126, v11, v124
	s_waitcnt lgkmcnt(9)
	v_mul_f32_e32 v122, v132, v2
	v_fmac_f32_e32 v122, v133, v3
	v_add_f32_dpp v127, v125, v125 quad_perm:[1,0,3,2] row_mask:0xf bank_mask:0xf
	s_waitcnt lgkmcnt(8)
	v_fmac_f32_e32 v122, v134, v4
	v_fmac_f32_e32 v122, v135, v5
	v_add_f32_dpp v125, v127, v127 quad_perm:[2,3,0,1] row_mask:0xf bank_mask:0xf
	v_fma_f32 v127, v44, v27, -v125
	v_cndmask_b32_e64 v11, v11, v127, s[92:93]
	s_waitcnt lgkmcnt(7)
	v_fmac_f32_e32 v122, v136, v6
	v_fmac_f32_e32 v122, v137, v7
	s_waitcnt lgkmcnt(6)
	v_fmac_f32_e32 v122, v138, v8
	v_fmac_f32_e32 v122, v139, v9
	s_waitcnt lgkmcnt(5)
	v_fmac_f32_e32 v122, v140, v10
	v_add_u32_e32 v121, 0x7390, v117
	ds_read2_b32 v[216:217], v121 offset0:0 offset1:4
	ds_read2_b32 v[218:219], v121 offset0:8 offset1:12
	ds_read2_b32 v[220:221], v121 offset0:16 offset1:20
	ds_read2_b32 v[222:223], v121 offset0:24 offset1:28
	ds_read2_b32 v[224:225], v121 offset0:32 offset1:36
	ds_read_b32 v226, v121 offset:160
	v_cndmask_b32_e64 v126, 0, v141, s[22:23]
	v_fma_f32 v125, v126, v11, v122
	s_waitcnt lgkmcnt(10)
	v_mul_f32_e32 v123, v148, v2
	v_fmac_f32_e32 v123, v149, v3
	v_add_f32_dpp v127, v125, v125 quad_perm:[1,0,3,2] row_mask:0xf bank_mask:0xf
	s_waitcnt lgkmcnt(9)
	v_fmac_f32_e32 v123, v150, v4
	v_fmac_f32_e32 v123, v151, v5
	v_add_f32_dpp v125, v127, v127 quad_perm:[2,3,0,1] row_mask:0xf bank_mask:0xf
	v_fma_f32 v127, v44, v27, -v125
	v_cndmask_b32_e64 v11, v11, v127, s[98:99]
	s_waitcnt lgkmcnt(8)
	v_fmac_f32_e32 v123, v152, v6
	v_fmac_f32_e32 v123, v153, v7
	s_waitcnt lgkmcnt(7)
	v_fmac_f32_e32 v123, v154, v8
	v_fmac_f32_e32 v123, v155, v9
	s_waitcnt lgkmcnt(6)
	v_fmac_f32_e32 v123, v156, v10
	v_add_u32_e32 v119, 0x74a0, v117
	ds_read2_b32 v[132:133], v119 offset0:0 offset1:4
	ds_read2_b32 v[134:135], v119 offset0:8 offset1:12
	ds_read2_b32 v[136:137], v119 offset0:16 offset1:20
	ds_read2_b32 v[138:139], v119 offset0:24 offset1:28
	ds_read2_b32 v[140:141], v119 offset0:32 offset1:36
	ds_read_b32 v142, v119 offset:160
	v_fma_f32 v125, v157, v11, v123
	s_waitcnt lgkmcnt(11)
; template <int DIR>
; DI void dn_solve4(const float* M, const h16* Ki, const h16* Vi, const float* betal, const float* gcl, int half, int c, int pp, float (&x)[16]) {
;     ...
; #pragma unroll
;   for (int il = 0; il < 64; ++il) {
;     const int ri = DIR ? 63 - il : il;
;     float part = 0.f;
; #pragma unroll
;     for (int k = 0; k < (il + 3) / 4; ++k) {
;       const int jl0 = 4 * k;
;       float mv = DIR ? M[ri * MLD + 63 - jl0 - pp] : M[ri * MLD + jl0 + pp];
;       if (jl0 + 3 >= il) mv = (jl0 + pp < il) ? mv : 0.f;
;       part += mv * x[k];
;     }
;     part += __shfl_xor(part, 1); part += __shfl_xor(part, 2);
;     const float e = half ? __expf(gcl[ri]) : 1.f;
;     const float xi = betal[ri] * (float)src[ri * LDH] * e - part;
;     if ((il & 3) == pp) x[il >> 2] = xi;
;   }
	v_mul_f32_e32 v124, v216, v2
	v_fmac_f32_e32 v124, v217, v3
	v_add_f32_dpp v127, v125, v125 quad_perm:[1,0,3,2] row_mask:0xf bank_mask:0xf
	s_waitcnt lgkmcnt(10)
	v_fmac_f32_e32 v124, v218, v4
	v_fmac_f32_e32 v124, v219, v5
	v_add_f32_dpp v125, v127, v127 quad_perm:[2,3,0,1] row_mask:0xf bank_mask:0xf
	v_fma_f32 v127, v45, v28, -v125
	v_cndmask_b32_e64 v12, v12, v127, s[88:89]
	s_waitcnt lgkmcnt(9)
	v_fmac_f32_e32 v124, v220, v6
	v_fmac_f32_e32 v124, v221, v7
	s_waitcnt lgkmcnt(8)
	v_fmac_f32_e32 v124, v222, v8
	v_fmac_f32_e32 v124, v223, v9
	s_waitcnt lgkmcnt(7)
	v_fmac_f32_e32 v124, v224, v10
	v_fmac_f32_e32 v124, v225, v11
	v_add_u32_e32 v120, 0x75b0, v117
	ds_read2_b32 v[148:149], v120 offset0:0 offset1:4
	ds_read2_b32 v[150:151], v120 offset0:8 offset1:12
	ds_read2_b32 v[152:153], v120 offset0:16 offset1:20
	ds_read2_b32 v[154:155], v120 offset0:24 offset1:28
	ds_read2_b32 v[156:157], v120 offset0:32 offset1:36
	ds_read_b32 v158, v120 offset:160
	s_waitcnt lgkmcnt(12)
	v_cndmask_b32_e64 v126, 0, v226, s[100:101]
	v_fma_f32 v125, v126, v12, v124
	s_waitcnt lgkmcnt(11)
	v_mul_f32_e32 v122, v132, v2
	v_fmac_f32_e32 v122, v133, v3
	v_add_f32_dpp v127, v125, v125 quad_perm:[1,0,3,2] row_mask:0xf bank_mask:0xf
	s_waitcnt lgkmcnt(10)
	v_fmac_f32_e32 v122, v134, v4
	v_fmac_f32_e32 v122, v135, v5
	v_add_f32_dpp v125, v127, v127 quad_perm:[2,3,0,1] row_mask:0xf bank_mask:0xf
	v_fma_f32 v127, v45, v28, -v125
	v_cndmask_b32_e64 v12, v12, v127, s[90:91]
	s_waitcnt lgkmcnt(9)
	v_fmac_f32_e32 v122, v136, v6
	v_fmac_f32_e32 v122, v137, v7
	s_waitcnt lgkmcnt(8)
	v_fmac_f32_e32 v122, v138, v8
	v_fmac_f32_e32 v122, v139, v9
	s_waitcnt lgkmcnt(7)
	v_fmac_f32_e32 v122, v140, v10
	v_fmac_f32_e32 v122, v141, v11
	v_add_u32_e32 v121, 0x76c0, v117
	ds_read2_b32 v[216:217], v121 offset0:0 offset1:4
	ds_read2_b32 v[218:219], v121 offset0:8 offset1:12
	ds_read2_b32 v[220:221], v121 offset0:16 offset1:20
	ds_read2_b32 v[222:223], v121 offset0:24 offset1:28
	ds_read2_b32 v[224:225], v121 offset0:32 offset1:36
	ds_read_b32 v226, v121 offset:160
	s_waitcnt lgkmcnt(12)
	v_cndmask_b32_e64 v126, 0, v142, s[18:19]
	v_fma_f32 v125, v126, v12, v122
	s_waitcnt lgkmcnt(11)
	v_mul_f32_e32 v123, v148, v2
	v_fmac_f32_e32 v123, v149, v3
	v_add_f32_dpp v127, v125, v125 quad_perm:[1,0,3,2] row_mask:0xf bank_mask:0xf
	s_waitcnt lgkmcnt(10)
	v_fmac_f32_e32 v123, v150, v4
	v_fmac_f32_e32 v123, v151, v5
	v_add_f32_dpp v125, v127, v127 quad_perm:[2,3,0,1] row_mask:0xf bank_mask:0xf
	v_fma_f32 v127, v45, v28, -v125
	v_cndmask_b32_e64 v12, v12, v127, s[92:93]
	s_waitcnt lgkmcnt(9)
	v_fmac_f32_e32 v123, v152, v6
	v_fmac_f32_e32 v123, v153, v7
	s_waitcnt lgkmcnt(8)
	v_fmac_f32_e32 v123, v154, v8
	v_fmac_f32_e32 v123, v155, v9
	s_waitcnt lgkmcnt(7)
	v_fmac_f32_e32 v123, v156, v10
	v_fmac_f32_e32 v123, v157, v11
	v_add_u32_e32 v119, 0x77d0, v117
	ds_read2_b32 v[132:133], v119 offset0:0 offset1:4
	ds_read2_b32 v[134:135], v119 offset0:8 offset1:12
	ds_read2_b32 v[136:137], v119 offset0:16 offset1:20
	ds_read2_b32 v[138:139], v119 offset0:24 offset1:28
	ds_read2_b32 v[140:141], v119 offset0:32 offset1:36
	ds_read2_b32 v[142:143], v119 offset0:40 offset1:44
	s_waitcnt lgkmcnt(12)
	v_cndmask_b32_e64 v126, 0, v158, s[22:23]
	v_fma_f32 v125, v126, v12, v123
	s_waitcnt lgkmcnt(11)
	v_mul_f32_e32 v124, v216, v2
	v_fmac_f32_e32 v124, v217, v3
	v_add_f32_dpp v127, v125, v125 quad_perm:[1,0,3,2] row_mask:0xf bank_mask:0xf
	s_waitcnt lgkmcnt(10)
	v_fmac_f32_e32 v124, v218, v4
	v_fmac_f32_e32 v124, v219, v5
	v_add_f32_dpp v125, v127, v127 quad_perm:[2,3,0,1] row_mask:0xf bank_mask:0xf
	v_fma_f32 v127, v45, v28, -v125
	v_cndmask_b32_e64 v12, v12, v127, s[98:99]
	s_waitcnt lgkmcnt(9)
	v_fmac_f32_e32 v124, v220, v6
	v_fmac_f32_e32 v124, v221, v7
	s_waitcnt lgkmcnt(8)
	v_fmac_f32_e32 v124, v222, v8
	v_fmac_f32_e32 v124, v223, v9
	s_waitcnt lgkmcnt(7)
	v_fmac_f32_e32 v124, v224, v10
	v_fmac_f32_e32 v124, v225, v11
	v_add_u32_e32 v120, 0x78e0, v117
	ds_read2_b32 v[148:149], v120 offset0:0 offset1:4
	ds_read2_b32 v[150:151], v120 offset0:8 offset1:12
	ds_read2_b32 v[152:153], v120 offset0:16 offset1:20
	ds_read2_b32 v[154:155], v120 offset0:24 offset1:28
	ds_read2_b32 v[156:157], v120 offset0:32 offset1:36
	ds_read2_b32 v[158:159], v120 offset0:40 offset1:44
	s_waitcnt lgkmcnt(12)
	v_fma_f32 v125, v226, v12, v124
	s_waitcnt lgkmcnt(11)
	v_mul_f32_e32 v122, v132, v2
	v_fmac_f32_e32 v122, v133, v3
	v_add_f32_dpp v127, v125, v125 quad_perm:[1,0,3,2] row_mask:0xf bank_mask:0xf
	s_waitcnt lgkmcnt(10)
	v_fmac_f32_e32 v122, v134, v4
	v_fmac_f32_e32 v122, v135, v5
	v_add_f32_dpp v125, v127, v127 quad_perm:[2,3,0,1] row_mask:0xf bank_mask:0xf
	v_fma_f32 v127, v46, v30, -v125
	v_cndmask_b32_e64 v13, v13, v127, s[88:89]
	s_waitcnt lgkmcnt(9)
	v_fmac_f32_e32 v122, v136, v6
	v_fmac_f32_e32 v122, v137, v7
	s_waitcnt lgkmcnt(8)
	v_fmac_f32_e32 v122, v138, v8
	v_fmac_f32_e32 v122, v139, v9
	s_waitcnt lgkmcnt(7)
	v_fmac_f32_e32 v122, v140, v10
	v_fmac_f32_e32 v122, v141, v11
	s_waitcnt lgkmcnt(6)
	v_fmac_f32_e32 v122, v142, v12
	v_add_u32_e32 v121, 0x79f0, v117
	ds_read2_b32 v[216:217], v121 offset0:0 offset1:4
	ds_read2_b32 v[218:219], v121 offset0:8 offset1:12
	ds_read2_b32 v[220:221], v121 offset0:16 offset1:20
	ds_read2_b32 v[222:223], v121 offset0:24 offset1:28
	ds_read2_b32 v[224:225], v121 offset0:32 offset1:36
	ds_read2_b32 v[226:227], v121 offset0:40 offset1:44
	v_cndmask_b32_e64 v126, 0, v143, s[100:101]
	v_fma_f32 v125, v126, v13, v122
	s_waitcnt lgkmcnt(11)
	v_mul_f32_e32 v123, v148, v2
	v_fmac_f32_e32 v123, v149, v3
	v_add_f32_dpp v127, v125, v125 quad_perm:[1,0,3,2] row_mask:0xf bank_mask:0xf
	s_waitcnt lgkmcnt(10)
; template <int DIR>
; DI void dn_solve4(const float* M, const h16* Ki, const h16* Vi, const float* betal, const float* gcl, int half, int c, int pp, float (&x)[16]) {
;     ...
; #pragma unroll
;   for (int il = 0; il < 64; ++il) {
;     const int ri = DIR ? 63 - il : il;
;     float part = 0.f;
; #pragma unroll
;     for (int k = 0; k < (il + 3) / 4; ++k) {
;       const int jl0 = 4 * k;
;       float mv = DIR ? M[ri * MLD + 63 - jl0 - pp] : M[ri * MLD + jl0 + pp];
;       if (jl0 + 3 >= il) mv = (jl0 + pp < il) ? mv : 0.f;
;       part += mv * x[k];
;     }
;     part += __shfl_xor(part, 1); part += __shfl_xor(part, 2);
;     const float e = half ? __expf(gcl[ri]) : 1.f;
;     const float xi = betal[ri] * (float)src[ri * LDH] * e - part;
;     if ((il & 3) == pp) x[il >> 2] = xi;
;   }
	v_fmac_f32_e32 v123, v150, v4
	v_fmac_f32_e32 v123, v151, v5
	v_add_f32_dpp v125, v127, v127 quad_perm:[2,3,0,1] row_mask:0xf bank_mask:0xf
	v_fma_f32 v127, v46, v30, -v125
	v_cndmask_b32_e64 v13, v13, v127, s[90:91]
	s_waitcnt lgkmcnt(9)
	v_fmac_f32_e32 v123, v152, v6
	v_fmac_f32_e32 v123, v153, v7
	s_waitcnt lgkmcnt(8)
	v_fmac_f32_e32 v123, v154, v8
	v_fmac_f32_e32 v123, v155, v9
	s_waitcnt lgkmcnt(7)
	v_fmac_f32_e32 v123, v156, v10
	v_fmac_f32_e32 v123, v157, v11
	s_waitcnt lgkmcnt(6)
	v_fmac_f32_e32 v123, v158, v12
	v_add_u32_e32 v119, 0x7b00, v117
	ds_read2_b32 v[132:133], v119 offset0:0 offset1:4
	ds_read2_b32 v[134:135], v119 offset0:8 offset1:12
	ds_read2_b32 v[136:137], v119 offset0:16 offset1:20
	ds_read2_b32 v[138:139], v119 offset0:24 offset1:28
	ds_read2_b32 v[140:141], v119 offset0:32 offset1:36
	ds_read2_b32 v[142:143], v119 offset0:40 offset1:44
	v_cndmask_b32_e64 v126, 0, v159, s[18:19]
	v_fma_f32 v125, v126, v13, v123
	s_waitcnt lgkmcnt(11)
	v_mul_f32_e32 v124, v216, v2
	v_fmac_f32_e32 v124, v217, v3
	v_add_f32_dpp v127, v125, v125 quad_perm:[1,0,3,2] row_mask:0xf bank_mask:0xf
	s_waitcnt lgkmcnt(10)
	v_fmac_f32_e32 v124, v218, v4
	v_fmac_f32_e32 v124, v219, v5
	v_add_f32_dpp v125, v127, v127 quad_perm:[2,3,0,1] row_mask:0xf bank_mask:0xf
	v_fma_f32 v127, v46, v30, -v125
	v_cndmask_b32_e64 v13, v13, v127, s[92:93]
	s_waitcnt lgkmcnt(9)
	v_fmac_f32_e32 v124, v220, v6
	v_fmac_f32_e32 v124, v221, v7
	s_waitcnt lgkmcnt(8)
	v_fmac_f32_e32 v124, v222, v8
	v_fmac_f32_e32 v124, v223, v9
	s_waitcnt lgkmcnt(7)
	v_fmac_f32_e32 v124, v224, v10
	v_fmac_f32_e32 v124, v225, v11
	s_waitcnt lgkmcnt(6)
	v_fmac_f32_e32 v124, v226, v12
	v_add_u32_e32 v120, 0x7c10, v117
	ds_read2_b32 v[148:149], v120 offset0:0 offset1:4
	ds_read2_b32 v[150:151], v120 offset0:8 offset1:12
	ds_read2_b32 v[152:153], v120 offset0:16 offset1:20
	ds_read2_b32 v[154:155], v120 offset0:24 offset1:28
	ds_read2_b32 v[156:157], v120 offset0:32 offset1:36
	ds_read2_b32 v[158:159], v120 offset0:40 offset1:44
	ds_read_b32 v160, v120 offset:192
	v_cndmask_b32_e64 v126, 0, v227, s[22:23]
	v_fma_f32 v125, v126, v13, v124
	s_waitcnt lgkmcnt(12)
	v_mul_f32_e32 v122, v132, v2
	v_fmac_f32_e32 v122, v133, v3
	v_add_f32_dpp v127, v125, v125 quad_perm:[1,0,3,2] row_mask:0xf bank_mask:0xf
	s_waitcnt lgkmcnt(11)
	v_fmac_f32_e32 v122, v134, v4
	v_fmac_f32_e32 v122, v135, v5
	v_add_f32_dpp v125, v127, v127 quad_perm:[2,3,0,1] row_mask:0xf bank_mask:0xf
	v_fma_f32 v127, v46, v30, -v125
	v_cndmask_b32_e64 v13, v13, v127, s[98:99]
	s_waitcnt lgkmcnt(10)
	v_fmac_f32_e32 v122, v136, v6
	v_fmac_f32_e32 v122, v137, v7
	s_waitcnt lgkmcnt(9)
	v_fmac_f32_e32 v122, v138, v8
	v_fmac_f32_e32 v122, v139, v9
	s_waitcnt lgkmcnt(8)
	v_fmac_f32_e32 v122, v140, v10
	v_fmac_f32_e32 v122, v141, v11
	s_waitcnt lgkmcnt(7)
	v_fmac_f32_e32 v122, v142, v12
	v_add_u32_e32 v121, 0x7d20, v117
	ds_read2_b32 v[216:217], v121 offset0:0 offset1:4
	ds_read2_b32 v[218:219], v121 offset0:8 offset1:12
	ds_read2_b32 v[220:221], v121 offset0:16 offset1:20
	ds_read2_b32 v[222:223], v121 offset0:24 offset1:28
	ds_read2_b32 v[224:225], v121 offset0:32 offset1:36
	ds_read2_b32 v[226:227], v121 offset0:40 offset1:44
	ds_read_b32 v228, v121 offset:192
	v_fma_f32 v125, v143, v13, v122
	s_waitcnt lgkmcnt(13)
	v_mul_f32_e32 v123, v148, v2
	v_fmac_f32_e32 v123, v149, v3
	v_add_f32_dpp v127, v125, v125 quad_perm:[1,0,3,2] row_mask:0xf bank_mask:0xf
	s_waitcnt lgkmcnt(12)
	v_fmac_f32_e32 v123, v150, v4
	v_fmac_f32_e32 v123, v151, v5
	v_add_f32_dpp v125, v127, v127 quad_perm:[2,3,0,1] row_mask:0xf bank_mask:0xf
	v_fma_f32 v127, v47, v31, -v125
	v_cndmask_b32_e64 v14, v14, v127, s[88:89]
	s_waitcnt lgkmcnt(11)
	v_fmac_f32_e32 v123, v152, v6
	v_fmac_f32_e32 v123, v153, v7
	s_waitcnt lgkmcnt(10)
	v_fmac_f32_e32 v123, v154, v8
	v_fmac_f32_e32 v123, v155, v9
	s_waitcnt lgkmcnt(9)
	v_fmac_f32_e32 v123, v156, v10
	v_fmac_f32_e32 v123, v157, v11
	s_waitcnt lgkmcnt(8)
	v_fmac_f32_e32 v123, v158, v12
	v_fmac_f32_e32 v123, v159, v13
	v_add_u32_e32 v119, 0x7e30, v117
	ds_read2_b32 v[132:133], v119 offset0:0 offset1:4
	ds_read2_b32 v[134:135], v119 offset0:8 offset1:12
	ds_read2_b32 v[136:137], v119 offset0:16 offset1:20
	ds_read2_b32 v[138:139], v119 offset0:24 offset1:28
	ds_read2_b32 v[140:141], v119 offset0:32 offset1:36
	ds_read2_b32 v[142:143], v119 offset0:40 offset1:44
	ds_read_b32 v144, v119 offset:192
	s_waitcnt lgkmcnt(14)
	v_cndmask_b32_e64 v126, 0, v160, s[100:101]
	v_fma_f32 v125, v126, v14, v123
	s_waitcnt lgkmcnt(13)
	v_mul_f32_e32 v124, v216, v2
	v_fmac_f32_e32 v124, v217, v3
	v_add_f32_dpp v127, v125, v125 quad_perm:[1,0,3,2] row_mask:0xf bank_mask:0xf
	s_waitcnt lgkmcnt(12)
	v_fmac_f32_e32 v124, v218, v4
	v_fmac_f32_e32 v124, v219, v5
	v_add_f32_dpp v125, v127, v127 quad_perm:[2,3,0,1] row_mask:0xf bank_mask:0xf
	v_fma_f32 v127, v47, v31, -v125
	v_cndmask_b32_e64 v14, v14, v127, s[90:91]
	s_waitcnt lgkmcnt(11)
	v_fmac_f32_e32 v124, v220, v6
	v_fmac_f32_e32 v124, v221, v7
	s_waitcnt lgkmcnt(10)
	v_fmac_f32_e32 v124, v222, v8
	v_fmac_f32_e32 v124, v223, v9
	s_waitcnt lgkmcnt(9)
	v_fmac_f32_e32 v124, v224, v10
	v_fmac_f32_e32 v124, v225, v11
	s_waitcnt lgkmcnt(8)
	v_fmac_f32_e32 v124, v226, v12
	v_fmac_f32_e32 v124, v227, v13
	v_add_u32_e32 v120, 0x7f40, v117
	ds_read2_b32 v[148:149], v120 offset0:0 offset1:4
	ds_read2_b32 v[150:151], v120 offset0:8 offset1:12
	ds_read2_b32 v[152:153], v120 offset0:16 offset1:20
	ds_read2_b32 v[154:155], v120 offset0:24 offset1:28
	ds_read2_b32 v[156:157], v120 offset0:32 offset1:36
	ds_read2_b32 v[158:159], v120 offset0:40 offset1:44
	ds_read_b32 v160, v120 offset:192
	s_waitcnt lgkmcnt(14)
; template <int DIR>
; DI void dn_solve4(const float* M, const h16* Ki, const h16* Vi, const float* betal, const float* gcl, int half, int c, int pp, float (&x)[16]) {
;     ...
; #pragma unroll
;   for (int il = 0; il < 64; ++il) {
;     const int ri = DIR ? 63 - il : il;
;     float part = 0.f;
; #pragma unroll
;     for (int k = 0; k < (il + 3) / 4; ++k) {
;       const int jl0 = 4 * k;
;       float mv = DIR ? M[ri * MLD + 63 - jl0 - pp] : M[ri * MLD + jl0 + pp];
;       if (jl0 + 3 >= il) mv = (jl0 + pp < il) ? mv : 0.f;
;       part += mv * x[k];
;     }
;     part += __shfl_xor(part, 1); part += __shfl_xor(part, 2);
;     const float e = half ? __expf(gcl[ri]) : 1.f;
;     const float xi = betal[ri] * (float)src[ri * LDH] * e - part;
;     if ((il & 3) == pp) x[il >> 2] = xi;
;   }
	v_cndmask_b32_e64 v126, 0, v228, s[18:19]
	v_fma_f32 v125, v126, v14, v124
	s_waitcnt lgkmcnt(13)
	v_mul_f32_e32 v122, v132, v2
	v_fmac_f32_e32 v122, v133, v3
	v_add_f32_dpp v127, v125, v125 quad_perm:[1,0,3,2] row_mask:0xf bank_mask:0xf
	s_waitcnt lgkmcnt(12)
	v_fmac_f32_e32 v122, v134, v4
	v_fmac_f32_e32 v122, v135, v5
	v_add_f32_dpp v125, v127, v127 quad_perm:[2,3,0,1] row_mask:0xf bank_mask:0xf
	v_fma_f32 v127, v47, v31, -v125
	v_cndmask_b32_e64 v14, v14, v127, s[92:93]
	s_waitcnt lgkmcnt(11)
	v_fmac_f32_e32 v122, v136, v6
	v_fmac_f32_e32 v122, v137, v7
	s_waitcnt lgkmcnt(10)
	v_fmac_f32_e32 v122, v138, v8
	v_fmac_f32_e32 v122, v139, v9
	s_waitcnt lgkmcnt(9)
	v_fmac_f32_e32 v122, v140, v10
	v_fmac_f32_e32 v122, v141, v11
	s_waitcnt lgkmcnt(8)
	v_fmac_f32_e32 v122, v142, v12
	v_fmac_f32_e32 v122, v143, v13
	v_add_u32_e32 v121, 0x8050, v117
	ds_read2_b32 v[216:217], v121 offset0:0 offset1:4
	ds_read2_b32 v[218:219], v121 offset0:8 offset1:12
	ds_read2_b32 v[220:221], v121 offset0:16 offset1:20
	ds_read2_b32 v[222:223], v121 offset0:24 offset1:28
	ds_read2_b32 v[224:225], v121 offset0:32 offset1:36
	ds_read2_b32 v[226:227], v121 offset0:40 offset1:44
	ds_read2_b32 v[228:229], v121 offset0:48 offset1:52
	s_waitcnt lgkmcnt(14)
	v_cndmask_b32_e64 v126, 0, v144, s[22:23]
	v_fma_f32 v125, v126, v14, v122
	s_waitcnt lgkmcnt(13)
	v_mul_f32_e32 v123, v148, v2
	v_fmac_f32_e32 v123, v149, v3
	v_add_f32_dpp v127, v125, v125 quad_perm:[1,0,3,2] row_mask:0xf bank_mask:0xf
	s_waitcnt lgkmcnt(12)
	v_fmac_f32_e32 v123, v150, v4
	v_fmac_f32_e32 v123, v151, v5
	v_add_f32_dpp v125, v127, v127 quad_perm:[2,3,0,1] row_mask:0xf bank_mask:0xf
	v_fma_f32 v127, v47, v31, -v125
	v_cndmask_b32_e64 v14, v14, v127, s[98:99]
	s_waitcnt lgkmcnt(11)
	v_fmac_f32_e32 v123, v152, v6
	v_fmac_f32_e32 v123, v153, v7
	s_waitcnt lgkmcnt(10)
	v_fmac_f32_e32 v123, v154, v8
	v_fmac_f32_e32 v123, v155, v9
	s_waitcnt lgkmcnt(9)
	v_fmac_f32_e32 v123, v156, v10
	v_fmac_f32_e32 v123, v157, v11
	s_waitcnt lgkmcnt(8)
	v_fmac_f32_e32 v123, v158, v12
	v_fmac_f32_e32 v123, v159, v13
	v_add_u32_e32 v119, 0x8160, v117
	ds_read2_b32 v[132:133], v119 offset0:0 offset1:4
	ds_read2_b32 v[134:135], v119 offset0:8 offset1:12
	ds_read2_b32 v[136:137], v119 offset0:16 offset1:20
	ds_read2_b32 v[138:139], v119 offset0:24 offset1:28
	ds_read2_b32 v[140:141], v119 offset0:32 offset1:36
	ds_read2_b32 v[142:143], v119 offset0:40 offset1:44
	ds_read2_b32 v[144:145], v119 offset0:48 offset1:52
	s_waitcnt lgkmcnt(14)
	v_fma_f32 v125, v160, v14, v123
	s_waitcnt lgkmcnt(13)
	v_mul_f32_e32 v124, v216, v2
	v_fmac_f32_e32 v124, v217, v3
	v_add_f32_dpp v127, v125, v125 quad_perm:[1,0,3,2] row_mask:0xf bank_mask:0xf
	s_waitcnt lgkmcnt(12)
	v_fmac_f32_e32 v124, v218, v4
	v_fmac_f32_e32 v124, v219, v5
	v_add_f32_dpp v125, v127, v127 quad_perm:[2,3,0,1] row_mask:0xf bank_mask:0xf
	v_fma_f32 v127, v48, v32, -v125
	v_cndmask_b32_e64 v15, v15, v127, s[88:89]
	s_waitcnt lgkmcnt(11)
	v_fmac_f32_e32 v124, v220, v6
	v_fmac_f32_e32 v124, v221, v7
	s_waitcnt lgkmcnt(10)
	v_fmac_f32_e32 v124, v222, v8
	v_fmac_f32_e32 v124, v223, v9
	s_waitcnt lgkmcnt(9)
	v_fmac_f32_e32 v124, v224, v10
	v_fmac_f32_e32 v124, v225, v11
	s_waitcnt lgkmcnt(8)
	v_fmac_f32_e32 v124, v226, v12
	v_fmac_f32_e32 v124, v227, v13
	s_waitcnt lgkmcnt(7)
	v_fmac_f32_e32 v124, v228, v14
	v_add_u32_e32 v120, 0x8270, v117
	ds_read2_b32 v[148:149], v120 offset0:0 offset1:4
	ds_read2_b32 v[150:151], v120 offset0:8 offset1:12
	ds_read2_b32 v[152:153], v120 offset0:16 offset1:20
	ds_read2_b32 v[154:155], v120 offset0:24 offset1:28
	ds_read2_b32 v[156:157], v120 offset0:32 offset1:36
	ds_read2_b32 v[158:159], v120 offset0:40 offset1:44
	ds_read2_b32 v[160:161], v120 offset0:48 offset1:52
	v_cndmask_b32_e64 v126, 0, v229, s[100:101]
	v_fma_f32 v125, v126, v15, v124
	s_waitcnt lgkmcnt(13)
	v_mul_f32_e32 v122, v132, v2
	v_fmac_f32_e32 v122, v133, v3
	v_add_f32_dpp v127, v125, v125 quad_perm:[1,0,3,2] row_mask:0xf bank_mask:0xf
	s_waitcnt lgkmcnt(12)
	v_fmac_f32_e32 v122, v134, v4
	v_fmac_f32_e32 v122, v135, v5
	v_add_f32_dpp v125, v127, v127 quad_perm:[2,3,0,1] row_mask:0xf bank_mask:0xf
	v_fma_f32 v127, v48, v32, -v125
	v_cndmask_b32_e64 v15, v15, v127, s[90:91]
	s_waitcnt lgkmcnt(11)
	v_fmac_f32_e32 v122, v136, v6
	v_fmac_f32_e32 v122, v137, v7
	s_waitcnt lgkmcnt(10)
	v_fmac_f32_e32 v122, v138, v8
	v_fmac_f32_e32 v122, v139, v9
	s_waitcnt lgkmcnt(9)
	v_fmac_f32_e32 v122, v140, v10
	v_fmac_f32_e32 v122, v141, v11
	s_waitcnt lgkmcnt(8)
	v_fmac_f32_e32 v122, v142, v12
	v_fmac_f32_e32 v122, v143, v13
	s_waitcnt lgkmcnt(7)
	v_fmac_f32_e32 v122, v144, v14
	v_add_u32_e32 v121, 0x8380, v117
	ds_read2_b32 v[216:217], v121 offset0:0 offset1:4
	ds_read2_b32 v[218:219], v121 offset0:8 offset1:12
	ds_read2_b32 v[220:221], v121 offset0:16 offset1:20
	ds_read2_b32 v[222:223], v121 offset0:24 offset1:28
	ds_read2_b32 v[224:225], v121 offset0:32 offset1:36
	ds_read2_b32 v[226:227], v121 offset0:40 offset1:44
	ds_read2_b32 v[228:229], v121 offset0:48 offset1:52
	v_cndmask_b32_e64 v126, 0, v145, s[18:19]
	v_fma_f32 v125, v126, v15, v122
	s_waitcnt lgkmcnt(13)
	v_mul_f32_e32 v123, v148, v2
	v_fmac_f32_e32 v123, v149, v3
	v_add_f32_dpp v127, v125, v125 quad_perm:[1,0,3,2] row_mask:0xf bank_mask:0xf
	s_waitcnt lgkmcnt(12)
	v_fmac_f32_e32 v123, v150, v4
	v_fmac_f32_e32 v123, v151, v5
	v_add_f32_dpp v125, v127, v127 quad_perm:[2,3,0,1] row_mask:0xf bank_mask:0xf
	v_fma_f32 v127, v48, v32, -v125
	v_cndmask_b32_e64 v15, v15, v127, s[92:93]
	s_waitcnt lgkmcnt(11)
	v_fmac_f32_e32 v123, v152, v6
	v_fmac_f32_e32 v123, v153, v7
	s_waitcnt lgkmcnt(10)
	v_fmac_f32_e32 v123, v154, v8
	v_fmac_f32_e32 v123, v155, v9
	s_waitcnt lgkmcnt(9)
; template <int DIR>
; DI void dn_solve4(const float* M, const h16* Ki, const h16* Vi, const float* betal, const float* gcl, int half, int c, int pp, float (&x)[16]) {
;     ...
; #pragma unroll
;   for (int il = 0; il < 64; ++il) {
;     const int ri = DIR ? 63 - il : il;
;     float part = 0.f;
; #pragma unroll
;     for (int k = 0; k < (il + 3) / 4; ++k) {
;       const int jl0 = 4 * k;
;       float mv = DIR ? M[ri * MLD + 63 - jl0 - pp] : M[ri * MLD + jl0 + pp];
;       if (jl0 + 3 >= il) mv = (jl0 + pp < il) ? mv : 0.f;
;       part += mv * x[k];
;     }
;     part += __shfl_xor(part, 1); part += __shfl_xor(part, 2);
;     const float e = half ? __expf(gcl[ri]) : 1.f;
;     const float xi = betal[ri] * (float)src[ri * LDH] * e - part;
;     if ((il & 3) == pp) x[il >> 2] = xi;
;   }
	v_fmac_f32_e32 v123, v156, v10
	v_fmac_f32_e32 v123, v157, v11
	s_waitcnt lgkmcnt(8)
	v_fmac_f32_e32 v123, v158, v12
	v_fmac_f32_e32 v123, v159, v13
	s_waitcnt lgkmcnt(7)
	v_fmac_f32_e32 v123, v160, v14
	v_add_u32_e32 v119, 0x8490, v117
	ds_read2_b32 v[132:133], v119 offset0:0 offset1:4
	ds_read2_b32 v[134:135], v119 offset0:8 offset1:12
	ds_read2_b32 v[136:137], v119 offset0:16 offset1:20
	ds_read2_b32 v[138:139], v119 offset0:24 offset1:28
	ds_read2_b32 v[140:141], v119 offset0:32 offset1:36
	ds_read2_b32 v[142:143], v119 offset0:40 offset1:44
	ds_read2_b32 v[144:145], v119 offset0:48 offset1:52
	ds_read_b32 v146, v119 offset:224
	v_cndmask_b32_e64 v126, 0, v161, s[22:23]
	v_fma_f32 v125, v126, v15, v123
	s_waitcnt lgkmcnt(14)
	v_mul_f32_e32 v124, v216, v2
	v_fmac_f32_e32 v124, v217, v3
	v_add_f32_dpp v127, v125, v125 quad_perm:[1,0,3,2] row_mask:0xf bank_mask:0xf
	s_waitcnt lgkmcnt(13)
	v_fmac_f32_e32 v124, v218, v4
	v_fmac_f32_e32 v124, v219, v5
	v_add_f32_dpp v125, v127, v127 quad_perm:[2,3,0,1] row_mask:0xf bank_mask:0xf
	v_fma_f32 v127, v48, v32, -v125
	v_cndmask_b32_e64 v15, v15, v127, s[98:99]
	s_waitcnt lgkmcnt(12)
	v_fmac_f32_e32 v124, v220, v6
	v_fmac_f32_e32 v124, v221, v7
	s_waitcnt lgkmcnt(11)
	v_fmac_f32_e32 v124, v222, v8
	v_fmac_f32_e32 v124, v223, v9
	s_waitcnt lgkmcnt(10)
	v_fmac_f32_e32 v124, v224, v10
	v_fmac_f32_e32 v124, v225, v11
	s_waitcnt lgkmcnt(9)
	v_fmac_f32_e32 v124, v226, v12
	v_fmac_f32_e32 v124, v227, v13
	s_waitcnt lgkmcnt(8)
	v_fmac_f32_e32 v124, v228, v14
	v_add_u32_e32 v120, 0x85a0, v117
	ds_read2_b32 v[148:149], v120 offset0:0 offset1:4
	ds_read2_b32 v[150:151], v120 offset0:8 offset1:12
	ds_read2_b32 v[152:153], v120 offset0:16 offset1:20
	ds_read2_b32 v[154:155], v120 offset0:24 offset1:28
	ds_read2_b32 v[156:157], v120 offset0:32 offset1:36
	ds_read2_b32 v[158:159], v120 offset0:40 offset1:44
	ds_read2_b32 v[160:161], v120 offset0:48 offset1:52
	ds_read_b32 v162, v120 offset:224
	v_fma_f32 v125, v229, v15, v124
	s_waitcnt lgkmcnt(15)
	v_mul_f32_e32 v122, v132, v2
	v_fmac_f32_e32 v122, v133, v3
	v_add_f32_dpp v127, v125, v125 quad_perm:[1,0,3,2] row_mask:0xf bank_mask:0xf
	s_waitcnt lgkmcnt(14)
	v_fmac_f32_e32 v122, v134, v4
	v_fmac_f32_e32 v122, v135, v5
	v_add_f32_dpp v125, v127, v127 quad_perm:[2,3,0,1] row_mask:0xf bank_mask:0xf
	v_fma_f32 v127, v49, v33, -v125
	v_cndmask_b32_e64 v16, v16, v127, s[88:89]
	s_waitcnt lgkmcnt(13)
	v_fmac_f32_e32 v122, v136, v6
	v_fmac_f32_e32 v122, v137, v7
	s_waitcnt lgkmcnt(12)
	v_fmac_f32_e32 v122, v138, v8
	v_fmac_f32_e32 v122, v139, v9
	s_waitcnt lgkmcnt(11)
	v_fmac_f32_e32 v122, v140, v10
	v_fmac_f32_e32 v122, v141, v11
	s_waitcnt lgkmcnt(10)
	v_fmac_f32_e32 v122, v142, v12
	v_fmac_f32_e32 v122, v143, v13
	s_waitcnt lgkmcnt(9)
	v_fmac_f32_e32 v122, v144, v14
	v_fmac_f32_e32 v122, v145, v15
	v_add_u32_e32 v121, 0x86b0, v117
	ds_read2_b32 v[216:217], v121 offset0:0 offset1:4
	ds_read2_b32 v[218:219], v121 offset0:8 offset1:12
	ds_read2_b32 v[220:221], v121 offset0:16 offset1:20
	ds_read2_b32 v[222:223], v121 offset0:24 offset1:28
	ds_read2_b32 v[224:225], v121 offset0:32 offset1:36
	ds_read2_b32 v[226:227], v121 offset0:40 offset1:44
	ds_read2_b32 v[228:229], v121 offset0:48 offset1:52
	ds_read_b32 v230, v121 offset:224
	s_waitcnt lgkmcnt(15)
	v_cndmask_b32_e64 v126, 0, v146, s[100:101]
	v_fma_f32 v125, v126, v16, v122
	s_waitcnt lgkmcnt(15)
	v_mul_f32_e32 v123, v148, v2
	v_fmac_f32_e32 v123, v149, v3
	v_add_f32_dpp v127, v125, v125 quad_perm:[1,0,3,2] row_mask:0xf bank_mask:0xf
	s_waitcnt lgkmcnt(14)
	v_fmac_f32_e32 v123, v150, v4
	v_fmac_f32_e32 v123, v151, v5
	v_add_f32_dpp v125, v127, v127 quad_perm:[2,3,0,1] row_mask:0xf bank_mask:0xf
	v_fma_f32 v127, v49, v33, -v125
	v_cndmask_b32_e64 v16, v16, v127, s[90:91]
	s_waitcnt lgkmcnt(13)
	v_fmac_f32_e32 v123, v152, v6
	v_fmac_f32_e32 v123, v153, v7
	s_waitcnt lgkmcnt(12)
	v_fmac_f32_e32 v123, v154, v8
	v_fmac_f32_e32 v123, v155, v9
	s_waitcnt lgkmcnt(11)
	v_fmac_f32_e32 v123, v156, v10
	v_fmac_f32_e32 v123, v157, v11
	s_waitcnt lgkmcnt(10)
	v_fmac_f32_e32 v123, v158, v12
	v_fmac_f32_e32 v123, v159, v13
	s_waitcnt lgkmcnt(9)
	v_fmac_f32_e32 v123, v160, v14
	v_fmac_f32_e32 v123, v161, v15
	v_add_u32_e32 v119, 0x87c0, v117
	ds_read2_b32 v[132:133], v119 offset0:0 offset1:4
	ds_read2_b32 v[134:135], v119 offset0:8 offset1:12
	ds_read2_b32 v[136:137], v119 offset0:16 offset1:20
	ds_read2_b32 v[138:139], v119 offset0:24 offset1:28
	ds_read2_b32 v[140:141], v119 offset0:32 offset1:36
	ds_read2_b32 v[142:143], v119 offset0:40 offset1:44
	ds_read2_b32 v[144:145], v119 offset0:48 offset1:52
	ds_read_b32 v146, v119 offset:224
	s_waitcnt lgkmcnt(15)
	v_cndmask_b32_e64 v126, 0, v162, s[18:19]
	v_fma_f32 v125, v126, v16, v123
	s_waitcnt lgkmcnt(15)
	v_mul_f32_e32 v124, v216, v2
	v_fmac_f32_e32 v124, v217, v3
	v_add_f32_dpp v127, v125, v125 quad_perm:[1,0,3,2] row_mask:0xf bank_mask:0xf
	s_waitcnt lgkmcnt(14)
	v_fmac_f32_e32 v124, v218, v4
	v_fmac_f32_e32 v124, v219, v5
	v_add_f32_dpp v125, v127, v127 quad_perm:[2,3,0,1] row_mask:0xf bank_mask:0xf
	v_fma_f32 v127, v49, v33, -v125
	v_cndmask_b32_e64 v16, v16, v127, s[92:93]
	s_waitcnt lgkmcnt(13)
	v_fmac_f32_e32 v124, v220, v6
	v_fmac_f32_e32 v124, v221, v7
	s_waitcnt lgkmcnt(12)
	v_fmac_f32_e32 v124, v222, v8
	v_fmac_f32_e32 v124, v223, v9
	s_waitcnt lgkmcnt(11)
	v_fmac_f32_e32 v124, v224, v10
	v_fmac_f32_e32 v124, v225, v11
	s_waitcnt lgkmcnt(10)
	v_fmac_f32_e32 v124, v226, v12
	v_fmac_f32_e32 v124, v227, v13
	s_waitcnt lgkmcnt(9)
; template <int DIR>
; DI void dn_solve4(const float* M, const h16* Ki, const h16* Vi, const float* betal, const float* gcl, int half, int c, int pp, float (&x)[16]) {
;     ...
; #pragma unroll
;   for (int il = 0; il < 64; ++il) {
;     const int ri = DIR ? 63 - il : il;
;     float part = 0.f;
; #pragma unroll
;     for (int k = 0; k < (il + 3) / 4; ++k) {
;       const int jl0 = 4 * k;
;       float mv = DIR ? M[ri * MLD + 63 - jl0 - pp] : M[ri * MLD + jl0 + pp];
;       if (jl0 + 3 >= il) mv = (jl0 + pp < il) ? mv : 0.f;
;       part += mv * x[k];
;     }
;     part += __shfl_xor(part, 1); part += __shfl_xor(part, 2);
;     const float e = half ? __expf(gcl[ri]) : 1.f;
;     const float xi = betal[ri] * (float)src[ri * LDH] * e - part;
;     if ((il & 3) == pp) x[il >> 2] = xi;
;   }
	v_fmac_f32_e32 v124, v228, v14
	v_fmac_f32_e32 v124, v229, v15
	v_add_u32_e32 v120, 0x88d0, v117
	ds_read2_b32 v[148:149], v120 offset0:0 offset1:4
	ds_read2_b32 v[150:151], v120 offset0:8 offset1:12
	ds_read2_b32 v[152:153], v120 offset0:16 offset1:20
	ds_read2_b32 v[154:155], v120 offset0:24 offset1:28
	ds_read2_b32 v[156:157], v120 offset0:32 offset1:36
	ds_read2_b32 v[158:159], v120 offset0:40 offset1:44
	ds_read2_b32 v[160:161], v120 offset0:48 offset1:52
	ds_read2_b32 v[162:163], v120 offset0:56 offset1:60
	s_waitcnt lgkmcnt(15)
	v_cndmask_b32_e64 v126, 0, v230, s[22:23]
	v_fma_f32 v125, v126, v16, v124
	s_waitcnt lgkmcnt(15)
	v_mul_f32_e32 v122, v132, v2
	v_fmac_f32_e32 v122, v133, v3
	v_add_f32_dpp v127, v125, v125 quad_perm:[1,0,3,2] row_mask:0xf bank_mask:0xf
	s_waitcnt lgkmcnt(14)
	v_fmac_f32_e32 v122, v134, v4
	v_fmac_f32_e32 v122, v135, v5
	v_add_f32_dpp v125, v127, v127 quad_perm:[2,3,0,1] row_mask:0xf bank_mask:0xf
	v_fma_f32 v127, v49, v33, -v125
	v_cndmask_b32_e64 v16, v16, v127, s[98:99]
	s_waitcnt lgkmcnt(13)
	v_fmac_f32_e32 v122, v136, v6
	v_fmac_f32_e32 v122, v137, v7
	s_waitcnt lgkmcnt(12)
	v_fmac_f32_e32 v122, v138, v8
	v_fmac_f32_e32 v122, v139, v9
	s_waitcnt lgkmcnt(11)
	v_fmac_f32_e32 v122, v140, v10
	v_fmac_f32_e32 v122, v141, v11
	s_waitcnt lgkmcnt(10)
	v_fmac_f32_e32 v122, v142, v12
	v_fmac_f32_e32 v122, v143, v13
	s_waitcnt lgkmcnt(9)
	v_fmac_f32_e32 v122, v144, v14
	v_fmac_f32_e32 v122, v145, v15
	v_add_u32_e32 v121, 0x89e0, v117
	ds_read2_b32 v[216:217], v121 offset0:0 offset1:4
	ds_read2_b32 v[218:219], v121 offset0:8 offset1:12
	ds_read2_b32 v[220:221], v121 offset0:16 offset1:20
	ds_read2_b32 v[222:223], v121 offset0:24 offset1:28
	ds_read2_b32 v[224:225], v121 offset0:32 offset1:36
	ds_read2_b32 v[226:227], v121 offset0:40 offset1:44
	ds_read2_b32 v[228:229], v121 offset0:48 offset1:52
	ds_read2_b32 v[230:231], v121 offset0:56 offset1:60
	s_waitcnt lgkmcnt(15)
	v_fma_f32 v125, v146, v16, v122
	s_waitcnt lgkmcnt(15)
	v_mul_f32_e32 v123, v148, v2
	v_fmac_f32_e32 v123, v149, v3
	v_add_f32_dpp v127, v125, v125 quad_perm:[1,0,3,2] row_mask:0xf bank_mask:0xf
	s_waitcnt lgkmcnt(14)
	v_fmac_f32_e32 v123, v150, v4
	v_fmac_f32_e32 v123, v151, v5
	v_add_f32_dpp v125, v127, v127 quad_perm:[2,3,0,1] row_mask:0xf bank_mask:0xf
	v_fma_f32 v127, v115, v34, -v125
	v_cndmask_b32_e64 v17, v17, v127, s[88:89]
	s_waitcnt lgkmcnt(13)
	v_fmac_f32_e32 v123, v152, v6
	v_fmac_f32_e32 v123, v153, v7
	s_waitcnt lgkmcnt(12)
	v_fmac_f32_e32 v123, v154, v8
	v_fmac_f32_e32 v123, v155, v9
	s_waitcnt lgkmcnt(11)
	v_fmac_f32_e32 v123, v156, v10
	v_fmac_f32_e32 v123, v157, v11
	s_waitcnt lgkmcnt(10)
	v_fmac_f32_e32 v123, v158, v12
	v_fmac_f32_e32 v123, v159, v13
	s_waitcnt lgkmcnt(9)
	v_fmac_f32_e32 v123, v160, v14
	v_fmac_f32_e32 v123, v161, v15
	s_waitcnt lgkmcnt(8)
	v_fmac_f32_e32 v123, v162, v16
	v_add_u32_e32 v119, 0x8af0, v117
	ds_read2_b32 v[132:133], v119 offset0:0 offset1:4
	ds_read2_b32 v[134:135], v119 offset0:8 offset1:12
	ds_read2_b32 v[136:137], v119 offset0:16 offset1:20
	ds_read2_b32 v[138:139], v119 offset0:24 offset1:28
	ds_read2_b32 v[140:141], v119 offset0:32 offset1:36
	ds_read2_b32 v[142:143], v119 offset0:40 offset1:44
	ds_read2_b32 v[144:145], v119 offset0:48 offset1:52
	ds_read2_b32 v[146:147], v119 offset0:56 offset1:60
	v_cndmask_b32_e64 v126, 0, v163, s[100:101]
	v_fma_f32 v125, v126, v17, v123
	s_waitcnt lgkmcnt(15)
	v_mul_f32_e32 v124, v216, v2
	v_fmac_f32_e32 v124, v217, v3
	v_add_f32_dpp v127, v125, v125 quad_perm:[1,0,3,2] row_mask:0xf bank_mask:0xf
	s_waitcnt lgkmcnt(14)
	v_fmac_f32_e32 v124, v218, v4
	v_fmac_f32_e32 v124, v219, v5
	v_add_f32_dpp v125, v127, v127 quad_perm:[2,3,0,1] row_mask:0xf bank_mask:0xf
	v_fma_f32 v127, v115, v34, -v125
	v_cndmask_b32_e64 v17, v17, v127, s[90:91]
	s_waitcnt lgkmcnt(13)
	v_fmac_f32_e32 v124, v220, v6
	v_fmac_f32_e32 v124, v221, v7
	s_waitcnt lgkmcnt(12)
	v_fmac_f32_e32 v124, v222, v8
	v_fmac_f32_e32 v124, v223, v9
	s_waitcnt lgkmcnt(11)
	v_fmac_f32_e32 v124, v224, v10
	v_fmac_f32_e32 v124, v225, v11
	s_waitcnt lgkmcnt(10)
	v_fmac_f32_e32 v124, v226, v12
	v_fmac_f32_e32 v124, v227, v13
	s_waitcnt lgkmcnt(9)
	v_fmac_f32_e32 v124, v228, v14
	v_fmac_f32_e32 v124, v229, v15
	s_waitcnt lgkmcnt(8)
	v_fmac_f32_e32 v124, v230, v16
	v_cndmask_b32_e64 v126, 0, v231, s[18:19]
	v_fma_f32 v125, v126, v17, v124
	s_waitcnt lgkmcnt(7)
	v_mul_f32_e32 v122, v132, v2
	v_fmac_f32_e32 v122, v133, v3
	v_add_f32_dpp v127, v125, v125 quad_perm:[1,0,3,2] row_mask:0xf bank_mask:0xf
	s_waitcnt lgkmcnt(6)
	v_fmac_f32_e32 v122, v134, v4
	v_fmac_f32_e32 v122, v135, v5
	v_add_f32_dpp v125, v127, v127 quad_perm:[2,3,0,1] row_mask:0xf bank_mask:0xf
	v_fma_f32 v127, v115, v34, -v125
	v_cndmask_b32_e64 v17, v17, v127, s[92:93]
	s_waitcnt lgkmcnt(5)
	v_fmac_f32_e32 v122, v136, v6
	v_fmac_f32_e32 v122, v137, v7
	s_waitcnt lgkmcnt(4)
	v_fmac_f32_e32 v122, v138, v8
	v_fmac_f32_e32 v122, v139, v9
	s_waitcnt lgkmcnt(3)
	v_fmac_f32_e32 v122, v140, v10
	v_fmac_f32_e32 v122, v141, v11
	s_waitcnt lgkmcnt(2)
	v_fmac_f32_e32 v122, v142, v12
	v_fmac_f32_e32 v122, v143, v13
	s_waitcnt lgkmcnt(1)
	v_fmac_f32_e32 v122, v144, v14
	v_fmac_f32_e32 v122, v145, v15
	s_waitcnt lgkmcnt(0)
	v_fmac_f32_e32 v122, v146, v16
	v_cndmask_b32_e64 v126, 0, v147, s[22:23]
	v_fma_f32 v125, v126, v17, v122
	s_nop 1
	v_add_f32_dpp v127, v125, v125 quad_perm:[1,0,3,2] row_mask:0xf bank_mask:0xf
	s_nop 1
	v_add_f32_dpp v125, v127, v127 quad_perm:[2,3,0,1] row_mask:0xf bank_mask:0xf
	v_fma_f32 v127, v115, v34, -v125
	v_cndmask_b32_e64 v17, v17, v127, s[98:99]
	v_mov_b32_e32 v29, v130

; __global__ void __launch_bounds__(512) fwd_megakernel(Params p) {
	.amdhsa_kernel _Z14fwd_megakernel6Params
		.amdhsa_group_segment_fixed_size 16
		.amdhsa_private_segment_fixed_size 0
		.amdhsa_kernarg_size 472
		.amdhsa_user_sgpr_count 2
		.amdhsa_user_sgpr_dispatch_ptr 0
		.amdhsa_user_sgpr_queue_ptr 0
		.amdhsa_user_sgpr_kernarg_segment_ptr 1
		.amdhsa_user_sgpr_dispatch_id 0
		.amdhsa_user_sgpr_kernarg_preload_length 0
		.amdhsa_user_sgpr_kernarg_preload_offset 0
		.amdhsa_user_sgpr_private_segment_size 0
		.amdhsa_uses_dynamic_stack 0
		.amdhsa_enable_private_segment 0
		.amdhsa_system_sgpr_workgroup_id_x 1
		.amdhsa_system_sgpr_workgroup_id_y 0
		.amdhsa_system_sgpr_workgroup_id_z 0
		.amdhsa_system_sgpr_workgroup_info 0
		.amdhsa_system_vgpr_workitem_id 2
		.amdhsa_next_free_vgpr 256
		.amdhsa_next_free_sgpr 102
		.amdhsa_accum_offset 256
		.amdhsa_reserve_vcc 1
		.amdhsa_float_round_mode_32 0
		.amdhsa_float_round_mode_16_64 0
		.amdhsa_float_denorm_mode_32 3
		.amdhsa_float_denorm_mode_16_64 3
		.amdhsa_dx10_clamp 1
		.amdhsa_ieee_mode 1
		.amdhsa_fp16_overflow 0
		.amdhsa_tg_split 0
		.amdhsa_exception_fp_ieee_invalid_op 0
		.amdhsa_exception_fp_denorm_src 0
		.amdhsa_exception_fp_ieee_div_zero 0
		.amdhsa_exception_fp_ieee_overflow 0
		.amdhsa_exception_fp_ieee_underflow 0
		.amdhsa_exception_fp_ieee_inexact 0
		.amdhsa_exception_int_div_zero 0
	.end_amdhsa_kernel

; __global__ void __launch_bounds__(512) fwd_megakernel(Params p) {
amdhsa.kernels:
  - .agpr_count:     0
    .args:
      - .offset:         0
        .size:           216
        .value_kind:     by_value
      - .offset:         216
        .size:           4
        .value_kind:     hidden_block_count_x
      - .offset:         220
        .size:           4
        .value_kind:     hidden_block_count_y
      - .offset:         224
        .size:           4
        .value_kind:     hidden_block_count_z
      - .offset:         228
        .size:           2
        .value_kind:     hidden_group_size_x
      - .offset:         230
        .size:           2
        .value_kind:     hidden_group_size_y
      - .offset:         232
        .size:           2
        .value_kind:     hidden_group_size_z
      - .offset:         234
        .size:           2
        .value_kind:     hidden_remainder_x
      - .offset:         236
        .size:           2
        .value_kind:     hidden_remainder_y
      - .offset:         238
        .size:           2
        .value_kind:     hidden_remainder_z
      - .offset:         256
        .size:           8
        .value_kind:     hidden_global_offset_x
      - .offset:         264
        .size:           8
        .value_kind:     hidden_global_offset_y
      - .offset:         272
        .size:           8
        .value_kind:     hidden_global_offset_z
      - .offset:         280
        .size:           2
        .value_kind:     hidden_grid_dims
      - .offset:         304
        .size:           8
        .value_kind:     hidden_multigrid_sync_arg
      - .offset:         336
        .size:           4
        .value_kind:     hidden_dynamic_lds_size
    .group_segment_fixed_size: 16
    .kernarg_segment_align: 8
    .kernarg_segment_size: 472
    .language:       OpenCL C
    .language_version:
      - 2
      - 0
    .max_flat_workgroup_size: 512
    .name:           _Z14fwd_megakernel6Params
    .private_segment_fixed_size: 0
    .sgpr_count:     108
    .sgpr_spill_count: 250
    .symbol:         _Z14fwd_megakernel6Params.kd
    .uniform_work_group_size: 1
    .uses_dynamic_stack: false
    .vgpr_count:     256
    .vgpr_spill_count: 0
    .wavefront_size: 64
